# v23 + GEMM K-loops: fragment ds_reads issued first in each load phase, ahead of the scalar tile bookkeeping and DMA address ops
# baseline (speedup 1.0000x reference)
; #define G_STAGE(bufoff, gbase, v0, v1) do { \
;     __builtin_amdgcn_global_load_lds((const unsigned*)((const char*)(gbase) + (v0)), (LAS unsigned*)(lds + (bufoff) + ldsw), 16, 0, 0); \
;     __builtin_amdgcn_global_load_lds((const unsigned*)((const char*)(gbase) + (v1)), (LAS unsigned*)(lds + (bufoff) + ldsw + 8192), 16, 0, 0); } while (0)
; #define G_LDA(dst, b, h) do { _Pragma("unroll") for (int m = 0; m < 4; ++m) _Pragma("unroll") for (int k = 0; k < 2; ++k) dst[m][k] = *(const LAS h8*)(lds + G_SA(b, h) + aoff + m * 2048 + k * 1024); } while (0)
; #define G_LDB(dst, b, h) do { _Pragma("unroll") for (int n = 0; n < 2; ++n) _Pragma("unroll") for (int k = 0; k < 2; ++k) dst[n][k] = *(const LAS h8*)(lds + G_SB(b, h) + boff + n * 2048 + k * 1024); } while (0)
; #define G_MMA(ai, bj, At, Bt) do { __builtin_amdgcn_s_setprio(1); _Pragma("unroll") for (int m = 0; m < 4; ++m) _Pragma("unroll") for (int n = 0; n < 2; ++n) _Pragma("unroll") for (int k = 0; k < 2; ++k) \
;     acc[ai][bj][m][n] = __builtin_amdgcn_mfma_f32_16x16x32_f16(Bt[n][k], At[m][k], acc[ai][bj][m][n], 0, 0, 0); __builtin_amdgcn_s_setprio(0); } while (0)
; #define G_WAIT_V(n) asm volatile("s_waitcnt vmcnt(" #n ")" ::: "memory")
; #define G_WAIT_L(n) asm volatile("s_waitcnt lgkmcnt(" #n ")" ::: "memory")
; #define G_BAR __builtin_amdgcn_s_barrier()
; #define G_SCHED __builtin_amdgcn_sched_barrier(0)
; template <bool PERM, class Sched, class Epi>
; DI void gemm256(LAS unsigned char* lds, const Sched& S, const Epi& E, int wv_) {
;     ...
;       const bool last = (t == nt - 2);
;       const char* a1 = cA + (size_t)(t + 1) * kstep;
;       const char* a2 = last ? nA : cA + (size_t)(t + 2) * kstep;
;       const char* b2 = last ? nB : cB + (size_t)(t + 2) * kstep;
;       const char* a3 = a2 + kstep;
;       const char* b3 = b2 + kstep;
;       G_LDB(B0, 0, 0); G_SCHED; G_LDA(At, 0, 0); G_STAGE(G_SA(1, 1), a1 + chA, cvA0, cvA1);
;       G_WAIT_L(8); G_BAR; G_WAIT_L(0); G_MMA(0, 0, At, B0); G_BAR; G_SCHED;
;       G_LDB(B1, 0, 1); G_STAGE(G_SB(0, 0), b2, cvB0, cvB1);
;       G_BAR; G_WAIT_L(0); G_MMA(0, 1, At, B1); G_BAR;
;       G_LDA(At, 0, 1); G_STAGE(G_SA(0, 0), a2, cvA0, cvA1);
;       G_BAR; G_WAIT_L(0); G_MMA(1, 0, At, B0); G_BAR; G_SCHED;
;       G_STAGE(G_SB(0, 1), b2 + chB, cvB0, cvB1);
;       G_WAIT_V(6); G_BAR; G_MMA(1, 1, At, B1); G_BAR;
.LBB0_1503:
	ds_read_b128 v[146:149], v218
	ds_read_b128 v[150:153], v218 offset:1024
	ds_read_b128 v[154:157], v218 offset:2048
	ds_read_b128 v[158:161], v218 offset:3072
	ds_read_b128 v[162:165], v142
	ds_read_b128 v[166:169], v142 offset:1024
	ds_read_b128 v[170:173], v142 offset:2048
	ds_read_b128 v[174:177], v142 offset:3072
	ds_read_b128 v[178:181], v142 offset:4096
	ds_read_b128 v[182:185], v142 offset:5120
	ds_read_b128 v[186:189], v142 offset:6144
	ds_read_b128 v[190:193], v142 offset:7168
	s_add_i32 s91, s12, 2
	s_add_u32 s13, s10, 0xfffc0080
	s_addc_u32 s14, s11, -1
	s_cmp_eq_u32 s75, s12
	s_cselect_b32 s12, s90, s46
	s_cselect_b32 s15, s16, s14
	s_cselect_b32 s14, s17, s13
	s_cselect_b32 s13, s85, s74
	s_mov_b32 m0, s59
	v_lshl_add_u64 v[194:195], s[10:11], 0, v[138:139]
	global_load_lds_dwordx4 v[194:195], off
	s_mov_b32 m0, s60
	v_lshl_add_u64 v[194:195], s[10:11], 0, v[140:141]
	global_load_lds_dwordx4 v[194:195], off
	s_waitcnt lgkmcnt(8)
	s_barrier
	s_waitcnt lgkmcnt(0)
	s_waitcnt lgkmcnt(0)
	v_mfma_f32_16x16x32_f16 v[122:125], v[146:149], v[162:165], v[122:125]
	v_mfma_f32_16x16x32_f16 v[126:129], v[154:157], v[162:165], v[126:129]
	v_mfma_f32_16x16x32_f16 v[114:117], v[146:149], v[170:173], v[114:117]
	v_mfma_f32_16x16x32_f16 v[118:121], v[154:157], v[170:173], v[118:121]
	v_mfma_f32_16x16x32_f16 v[106:109], v[146:149], v[178:181], v[106:109]
	v_mfma_f32_16x16x32_f16 v[110:113], v[154:157], v[178:181], v[110:113]
	v_mfma_f32_16x16x32_f16 v[98:101], v[146:149], v[186:189], v[98:101]
	v_mfma_f32_16x16x32_f16 v[102:105], v[154:157], v[186:189], v[102:105]
	v_mfma_f32_16x16x32_f16 v[122:125], v[150:153], v[166:169], v[122:125]
	v_mfma_f32_16x16x32_f16 v[126:129], v[158:161], v[166:169], v[126:129]
	v_mfma_f32_16x16x32_f16 v[114:117], v[150:153], v[174:177], v[114:117]
	v_mfma_f32_16x16x32_f16 v[118:121], v[158:161], v[174:177], v[118:121]
	v_mfma_f32_16x16x32_f16 v[106:109], v[150:153], v[182:185], v[106:109]
	v_mfma_f32_16x16x32_f16 v[110:113], v[158:161], v[182:185], v[110:113]
	v_mfma_f32_16x16x32_f16 v[98:101], v[150:153], v[190:193], v[98:101]
	v_mfma_f32_16x16x32_f16 v[102:105], v[158:161], v[190:193], v[102:105]
	s_barrier
	ds_read_b128 v[194:197], v219
	ds_read_b128 v[198:201], v219 offset:1024
	ds_read_b128 v[202:205], v219 offset:2048
	ds_read_b128 v[206:209], v219 offset:3072
	s_mov_b32 m0, s20
	v_lshl_add_u64 v[210:211], s[12:13], 0, v[132:133]
	global_load_lds_dwordx4 v[210:211], off
	s_mov_b32 m0, s21
	v_lshl_add_u64 v[212:213], s[12:13], 0, v[136:137]
	global_load_lds_dwordx4 v[212:213], off
	s_barrier
	s_waitcnt lgkmcnt(0)
	s_waitcnt lgkmcnt(0)
	v_mfma_f32_16x16x32_f16 v[58:61], v[194:197], v[162:165], v[58:61]
	v_mfma_f32_16x16x32_f16 v[62:65], v[202:205], v[162:165], v[62:65]
	v_mfma_f32_16x16x32_f16 v[50:53], v[194:197], v[170:173], v[50:53]
	v_mfma_f32_16x16x32_f16 v[54:57], v[202:205], v[170:173], v[54:57]
	v_mfma_f32_16x16x32_f16 v[42:45], v[194:197], v[178:181], v[42:45]
	v_mfma_f32_16x16x32_f16 v[46:49], v[202:205], v[178:181], v[46:49]
	v_mfma_f32_16x16x32_f16 v[34:37], v[194:197], v[186:189], v[34:37]
	v_mfma_f32_16x16x32_f16 v[38:41], v[202:205], v[186:189], v[38:41]
	v_mfma_f32_16x16x32_f16 v[58:61], v[198:201], v[166:169], v[58:61]
	v_mfma_f32_16x16x32_f16 v[62:65], v[206:209], v[166:169], v[62:65]
	v_mfma_f32_16x16x32_f16 v[50:53], v[198:201], v[174:177], v[50:53]
	v_mfma_f32_16x16x32_f16 v[54:57], v[206:209], v[174:177], v[54:57]
	v_mfma_f32_16x16x32_f16 v[42:45], v[198:201], v[182:185], v[42:45]
	v_mfma_f32_16x16x32_f16 v[46:49], v[206:209], v[182:185], v[46:49]
	v_mfma_f32_16x16x32_f16 v[34:37], v[198:201], v[190:193], v[34:37]
	v_mfma_f32_16x16x32_f16 v[38:41], v[206:209], v[190:193], v[38:41]
	s_mov_b32 m0, s19
	v_lshl_add_u64 v[214:215], s[14:15], 0, v[130:131]
	s_barrier
	ds_read_b128 v[162:165], v142 offset:16384
	ds_read_b128 v[166:169], v142 offset:17408
	ds_read_b128 v[170:173], v142 offset:18432
	ds_read_b128 v[174:177], v142 offset:19456
	ds_read_b128 v[178:181], v142 offset:20480
	ds_read_b128 v[182:185], v142 offset:21504
	ds_read_b128 v[186:189], v142 offset:22528
	ds_read_b128 v[190:193], v142 offset:23552
	global_load_lds_dwordx4 v[214:215], off
	s_mov_b32 m0, s22
	v_lshl_add_u64 v[216:217], s[14:15], 0, v[134:135]
	global_load_lds_dwordx4 v[216:217], off
	s_barrier
	s_waitcnt lgkmcnt(0)
	s_waitcnt lgkmcnt(0)
	v_mfma_f32_16x16x32_f16 v[90:93], v[146:149], v[162:165], v[90:93]
	v_mfma_f32_16x16x32_f16 v[94:97], v[154:157], v[162:165], v[94:97]
	v_mfma_f32_16x16x32_f16 v[82:85], v[146:149], v[170:173], v[82:85]
	v_mfma_f32_16x16x32_f16 v[86:89], v[154:157], v[170:173], v[86:89]
	v_mfma_f32_16x16x32_f16 v[74:77], v[146:149], v[178:181], v[74:77]
	v_mfma_f32_16x16x32_f16 v[78:81], v[154:157], v[178:181], v[78:81]
	v_mfma_f32_16x16x32_f16 v[66:69], v[146:149], v[186:189], v[66:69]
	v_mfma_f32_16x16x32_f16 v[70:73], v[154:157], v[186:189], v[70:73]
	v_mfma_f32_16x16x32_f16 v[90:93], v[150:153], v[166:169], v[90:93]
	v_mfma_f32_16x16x32_f16 v[94:97], v[158:161], v[166:169], v[94:97]
	v_mfma_f32_16x16x32_f16 v[82:85], v[150:153], v[174:177], v[82:85]
	v_mfma_f32_16x16x32_f16 v[86:89], v[158:161], v[174:177], v[86:89]
	v_mfma_f32_16x16x32_f16 v[74:77], v[150:153], v[182:185], v[74:77]
	v_mfma_f32_16x16x32_f16 v[78:81], v[158:161], v[182:185], v[78:81]
	v_mfma_f32_16x16x32_f16 v[66:69], v[150:153], v[190:193], v[66:69]
	v_mfma_f32_16x16x32_f16 v[70:73], v[158:161], v[190:193], v[70:73]
	s_barrier
	s_add_u32 vcc_lo, s12, 0x40000
	s_addc_u32 vcc_hi, s13, 0
	s_mov_b32 m0, s23
	v_lshl_add_u64 v[146:147], vcc, 0, v[132:133]
	global_load_lds_dwordx4 v[146:147], off
	s_mov_b32 m0, s24
	v_lshl_add_u64 v[146:147], vcc, 0, v[136:137]
	global_load_lds_dwordx4 v[146:147], off
	s_waitcnt vmcnt(6)
	s_barrier
; #define G_STAGE(bufoff, gbase, v0, v1) do { \
;     __builtin_amdgcn_global_load_lds((const unsigned*)((const char*)(gbase) + (v0)), (LAS unsigned*)(lds + (bufoff) + ldsw), 16, 0, 0); \
;     __builtin_amdgcn_global_load_lds((const unsigned*)((const char*)(gbase) + (v1)), (LAS unsigned*)(lds + (bufoff) + ldsw + 8192), 16, 0, 0); } while (0)
; #define G_LDA(dst, b, h) do { _Pragma("unroll") for (int m = 0; m < 4; ++m) _Pragma("unroll") for (int k = 0; k < 2; ++k) dst[m][k] = *(const LAS h8*)(lds + G_SA(b, h) + aoff + m * 2048 + k * 1024); } while (0)
; #define G_LDB(dst, b, h) do { _Pragma("unroll") for (int n = 0; n < 2; ++n) _Pragma("unroll") for (int k = 0; k < 2; ++k) dst[n][k] = *(const LAS h8*)(lds + G_SB(b, h) + boff + n * 2048 + k * 1024); } while (0)
; #define G_MMA(ai, bj, At, Bt) do { __builtin_amdgcn_s_setprio(1); _Pragma("unroll") for (int m = 0; m < 4; ++m) _Pragma("unroll") for (int n = 0; n < 2; ++n) _Pragma("unroll") for (int k = 0; k < 2; ++k) \
;     acc[ai][bj][m][n] = __builtin_amdgcn_mfma_f32_16x16x32_f16(Bt[n][k], At[m][k], acc[ai][bj][m][n], 0, 0, 0); __builtin_amdgcn_s_setprio(0); } while (0)
; #define G_WAIT_V(n) asm volatile("s_waitcnt vmcnt(" #n ")" ::: "memory")
; #define G_WAIT_L(n) asm volatile("s_waitcnt lgkmcnt(" #n ")" ::: "memory")
; #define G_BAR __builtin_amdgcn_s_barrier()
; #define G_SCHED __builtin_amdgcn_sched_barrier(0)
; template <bool PERM, class Sched, class Epi>
; DI void gemm256(LAS unsigned char* lds, const Sched& S, const Epi& E, int wv_) {
;     ...
;       G_WAIT_V(6); G_BAR; G_MMA(1, 1, At, B1); G_BAR;
;       G_LDB(B0, 1, 0); G_SCHED; G_LDA(At, 1, 0); G_STAGE(G_SA(0, 1), a2 + chA, cvA0, cvA1);
;       G_WAIT_L(8); G_BAR; G_WAIT_L(0); G_MMA(0, 0, At, B0); G_BAR; G_SCHED;
;       G_LDB(B1, 1, 1); G_STAGE(G_SB(1, 0), b3, cvB0, cvB1);
	v_mfma_f32_16x16x32_f16 v[26:29], v[194:197], v[162:165], v[26:29]
	v_mfma_f32_16x16x32_f16 v[30:33], v[202:205], v[162:165], v[30:33]
	v_mfma_f32_16x16x32_f16 v[18:21], v[194:197], v[170:173], v[18:21]
	v_mfma_f32_16x16x32_f16 v[22:25], v[202:205], v[170:173], v[22:25]
	v_mfma_f32_16x16x32_f16 v[10:13], v[194:197], v[178:181], v[10:13]
	v_mfma_f32_16x16x32_f16 v[14:17], v[202:205], v[178:181], v[14:17]
	v_mfma_f32_16x16x32_f16 v[6:9], v[194:197], v[186:189], v[6:9]
	v_mfma_f32_16x16x32_f16 v[2:5], v[202:205], v[186:189], v[2:5]
	v_mfma_f32_16x16x32_f16 v[26:29], v[198:201], v[166:169], v[26:29]
	v_mfma_f32_16x16x32_f16 v[30:33], v[206:209], v[166:169], v[30:33]
	v_mfma_f32_16x16x32_f16 v[18:21], v[198:201], v[174:177], v[18:21]
	v_mfma_f32_16x16x32_f16 v[22:25], v[206:209], v[174:177], v[22:25]
	v_mfma_f32_16x16x32_f16 v[10:13], v[198:201], v[182:185], v[10:13]
	v_mfma_f32_16x16x32_f16 v[14:17], v[206:209], v[182:185], v[14:17]
	v_mfma_f32_16x16x32_f16 v[6:9], v[198:201], v[190:193], v[6:9]
	v_mfma_f32_16x16x32_f16 v[2:5], v[206:209], v[190:193], v[2:5]
	s_barrier
	ds_read_b128 v[146:149], v220
	ds_read_b128 v[150:153], v220 offset:1024
	ds_read_b128 v[154:157], v220 offset:2048
	ds_read_b128 v[158:161], v220 offset:3072
	ds_read_b128 v[162:165], v142 offset:32768
	ds_read_b128 v[166:169], v142 offset:33792
	ds_read_b128 v[170:173], v142 offset:34816
	ds_read_b128 v[174:177], v142 offset:35840
	ds_read_b128 v[178:181], v142 offset:36864
	ds_read_b128 v[182:185], v142 offset:37888
	ds_read_b128 v[186:189], v142 offset:38912
	ds_read_b128 v[190:193], v142 offset:39936
	s_add_u32 s14, s14, 0x40000
	s_addc_u32 s15, s15, 0
	s_mov_b32 m0, s25
	v_lshl_add_u64 v[194:195], s[14:15], 0, v[130:131]
	global_load_lds_dwordx4 v[194:195], off
	s_mov_b32 m0, s26
	v_lshl_add_u64 v[194:195], s[14:15], 0, v[134:135]
	global_load_lds_dwordx4 v[194:195], off
	s_waitcnt lgkmcnt(8)
	s_barrier
	s_waitcnt lgkmcnt(0)
	s_waitcnt lgkmcnt(0)
	v_mfma_f32_16x16x32_f16 v[122:125], v[146:149], v[162:165], v[122:125]
	v_mfma_f32_16x16x32_f16 v[126:129], v[154:157], v[162:165], v[126:129]
	v_mfma_f32_16x16x32_f16 v[114:117], v[146:149], v[170:173], v[114:117]
	v_mfma_f32_16x16x32_f16 v[118:121], v[154:157], v[170:173], v[118:121]
	v_mfma_f32_16x16x32_f16 v[106:109], v[146:149], v[178:181], v[106:109]
	v_mfma_f32_16x16x32_f16 v[110:113], v[154:157], v[178:181], v[110:113]
	v_mfma_f32_16x16x32_f16 v[98:101], v[146:149], v[186:189], v[98:101]
	v_mfma_f32_16x16x32_f16 v[102:105], v[154:157], v[186:189], v[102:105]
	v_mfma_f32_16x16x32_f16 v[122:125], v[150:153], v[166:169], v[122:125]
	v_mfma_f32_16x16x32_f16 v[126:129], v[158:161], v[166:169], v[126:129]
	v_mfma_f32_16x16x32_f16 v[114:117], v[150:153], v[174:177], v[114:117]
	v_mfma_f32_16x16x32_f16 v[118:121], v[158:161], v[174:177], v[118:121]
	v_mfma_f32_16x16x32_f16 v[106:109], v[150:153], v[182:185], v[106:109]
	v_mfma_f32_16x16x32_f16 v[110:113], v[158:161], v[182:185], v[110:113]
	v_mfma_f32_16x16x32_f16 v[98:101], v[150:153], v[190:193], v[98:101]
	v_mfma_f32_16x16x32_f16 v[102:105], v[158:161], v[190:193], v[102:105]
	s_barrier
	ds_read_b128 v[194:197], v221
	ds_read_b128 v[198:201], v221 offset:1024
	ds_read_b128 v[202:205], v221 offset:2048
	ds_read_b128 v[206:209], v221 offset:3072
	s_mov_b32 m0, s29
	v_lshl_add_u64 v[210:211], v[210:211], 0, s[86:87]
	global_load_lds_dwordx4 v[210:211], off
	s_mov_b32 m0, s30
	v_lshl_add_u64 v[210:211], v[212:213], 0, s[86:87]
	global_load_lds_dwordx4 v[210:211], off
	s_barrier
; #define G_STAGE(bufoff, gbase, v0, v1) do { \
;     __builtin_amdgcn_global_load_lds((const unsigned*)((const char*)(gbase) + (v0)), (LAS unsigned*)(lds + (bufoff) + ldsw), 16, 0, 0); \
;     __builtin_amdgcn_global_load_lds((const unsigned*)((const char*)(gbase) + (v1)), (LAS unsigned*)(lds + (bufoff) + ldsw + 8192), 16, 0, 0); } while (0)
; #define G_LDA(dst, b, h) do { _Pragma("unroll") for (int m = 0; m < 4; ++m) _Pragma("unroll") for (int k = 0; k < 2; ++k) dst[m][k] = *(const LAS h8*)(lds + G_SA(b, h) + aoff + m * 2048 + k * 1024); } while (0)
; #define G_MMA(ai, bj, At, Bt) do { __builtin_amdgcn_s_setprio(1); _Pragma("unroll") for (int m = 0; m < 4; ++m) _Pragma("unroll") for (int n = 0; n < 2; ++n) _Pragma("unroll") for (int k = 0; k < 2; ++k) \
;     acc[ai][bj][m][n] = __builtin_amdgcn_mfma_f32_16x16x32_f16(Bt[n][k], At[m][k], acc[ai][bj][m][n], 0, 0, 0); __builtin_amdgcn_s_setprio(0); } while (0)
; #define G_WAIT_V(n) asm volatile("s_waitcnt vmcnt(" #n ")" ::: "memory")
; #define G_WAIT_L(n) asm volatile("s_waitcnt lgkmcnt(" #n ")" ::: "memory")
; #define G_BAR __builtin_amdgcn_s_barrier()
; #define G_SCHED __builtin_amdgcn_sched_barrier(0)
; template <bool PERM, class Sched, class Epi>
; DI void gemm256(LAS unsigned char* lds, const Sched& S, const Epi& E, int wv_) {
;     ...
;       G_BAR; G_WAIT_L(0); G_MMA(0, 1, At, B1); G_BAR;
;       G_LDA(At, 1, 1); G_STAGE(G_SA(1, 0), a3, cvA0, cvA1);
;       G_BAR; G_WAIT_L(0); G_MMA(1, 0, At, B0); G_BAR; G_SCHED;
;       G_STAGE(G_SB(1, 1), b3 + chB, cvB0, cvB1);
;       G_WAIT_V(6); G_BAR; G_MMA(1, 1, At, B1); G_BAR;
;     }
;     bool keep = false;
;     if constexpr (Sched::CHAIN) keep = E(acc, cur, wr, wc, fr, fq); else E(acc, cur, wr, wc, fr, fq);
;     if (!has_next) break;
	s_waitcnt lgkmcnt(0)
	s_waitcnt lgkmcnt(0)
	v_mfma_f32_16x16x32_f16 v[58:61], v[194:197], v[162:165], v[58:61]
	v_mfma_f32_16x16x32_f16 v[62:65], v[202:205], v[162:165], v[62:65]
	v_mfma_f32_16x16x32_f16 v[50:53], v[194:197], v[170:173], v[50:53]
	v_mfma_f32_16x16x32_f16 v[54:57], v[202:205], v[170:173], v[54:57]
	v_mfma_f32_16x16x32_f16 v[42:45], v[194:197], v[178:181], v[42:45]
	v_mfma_f32_16x16x32_f16 v[46:49], v[202:205], v[178:181], v[46:49]
	v_mfma_f32_16x16x32_f16 v[34:37], v[194:197], v[186:189], v[34:37]
	v_mfma_f32_16x16x32_f16 v[38:41], v[202:205], v[186:189], v[38:41]
	v_mfma_f32_16x16x32_f16 v[58:61], v[198:201], v[166:169], v[58:61]
	v_mfma_f32_16x16x32_f16 v[62:65], v[206:209], v[166:169], v[62:65]
	v_mfma_f32_16x16x32_f16 v[50:53], v[198:201], v[174:177], v[50:53]
	v_mfma_f32_16x16x32_f16 v[54:57], v[206:209], v[174:177], v[54:57]
	v_mfma_f32_16x16x32_f16 v[42:45], v[198:201], v[182:185], v[42:45]
	v_mfma_f32_16x16x32_f16 v[46:49], v[206:209], v[182:185], v[46:49]
	v_mfma_f32_16x16x32_f16 v[34:37], v[198:201], v[190:193], v[34:37]
	v_mfma_f32_16x16x32_f16 v[38:41], v[206:209], v[190:193], v[38:41]
	s_mov_b32 m0, s31
	v_lshl_add_u64 v[210:211], v[214:215], 0, s[86:87]
	s_barrier
	ds_read_b128 v[162:165], v142 offset:49152
	ds_read_b128 v[166:169], v142 offset:50176
	ds_read_b128 v[170:173], v142 offset:51200
	ds_read_b128 v[174:177], v142 offset:52224
	ds_read_b128 v[178:181], v142 offset:53248
	ds_read_b128 v[182:185], v142 offset:54272
	ds_read_b128 v[186:189], v142 offset:55296
	ds_read_b128 v[190:193], v142 offset:56320
	global_load_lds_dwordx4 v[210:211], off
	s_mov_b32 m0, s34
	v_lshl_add_u64 v[210:211], v[216:217], 0, s[86:87]
	global_load_lds_dwordx4 v[210:211], off
	s_barrier
	s_waitcnt lgkmcnt(0)
	s_waitcnt lgkmcnt(0)
	v_mfma_f32_16x16x32_f16 v[90:93], v[146:149], v[162:165], v[90:93]
	v_mfma_f32_16x16x32_f16 v[94:97], v[154:157], v[162:165], v[94:97]
	v_mfma_f32_16x16x32_f16 v[82:85], v[146:149], v[170:173], v[82:85]
	v_mfma_f32_16x16x32_f16 v[86:89], v[154:157], v[170:173], v[86:89]
	v_mfma_f32_16x16x32_f16 v[74:77], v[146:149], v[178:181], v[74:77]
	v_mfma_f32_16x16x32_f16 v[78:81], v[154:157], v[178:181], v[78:81]
	v_mfma_f32_16x16x32_f16 v[66:69], v[146:149], v[186:189], v[66:69]
	v_mfma_f32_16x16x32_f16 v[70:73], v[154:157], v[186:189], v[70:73]
	v_mfma_f32_16x16x32_f16 v[90:93], v[150:153], v[166:169], v[90:93]
	v_mfma_f32_16x16x32_f16 v[94:97], v[158:161], v[166:169], v[94:97]
	v_mfma_f32_16x16x32_f16 v[82:85], v[150:153], v[174:177], v[82:85]
	v_mfma_f32_16x16x32_f16 v[86:89], v[158:161], v[174:177], v[86:89]
	v_mfma_f32_16x16x32_f16 v[74:77], v[150:153], v[182:185], v[74:77]
	v_mfma_f32_16x16x32_f16 v[78:81], v[158:161], v[182:185], v[78:81]
	v_mfma_f32_16x16x32_f16 v[66:69], v[150:153], v[190:193], v[66:69]
	v_mfma_f32_16x16x32_f16 v[70:73], v[158:161], v[190:193], v[70:73]
	s_barrier
	s_add_u32 s12, s12, 0x40080
	s_addc_u32 s13, s13, 0
	s_mov_b32 m0, s35
	v_lshl_add_u64 v[146:147], s[12:13], 0, v[132:133]
	global_load_lds_dwordx4 v[146:147], off
	s_mov_b32 m0, s36
	v_lshl_add_u64 v[146:147], s[12:13], 0, v[136:137]
	global_load_lds_dwordx4 v[146:147], off
	s_waitcnt vmcnt(6)
	s_barrier
	v_mfma_f32_16x16x32_f16 v[26:29], v[194:197], v[162:165], v[26:29]
	v_mfma_f32_16x16x32_f16 v[30:33], v[202:205], v[162:165], v[30:33]
	v_mfma_f32_16x16x32_f16 v[18:21], v[194:197], v[170:173], v[18:21]
	v_mfma_f32_16x16x32_f16 v[22:25], v[202:205], v[170:173], v[22:25]
	v_mfma_f32_16x16x32_f16 v[10:13], v[194:197], v[178:181], v[10:13]
	v_mfma_f32_16x16x32_f16 v[14:17], v[202:205], v[178:181], v[14:17]
	v_mfma_f32_16x16x32_f16 v[6:9], v[194:197], v[186:189], v[6:9]
	v_mfma_f32_16x16x32_f16 v[2:5], v[202:205], v[186:189], v[2:5]
	v_mfma_f32_16x16x32_f16 v[26:29], v[198:201], v[166:169], v[26:29]
	v_mfma_f32_16x16x32_f16 v[30:33], v[206:209], v[166:169], v[30:33]
	v_mfma_f32_16x16x32_f16 v[18:21], v[198:201], v[174:177], v[18:21]
	v_mfma_f32_16x16x32_f16 v[22:25], v[206:209], v[174:177], v[22:25]
	v_mfma_f32_16x16x32_f16 v[10:13], v[198:201], v[182:185], v[10:13]
	v_mfma_f32_16x16x32_f16 v[14:17], v[206:209], v[182:185], v[14:17]
	v_mfma_f32_16x16x32_f16 v[6:9], v[198:201], v[190:193], v[6:9]
	v_mfma_f32_16x16x32_f16 v[2:5], v[206:209], v[190:193], v[2:5]
	s_add_u32 s10, s10, 0x100
	s_addc_u32 s11, s11, 0
	s_add_u32 s46, s46, 0x100
	s_addc_u32 s74, s74, 0
	s_cmp_ge_i32 s91, s7
	s_mov_b32 s12, s91
	s_barrier
	s_cbranch_scc0 .LBB0_1503
	v_readlane_b32 s91, v254, 47
	s_movk_i32 s85, 0x800
	s_xor_b64 s[8:9], s[8:9], -1
	s_cmp_lg_u32 s84, 0
	s_cbranch_scc0 .LBB0_1509

; #define G_STAGE(bufoff, gbase, v0, v1) do { \
;     __builtin_amdgcn_global_load_lds((const unsigned*)((const char*)(gbase) + (v0)), (LAS unsigned*)(lds + (bufoff) + ldsw), 16, 0, 0); \
;     __builtin_amdgcn_global_load_lds((const unsigned*)((const char*)(gbase) + (v1)), (LAS unsigned*)(lds + (bufoff) + ldsw + 8192), 16, 0, 0); } while (0)
; #define G_LDA(dst, b, h) do { _Pragma("unroll") for (int m = 0; m < 4; ++m) _Pragma("unroll") for (int k = 0; k < 2; ++k) dst[m][k] = *(const LAS h8*)(lds + G_SA(b, h) + aoff + m * 2048 + k * 1024); } while (0)
; #define G_LDB(dst, b, h) do { _Pragma("unroll") for (int n = 0; n < 2; ++n) _Pragma("unroll") for (int k = 0; k < 2; ++k) dst[n][k] = *(const LAS h8*)(lds + G_SB(b, h) + boff + n * 2048 + k * 1024); } while (0)
; #define G_MMA(ai, bj, At, Bt) do { __builtin_amdgcn_s_setprio(1); _Pragma("unroll") for (int m = 0; m < 4; ++m) _Pragma("unroll") for (int n = 0; n < 2; ++n) _Pragma("unroll") for (int k = 0; k < 2; ++k) \
;     acc[ai][bj][m][n] = __builtin_amdgcn_mfma_f32_16x16x32_f16(Bt[n][k], At[m][k], acc[ai][bj][m][n], 0, 0, 0); __builtin_amdgcn_s_setprio(0); } while (0)
; #define G_WAIT_V(n) asm volatile("s_waitcnt vmcnt(" #n ")" ::: "memory")
; #define G_WAIT_L(n) asm volatile("s_waitcnt lgkmcnt(" #n ")" ::: "memory")
; #define G_BAR __builtin_amdgcn_s_barrier()
; #define G_SCHED __builtin_amdgcn_sched_barrier(0)
; template <bool PERM, class Sched, class Epi>
; DI void gemm256(LAS unsigned char* lds, const Sched& S, const Epi& E, int wv_) {
;     ...
;       const bool last = (t == nt - 2);
;       const char* a1 = cA + (size_t)(t + 1) * kstep;
;       const char* a2 = last ? nA : cA + (size_t)(t + 2) * kstep;
;       const char* b2 = last ? nB : cB + (size_t)(t + 2) * kstep;
;       const char* a3 = a2 + kstep;
;       const char* b3 = b2 + kstep;
;       G_LDB(B0, 0, 0); G_SCHED; G_LDA(At, 0, 0); G_STAGE(G_SA(1, 1), a1 + chA, cvA0, cvA1);
;       G_WAIT_L(8); G_BAR; G_WAIT_L(0); G_MMA(0, 0, At, B0); G_BAR; G_SCHED;
;       G_LDB(B1, 0, 1); G_STAGE(G_SB(0, 0), b2, cvB0, cvB1);
;       G_BAR; G_WAIT_L(0); G_MMA(0, 1, At, B1); G_BAR;
;       G_LDA(At, 0, 1); G_STAGE(G_SA(0, 0), a2, cvA0, cvA1);
;       G_BAR; G_WAIT_L(0); G_MMA(1, 0, At, B0); G_BAR; G_SCHED;
;       G_STAGE(G_SB(0, 1), b2 + chB, cvB0, cvB1);
;       G_WAIT_V(6); G_BAR; G_MMA(1, 1, At, B1); G_BAR;
.LBB0_1718:
	ds_read_b128 v[144:147], v216
	ds_read_b128 v[148:151], v216 offset:1024
	ds_read_b128 v[152:155], v216 offset:2048
	ds_read_b128 v[156:159], v216 offset:3072
	ds_read_b128 v[160:163], v1
	ds_read_b128 v[164:167], v1 offset:1024
	ds_read_b128 v[168:171], v1 offset:2048
	ds_read_b128 v[172:175], v1 offset:3072
	ds_read_b128 v[176:179], v1 offset:4096
	ds_read_b128 v[180:183], v1 offset:5120
	ds_read_b128 v[184:187], v1 offset:6144
	ds_read_b128 v[188:191], v1 offset:7168
	s_add_i32 s74, s12, 2
	s_add_u32 s13, s10, 0xfffea080
	s_addc_u32 s14, s11, -1
	s_cmp_eq_u32 vcc_lo, s12
	s_cselect_b32 s12, s93, s75
	s_cselect_b32 s15, s84, s14
	s_cselect_b32 s14, s85, s13
	s_cselect_b32 s13, s90, s46
	s_add_i32 m0, s19, 0xc000
	v_lshl_add_u64 v[192:193], s[10:11], 0, v[138:139]
	global_load_lds_dwordx4 v[192:193], off
	s_add_i32 m0, s19, 0xe000
	v_lshl_add_u64 v[192:193], s[10:11], 0, v[140:141]
	global_load_lds_dwordx4 v[192:193], off
	s_waitcnt lgkmcnt(8)
	s_barrier
	s_waitcnt lgkmcnt(0)
	s_waitcnt lgkmcnt(0)
	v_mfma_f32_16x16x32_f16 v[122:125], v[144:147], v[160:163], v[122:125]
	v_mfma_f32_16x16x32_f16 v[126:129], v[152:155], v[160:163], v[126:129]
	v_mfma_f32_16x16x32_f16 v[114:117], v[144:147], v[168:171], v[114:117]
	v_mfma_f32_16x16x32_f16 v[118:121], v[152:155], v[168:171], v[118:121]
	v_mfma_f32_16x16x32_f16 v[106:109], v[144:147], v[176:179], v[106:109]
	v_mfma_f32_16x16x32_f16 v[110:113], v[152:155], v[176:179], v[110:113]
	v_mfma_f32_16x16x32_f16 v[98:101], v[144:147], v[184:187], v[98:101]
	v_mfma_f32_16x16x32_f16 v[102:105], v[152:155], v[184:187], v[102:105]
	v_mfma_f32_16x16x32_f16 v[122:125], v[148:151], v[164:167], v[122:125]
	v_mfma_f32_16x16x32_f16 v[126:129], v[156:159], v[164:167], v[126:129]
	v_mfma_f32_16x16x32_f16 v[114:117], v[148:151], v[172:175], v[114:117]
	v_mfma_f32_16x16x32_f16 v[118:121], v[156:159], v[172:175], v[118:121]
	v_mfma_f32_16x16x32_f16 v[106:109], v[148:151], v[180:183], v[106:109]
	v_mfma_f32_16x16x32_f16 v[110:113], v[156:159], v[180:183], v[110:113]
	v_mfma_f32_16x16x32_f16 v[98:101], v[148:151], v[188:191], v[98:101]
	v_mfma_f32_16x16x32_f16 v[102:105], v[156:159], v[188:191], v[102:105]
	s_barrier
	ds_read_b128 v[192:195], v217
	ds_read_b128 v[196:199], v217 offset:1024
	ds_read_b128 v[200:203], v217 offset:2048
	ds_read_b128 v[204:207], v217 offset:3072
	s_mov_b32 m0, s20
	v_lshl_add_u64 v[208:209], s[12:13], 0, v[132:133]
	global_load_lds_dwordx4 v[208:209], off
	s_mov_b32 m0, s21
	v_lshl_add_u64 v[210:211], s[12:13], 0, v[136:137]
	global_load_lds_dwordx4 v[210:211], off
	s_barrier
	s_waitcnt lgkmcnt(0)
	s_waitcnt lgkmcnt(0)
	v_mfma_f32_16x16x32_f16 v[58:61], v[192:195], v[160:163], v[58:61]
	v_mfma_f32_16x16x32_f16 v[62:65], v[200:203], v[160:163], v[62:65]
	v_mfma_f32_16x16x32_f16 v[50:53], v[192:195], v[168:171], v[50:53]
	v_mfma_f32_16x16x32_f16 v[54:57], v[200:203], v[168:171], v[54:57]
	v_mfma_f32_16x16x32_f16 v[42:45], v[192:195], v[176:179], v[42:45]
	v_mfma_f32_16x16x32_f16 v[46:49], v[200:203], v[176:179], v[46:49]
	v_mfma_f32_16x16x32_f16 v[34:37], v[192:195], v[184:187], v[34:37]
	v_mfma_f32_16x16x32_f16 v[38:41], v[200:203], v[184:187], v[38:41]
	v_mfma_f32_16x16x32_f16 v[58:61], v[196:199], v[164:167], v[58:61]
	v_mfma_f32_16x16x32_f16 v[62:65], v[204:207], v[164:167], v[62:65]
	v_mfma_f32_16x16x32_f16 v[50:53], v[196:199], v[172:175], v[50:53]
	v_mfma_f32_16x16x32_f16 v[54:57], v[204:207], v[172:175], v[54:57]
	v_mfma_f32_16x16x32_f16 v[42:45], v[196:199], v[180:183], v[42:45]
	v_mfma_f32_16x16x32_f16 v[46:49], v[204:207], v[180:183], v[46:49]
	v_mfma_f32_16x16x32_f16 v[34:37], v[196:199], v[188:191], v[34:37]
	v_mfma_f32_16x16x32_f16 v[38:41], v[204:207], v[188:191], v[38:41]
	s_mov_b32 m0, s19
	v_lshl_add_u64 v[212:213], s[14:15], 0, v[130:131]
	s_barrier
	ds_read_b128 v[160:163], v1 offset:16384
	ds_read_b128 v[164:167], v1 offset:17408
	ds_read_b128 v[168:171], v1 offset:18432
	ds_read_b128 v[172:175], v1 offset:19456
	ds_read_b128 v[176:179], v1 offset:20480
	ds_read_b128 v[180:183], v1 offset:21504
	ds_read_b128 v[184:187], v1 offset:22528
	ds_read_b128 v[188:191], v1 offset:23552
	global_load_lds_dwordx4 v[212:213], off
	s_mov_b32 m0, s22
	v_lshl_add_u64 v[214:215], s[14:15], 0, v[134:135]
	global_load_lds_dwordx4 v[214:215], off
	s_barrier
	s_waitcnt lgkmcnt(0)
	s_waitcnt lgkmcnt(0)
	v_mfma_f32_16x16x32_f16 v[90:93], v[144:147], v[160:163], v[90:93]
	v_mfma_f32_16x16x32_f16 v[94:97], v[152:155], v[160:163], v[94:97]
	v_mfma_f32_16x16x32_f16 v[82:85], v[144:147], v[168:171], v[82:85]
	v_mfma_f32_16x16x32_f16 v[86:89], v[152:155], v[168:171], v[86:89]
	v_mfma_f32_16x16x32_f16 v[74:77], v[144:147], v[176:179], v[74:77]
	v_mfma_f32_16x16x32_f16 v[78:81], v[152:155], v[176:179], v[78:81]
	v_mfma_f32_16x16x32_f16 v[66:69], v[144:147], v[184:187], v[66:69]
	v_mfma_f32_16x16x32_f16 v[70:73], v[152:155], v[184:187], v[70:73]
	v_mfma_f32_16x16x32_f16 v[90:93], v[148:151], v[164:167], v[90:93]
	v_mfma_f32_16x16x32_f16 v[94:97], v[156:159], v[164:167], v[94:97]
	v_mfma_f32_16x16x32_f16 v[82:85], v[148:151], v[172:175], v[82:85]
	v_mfma_f32_16x16x32_f16 v[86:89], v[156:159], v[172:175], v[86:89]
	v_mfma_f32_16x16x32_f16 v[74:77], v[148:151], v[180:183], v[74:77]
	v_mfma_f32_16x16x32_f16 v[78:81], v[156:159], v[180:183], v[78:81]
	v_mfma_f32_16x16x32_f16 v[66:69], v[148:151], v[188:191], v[66:69]
	v_mfma_f32_16x16x32_f16 v[70:73], v[156:159], v[188:191], v[70:73]
	s_barrier
	s_add_u32 s68, s12, 0x10000
	s_addc_u32 s69, s13, 0
	s_mov_b32 m0, s23
	v_lshl_add_u64 v[144:145], s[68:69], 0, v[132:133]
	global_load_lds_dwordx4 v[144:145], off
	s_mov_b32 m0, s24
	v_lshl_add_u64 v[144:145], s[68:69], 0, v[136:137]
	global_load_lds_dwordx4 v[144:145], off
	s_waitcnt vmcnt(6)
	s_barrier
; #define G_STAGE(bufoff, gbase, v0, v1) do { \
;     __builtin_amdgcn_global_load_lds((const unsigned*)((const char*)(gbase) + (v0)), (LAS unsigned*)(lds + (bufoff) + ldsw), 16, 0, 0); \
;     __builtin_amdgcn_global_load_lds((const unsigned*)((const char*)(gbase) + (v1)), (LAS unsigned*)(lds + (bufoff) + ldsw + 8192), 16, 0, 0); } while (0)
; #define G_LDA(dst, b, h) do { _Pragma("unroll") for (int m = 0; m < 4; ++m) _Pragma("unroll") for (int k = 0; k < 2; ++k) dst[m][k] = *(const LAS h8*)(lds + G_SA(b, h) + aoff + m * 2048 + k * 1024); } while (0)
; #define G_LDB(dst, b, h) do { _Pragma("unroll") for (int n = 0; n < 2; ++n) _Pragma("unroll") for (int k = 0; k < 2; ++k) dst[n][k] = *(const LAS h8*)(lds + G_SB(b, h) + boff + n * 2048 + k * 1024); } while (0)
; #define G_MMA(ai, bj, At, Bt) do { __builtin_amdgcn_s_setprio(1); _Pragma("unroll") for (int m = 0; m < 4; ++m) _Pragma("unroll") for (int n = 0; n < 2; ++n) _Pragma("unroll") for (int k = 0; k < 2; ++k) \
;     acc[ai][bj][m][n] = __builtin_amdgcn_mfma_f32_16x16x32_f16(Bt[n][k], At[m][k], acc[ai][bj][m][n], 0, 0, 0); __builtin_amdgcn_s_setprio(0); } while (0)
; #define G_WAIT_V(n) asm volatile("s_waitcnt vmcnt(" #n ")" ::: "memory")
; #define G_WAIT_L(n) asm volatile("s_waitcnt lgkmcnt(" #n ")" ::: "memory")
; #define G_BAR __builtin_amdgcn_s_barrier()
; #define G_SCHED __builtin_amdgcn_sched_barrier(0)
; template <bool PERM, class Sched, class Epi>
; DI void gemm256(LAS unsigned char* lds, const Sched& S, const Epi& E, int wv_) {
;     ...
;       G_WAIT_V(6); G_BAR; G_MMA(1, 1, At, B1); G_BAR;
;       G_LDB(B0, 1, 0); G_SCHED; G_LDA(At, 1, 0); G_STAGE(G_SA(0, 1), a2 + chA, cvA0, cvA1);
;       G_WAIT_L(8); G_BAR; G_WAIT_L(0); G_MMA(0, 0, At, B0); G_BAR; G_SCHED;
;       G_LDB(B1, 1, 1); G_STAGE(G_SB(1, 0), b3, cvB0, cvB1);
	v_mfma_f32_16x16x32_f16 v[26:29], v[192:195], v[160:163], v[26:29]
	v_mfma_f32_16x16x32_f16 v[30:33], v[200:203], v[160:163], v[30:33]
	v_mfma_f32_16x16x32_f16 v[18:21], v[192:195], v[168:171], v[18:21]
	v_mfma_f32_16x16x32_f16 v[22:25], v[200:203], v[168:171], v[22:25]
	v_mfma_f32_16x16x32_f16 v[10:13], v[192:195], v[176:179], v[10:13]
	v_mfma_f32_16x16x32_f16 v[14:17], v[200:203], v[176:179], v[14:17]
	v_mfma_f32_16x16x32_f16 v[6:9], v[192:195], v[184:187], v[6:9]
	v_mfma_f32_16x16x32_f16 v[2:5], v[200:203], v[184:187], v[2:5]
	v_mfma_f32_16x16x32_f16 v[26:29], v[196:199], v[164:167], v[26:29]
	v_mfma_f32_16x16x32_f16 v[30:33], v[204:207], v[164:167], v[30:33]
	v_mfma_f32_16x16x32_f16 v[18:21], v[196:199], v[172:175], v[18:21]
	v_mfma_f32_16x16x32_f16 v[22:25], v[204:207], v[172:175], v[22:25]
	v_mfma_f32_16x16x32_f16 v[10:13], v[196:199], v[180:183], v[10:13]
	v_mfma_f32_16x16x32_f16 v[14:17], v[204:207], v[180:183], v[14:17]
	v_mfma_f32_16x16x32_f16 v[6:9], v[196:199], v[188:191], v[6:9]
	v_mfma_f32_16x16x32_f16 v[2:5], v[204:207], v[188:191], v[2:5]
	s_barrier
	ds_read_b128 v[144:147], v218
	ds_read_b128 v[148:151], v218 offset:1024
	ds_read_b128 v[152:155], v218 offset:2048
	ds_read_b128 v[156:159], v218 offset:3072
	ds_read_b128 v[160:163], v1 offset:32768
	ds_read_b128 v[164:167], v1 offset:33792
	ds_read_b128 v[168:171], v1 offset:34816
	ds_read_b128 v[172:175], v1 offset:35840
	ds_read_b128 v[176:179], v1 offset:36864
	ds_read_b128 v[180:183], v1 offset:37888
	ds_read_b128 v[184:187], v1 offset:38912
	ds_read_b128 v[188:191], v1 offset:39936
	s_add_u32 s14, s14, 0x16000
	s_addc_u32 s15, s15, 0
	s_mov_b32 m0, s25
	v_lshl_add_u64 v[192:193], s[14:15], 0, v[130:131]
	global_load_lds_dwordx4 v[192:193], off
	s_mov_b32 m0, s26
	v_lshl_add_u64 v[192:193], s[14:15], 0, v[134:135]
	global_load_lds_dwordx4 v[192:193], off
	s_waitcnt lgkmcnt(8)
	s_barrier
	s_waitcnt lgkmcnt(0)
	s_waitcnt lgkmcnt(0)
	v_mfma_f32_16x16x32_f16 v[122:125], v[144:147], v[160:163], v[122:125]
	v_mfma_f32_16x16x32_f16 v[126:129], v[152:155], v[160:163], v[126:129]
	v_mfma_f32_16x16x32_f16 v[114:117], v[144:147], v[168:171], v[114:117]
	v_mfma_f32_16x16x32_f16 v[118:121], v[152:155], v[168:171], v[118:121]
	v_mfma_f32_16x16x32_f16 v[106:109], v[144:147], v[176:179], v[106:109]
	v_mfma_f32_16x16x32_f16 v[110:113], v[152:155], v[176:179], v[110:113]
	v_mfma_f32_16x16x32_f16 v[98:101], v[144:147], v[184:187], v[98:101]
	v_mfma_f32_16x16x32_f16 v[102:105], v[152:155], v[184:187], v[102:105]
	v_mfma_f32_16x16x32_f16 v[122:125], v[148:151], v[164:167], v[122:125]
	v_mfma_f32_16x16x32_f16 v[126:129], v[156:159], v[164:167], v[126:129]
	v_mfma_f32_16x16x32_f16 v[114:117], v[148:151], v[172:175], v[114:117]
	v_mfma_f32_16x16x32_f16 v[118:121], v[156:159], v[172:175], v[118:121]
	v_mfma_f32_16x16x32_f16 v[106:109], v[148:151], v[180:183], v[106:109]
	v_mfma_f32_16x16x32_f16 v[110:113], v[156:159], v[180:183], v[110:113]
	v_mfma_f32_16x16x32_f16 v[98:101], v[148:151], v[188:191], v[98:101]
	v_mfma_f32_16x16x32_f16 v[102:105], v[156:159], v[188:191], v[102:105]
	s_barrier
	ds_read_b128 v[192:195], v219
	ds_read_b128 v[196:199], v219 offset:1024
	ds_read_b128 v[200:203], v219 offset:2048
	ds_read_b128 v[204:207], v219 offset:3072
	s_mov_b32 m0, s29
	v_lshl_add_u64 v[208:209], v[208:209], 0, s[86:87]
	global_load_lds_dwordx4 v[208:209], off
	s_mov_b32 m0, s30
	v_lshl_add_u64 v[208:209], v[210:211], 0, s[86:87]
	global_load_lds_dwordx4 v[208:209], off
	s_barrier
; #define G_STAGE(bufoff, gbase, v0, v1) do { \
;     __builtin_amdgcn_global_load_lds((const unsigned*)((const char*)(gbase) + (v0)), (LAS unsigned*)(lds + (bufoff) + ldsw), 16, 0, 0); \
;     __builtin_amdgcn_global_load_lds((const unsigned*)((const char*)(gbase) + (v1)), (LAS unsigned*)(lds + (bufoff) + ldsw + 8192), 16, 0, 0); } while (0)
; #define G_LDA(dst, b, h) do { _Pragma("unroll") for (int m = 0; m < 4; ++m) _Pragma("unroll") for (int k = 0; k < 2; ++k) dst[m][k] = *(const LAS h8*)(lds + G_SA(b, h) + aoff + m * 2048 + k * 1024); } while (0)
; #define G_MMA(ai, bj, At, Bt) do { __builtin_amdgcn_s_setprio(1); _Pragma("unroll") for (int m = 0; m < 4; ++m) _Pragma("unroll") for (int n = 0; n < 2; ++n) _Pragma("unroll") for (int k = 0; k < 2; ++k) \
;     acc[ai][bj][m][n] = __builtin_amdgcn_mfma_f32_16x16x32_f16(Bt[n][k], At[m][k], acc[ai][bj][m][n], 0, 0, 0); __builtin_amdgcn_s_setprio(0); } while (0)
; #define G_WAIT_V(n) asm volatile("s_waitcnt vmcnt(" #n ")" ::: "memory")
; #define G_WAIT_L(n) asm volatile("s_waitcnt lgkmcnt(" #n ")" ::: "memory")
; #define G_BAR __builtin_amdgcn_s_barrier()
; #define G_SCHED __builtin_amdgcn_sched_barrier(0)
; template <bool PERM, class Sched, class Epi>
; DI void gemm256(LAS unsigned char* lds, const Sched& S, const Epi& E, int wv_) {
;     ...
;       G_BAR; G_WAIT_L(0); G_MMA(0, 1, At, B1); G_BAR;
;       G_LDA(At, 1, 1); G_STAGE(G_SA(1, 0), a3, cvA0, cvA1);
;       G_BAR; G_WAIT_L(0); G_MMA(1, 0, At, B0); G_BAR; G_SCHED;
;       G_STAGE(G_SB(1, 1), b3 + chB, cvB0, cvB1);
;       G_WAIT_V(6); G_BAR; G_MMA(1, 1, At, B1); G_BAR;
;     }
;     bool keep = false;
;     if constexpr (Sched::CHAIN) keep = E(acc, cur, wr, wc, fr, fq); else E(acc, cur, wr, wc, fr, fq);
;     if (!has_next) break;
	s_waitcnt lgkmcnt(0)
	s_waitcnt lgkmcnt(0)
	v_mfma_f32_16x16x32_f16 v[58:61], v[192:195], v[160:163], v[58:61]
	v_mfma_f32_16x16x32_f16 v[62:65], v[200:203], v[160:163], v[62:65]
	v_mfma_f32_16x16x32_f16 v[50:53], v[192:195], v[168:171], v[50:53]
	v_mfma_f32_16x16x32_f16 v[54:57], v[200:203], v[168:171], v[54:57]
	v_mfma_f32_16x16x32_f16 v[42:45], v[192:195], v[176:179], v[42:45]
	v_mfma_f32_16x16x32_f16 v[46:49], v[200:203], v[176:179], v[46:49]
	v_mfma_f32_16x16x32_f16 v[34:37], v[192:195], v[184:187], v[34:37]
	v_mfma_f32_16x16x32_f16 v[38:41], v[200:203], v[184:187], v[38:41]
	v_mfma_f32_16x16x32_f16 v[58:61], v[196:199], v[164:167], v[58:61]
	v_mfma_f32_16x16x32_f16 v[62:65], v[204:207], v[164:167], v[62:65]
	v_mfma_f32_16x16x32_f16 v[50:53], v[196:199], v[172:175], v[50:53]
	v_mfma_f32_16x16x32_f16 v[54:57], v[204:207], v[172:175], v[54:57]
	v_mfma_f32_16x16x32_f16 v[42:45], v[196:199], v[180:183], v[42:45]
	v_mfma_f32_16x16x32_f16 v[46:49], v[204:207], v[180:183], v[46:49]
	v_mfma_f32_16x16x32_f16 v[34:37], v[196:199], v[188:191], v[34:37]
	v_mfma_f32_16x16x32_f16 v[38:41], v[204:207], v[188:191], v[38:41]
	s_mov_b32 m0, s31
	v_lshl_add_u64 v[208:209], v[212:213], 0, s[86:87]
	s_barrier
	ds_read_b128 v[160:163], v1 offset:49152
	ds_read_b128 v[164:167], v1 offset:50176
	ds_read_b128 v[168:171], v1 offset:51200
	ds_read_b128 v[172:175], v1 offset:52224
	ds_read_b128 v[176:179], v1 offset:53248
	ds_read_b128 v[180:183], v1 offset:54272
	ds_read_b128 v[184:187], v1 offset:55296
	ds_read_b128 v[188:191], v1 offset:56320
	global_load_lds_dwordx4 v[208:209], off
	s_mov_b32 m0, s34
	v_lshl_add_u64 v[208:209], v[214:215], 0, s[86:87]
	global_load_lds_dwordx4 v[208:209], off
	s_barrier
	s_waitcnt lgkmcnt(0)
	s_waitcnt lgkmcnt(0)
	v_mfma_f32_16x16x32_f16 v[90:93], v[144:147], v[160:163], v[90:93]
	v_mfma_f32_16x16x32_f16 v[94:97], v[152:155], v[160:163], v[94:97]
	v_mfma_f32_16x16x32_f16 v[82:85], v[144:147], v[168:171], v[82:85]
	v_mfma_f32_16x16x32_f16 v[86:89], v[152:155], v[168:171], v[86:89]
	v_mfma_f32_16x16x32_f16 v[74:77], v[144:147], v[176:179], v[74:77]
	v_mfma_f32_16x16x32_f16 v[78:81], v[152:155], v[176:179], v[78:81]
	v_mfma_f32_16x16x32_f16 v[66:69], v[144:147], v[184:187], v[66:69]
	v_mfma_f32_16x16x32_f16 v[70:73], v[152:155], v[184:187], v[70:73]
	v_mfma_f32_16x16x32_f16 v[90:93], v[148:151], v[164:167], v[90:93]
	v_mfma_f32_16x16x32_f16 v[94:97], v[156:159], v[164:167], v[94:97]
	v_mfma_f32_16x16x32_f16 v[82:85], v[148:151], v[172:175], v[82:85]
	v_mfma_f32_16x16x32_f16 v[86:89], v[156:159], v[172:175], v[86:89]
	v_mfma_f32_16x16x32_f16 v[74:77], v[148:151], v[180:183], v[74:77]
	v_mfma_f32_16x16x32_f16 v[78:81], v[156:159], v[180:183], v[78:81]
	v_mfma_f32_16x16x32_f16 v[66:69], v[148:151], v[188:191], v[66:69]
	v_mfma_f32_16x16x32_f16 v[70:73], v[156:159], v[188:191], v[70:73]
	s_barrier
	s_add_u32 s12, s12, 0x10080
	s_addc_u32 s13, s13, 0
	s_mov_b32 m0, s35
	v_lshl_add_u64 v[144:145], s[12:13], 0, v[132:133]
	global_load_lds_dwordx4 v[144:145], off
	s_mov_b32 m0, s37
	v_lshl_add_u64 v[144:145], s[12:13], 0, v[136:137]
	global_load_lds_dwordx4 v[144:145], off
	s_waitcnt vmcnt(6)
	s_barrier
	v_mfma_f32_16x16x32_f16 v[26:29], v[192:195], v[160:163], v[26:29]
	v_mfma_f32_16x16x32_f16 v[30:33], v[200:203], v[160:163], v[30:33]
	v_mfma_f32_16x16x32_f16 v[18:21], v[192:195], v[168:171], v[18:21]
	v_mfma_f32_16x16x32_f16 v[22:25], v[200:203], v[168:171], v[22:25]
	v_mfma_f32_16x16x32_f16 v[10:13], v[192:195], v[176:179], v[10:13]
	v_mfma_f32_16x16x32_f16 v[14:17], v[200:203], v[176:179], v[14:17]
	v_mfma_f32_16x16x32_f16 v[6:9], v[192:195], v[184:187], v[6:9]
	v_mfma_f32_16x16x32_f16 v[2:5], v[200:203], v[184:187], v[2:5]
	v_mfma_f32_16x16x32_f16 v[26:29], v[196:199], v[164:167], v[26:29]
	v_mfma_f32_16x16x32_f16 v[30:33], v[204:207], v[164:167], v[30:33]
	v_mfma_f32_16x16x32_f16 v[18:21], v[196:199], v[172:175], v[18:21]
	v_mfma_f32_16x16x32_f16 v[22:25], v[204:207], v[172:175], v[22:25]
	v_mfma_f32_16x16x32_f16 v[10:13], v[196:199], v[180:183], v[10:13]
	v_mfma_f32_16x16x32_f16 v[14:17], v[204:207], v[180:183], v[14:17]
	v_mfma_f32_16x16x32_f16 v[6:9], v[196:199], v[188:191], v[6:9]
	v_mfma_f32_16x16x32_f16 v[2:5], v[204:207], v[188:191], v[2:5]
	s_add_u32 s10, s10, 0x100
	s_addc_u32 s11, s11, 0
	s_add_u32 s75, s75, 0x100
	s_addc_u32 s46, s46, 0
	s_cmp_ge_i32 s74, s79
	s_mov_b32 s12, s74
	s_barrier
	s_cbranch_scc0 .LBB0_1718
	s_mov_b32 s93, 0x23fff
	s_movk_i32 s85, 0x800
	s_branch .LBB0_1721

; #define G_STAGE(bufoff, gbase, v0, v1) do { \
;     __builtin_amdgcn_global_load_lds((const unsigned*)((const char*)(gbase) + (v0)), (LAS unsigned*)(lds + (bufoff) + ldsw), 16, 0, 0); \
;     __builtin_amdgcn_global_load_lds((const unsigned*)((const char*)(gbase) + (v1)), (LAS unsigned*)(lds + (bufoff) + ldsw + 8192), 16, 0, 0); } while (0)
; #define G_LDA(dst, b, h) do { _Pragma("unroll") for (int m = 0; m < 4; ++m) _Pragma("unroll") for (int k = 0; k < 2; ++k) dst[m][k] = *(const LAS h8*)(lds + G_SA(b, h) + aoff + m * 2048 + k * 1024); } while (0)
; #define G_LDB(dst, b, h) do { _Pragma("unroll") for (int n = 0; n < 2; ++n) _Pragma("unroll") for (int k = 0; k < 2; ++k) dst[n][k] = *(const LAS h8*)(lds + G_SB(b, h) + boff + n * 2048 + k * 1024); } while (0)
; #define G_MMA(ai, bj, At, Bt) do { __builtin_amdgcn_s_setprio(1); _Pragma("unroll") for (int m = 0; m < 4; ++m) _Pragma("unroll") for (int n = 0; n < 2; ++n) _Pragma("unroll") for (int k = 0; k < 2; ++k) \
;     acc[ai][bj][m][n] = __builtin_amdgcn_mfma_f32_16x16x32_f16(Bt[n][k], At[m][k], acc[ai][bj][m][n], 0, 0, 0); __builtin_amdgcn_s_setprio(0); } while (0)
; #define G_WAIT_V(n) asm volatile("s_waitcnt vmcnt(" #n ")" ::: "memory")
; #define G_WAIT_L(n) asm volatile("s_waitcnt lgkmcnt(" #n ")" ::: "memory")
; #define G_BAR __builtin_amdgcn_s_barrier()
; #define G_SCHED __builtin_amdgcn_sched_barrier(0)
; template <bool PERM, class Sched, class Epi>
; DI void gemm256(LAS unsigned char* lds, const Sched& S, const Epi& E, int wv_) {
;     ...
;       const bool last = (t == nt - 2);
;       const char* a1 = cA + (size_t)(t + 1) * kstep;
;       const char* a2 = last ? nA : cA + (size_t)(t + 2) * kstep;
;       const char* b2 = last ? nB : cB + (size_t)(t + 2) * kstep;
;       const char* a3 = a2 + kstep;
;       const char* b3 = b2 + kstep;
;       G_LDB(B0, 0, 0); G_SCHED; G_LDA(At, 0, 0); G_STAGE(G_SA(1, 1), a1 + chA, cvA0, cvA1);
;       G_WAIT_L(8); G_BAR; G_WAIT_L(0); G_MMA(0, 0, At, B0); G_BAR; G_SCHED;
;       G_LDB(B1, 0, 1); G_STAGE(G_SB(0, 0), b2, cvB0, cvB1);
;       G_BAR; G_WAIT_L(0); G_MMA(0, 1, At, B1); G_BAR;
;       G_LDA(At, 0, 1); G_STAGE(G_SA(0, 0), a2, cvA0, cvA1);
;       G_BAR; G_WAIT_L(0); G_MMA(1, 0, At, B0); G_BAR; G_SCHED;
;       G_STAGE(G_SB(0, 1), b2 + chB, cvB0, cvB1);
;       G_WAIT_V(6); G_BAR; G_MMA(1, 1, At, B1); G_BAR;
.LBB0_1748:
	ds_read_b128 v[144:147], v216
	ds_read_b128 v[148:151], v216 offset:1024
	ds_read_b128 v[152:155], v216 offset:2048
	ds_read_b128 v[156:159], v216 offset:3072
	ds_read_b128 v[160:163], v1
	ds_read_b128 v[164:167], v1 offset:1024
	ds_read_b128 v[168:171], v1 offset:2048
	ds_read_b128 v[172:175], v1 offset:3072
	ds_read_b128 v[176:179], v1 offset:4096
	ds_read_b128 v[180:183], v1 offset:5120
	ds_read_b128 v[184:187], v1 offset:6144
	ds_read_b128 v[188:191], v1 offset:7168
	s_add_i32 s60, s12, 2
	s_add_u32 s10, s8, 0x100
	s_addc_u32 s11, s9, 0
	s_add_u32 s13, s58, s8
	s_addc_u32 s14, s59, s9
	s_cmp_eq_u32 s56, s12
	s_cselect_b32 s40, 0, s10
	s_cselect_b32 s15, 0, s11
	s_cselect_b32 s12, s4, s13
	s_cselect_b32 s13, s5, s14
	s_add_u32 s14, s2, s40
	s_addc_u32 s15, s3, s15
	s_add_i32 m0, s17, 0xc000
	v_lshl_add_u64 v[192:193], v[138:139], 0, s[8:9]
	global_load_lds_dwordx4 v[192:193], off
	s_add_i32 m0, s17, 0xe000
	v_lshl_add_u64 v[192:193], v[140:141], 0, s[8:9]
	global_load_lds_dwordx4 v[192:193], off
	s_waitcnt lgkmcnt(8)
	s_barrier
	s_waitcnt lgkmcnt(0)
	s_waitcnt lgkmcnt(0)
	v_mfma_f32_16x16x32_f16 v[122:125], v[144:147], v[160:163], v[122:125]
	v_mfma_f32_16x16x32_f16 v[126:129], v[152:155], v[160:163], v[126:129]
	v_mfma_f32_16x16x32_f16 v[106:109], v[144:147], v[168:171], v[106:109]
	v_mfma_f32_16x16x32_f16 v[110:113], v[152:155], v[168:171], v[110:113]
	v_mfma_f32_16x16x32_f16 v[90:93], v[144:147], v[176:179], v[90:93]
	v_mfma_f32_16x16x32_f16 v[94:97], v[152:155], v[176:179], v[94:97]
	v_mfma_f32_16x16x32_f16 v[74:77], v[144:147], v[184:187], v[74:77]
	v_mfma_f32_16x16x32_f16 v[78:81], v[152:155], v[184:187], v[78:81]
	v_mfma_f32_16x16x32_f16 v[122:125], v[148:151], v[164:167], v[122:125]
	v_mfma_f32_16x16x32_f16 v[126:129], v[156:159], v[164:167], v[126:129]
	v_mfma_f32_16x16x32_f16 v[106:109], v[148:151], v[172:175], v[106:109]
	v_mfma_f32_16x16x32_f16 v[110:113], v[156:159], v[172:175], v[110:113]
	v_mfma_f32_16x16x32_f16 v[90:93], v[148:151], v[180:183], v[90:93]
	v_mfma_f32_16x16x32_f16 v[94:97], v[156:159], v[180:183], v[94:97]
	v_mfma_f32_16x16x32_f16 v[74:77], v[148:151], v[188:191], v[74:77]
	v_mfma_f32_16x16x32_f16 v[78:81], v[156:159], v[188:191], v[78:81]
	s_barrier
	ds_read_b128 v[192:195], v217
	ds_read_b128 v[196:199], v217 offset:1024
	ds_read_b128 v[200:203], v217 offset:2048
	ds_read_b128 v[204:207], v217 offset:3072
	s_mov_b32 m0, s18
	v_lshl_add_u64 v[208:209], s[12:13], 0, v[134:135]
	global_load_lds_dwordx4 v[208:209], off
	s_mov_b32 m0, s19
	v_lshl_add_u64 v[210:211], s[12:13], 0, v[130:131]
	global_load_lds_dwordx4 v[210:211], off
	s_barrier
	s_waitcnt lgkmcnt(0)
	s_waitcnt lgkmcnt(0)
	v_mfma_f32_16x16x32_f16 v[114:117], v[192:195], v[160:163], v[114:117]
	v_mfma_f32_16x16x32_f16 v[118:121], v[200:203], v[160:163], v[118:121]
	v_mfma_f32_16x16x32_f16 v[98:101], v[192:195], v[168:171], v[98:101]
	v_mfma_f32_16x16x32_f16 v[102:105], v[200:203], v[168:171], v[102:105]
	v_mfma_f32_16x16x32_f16 v[82:85], v[192:195], v[176:179], v[82:85]
	v_mfma_f32_16x16x32_f16 v[86:89], v[200:203], v[176:179], v[86:89]
	v_mfma_f32_16x16x32_f16 v[66:69], v[192:195], v[184:187], v[66:69]
	v_mfma_f32_16x16x32_f16 v[70:73], v[200:203], v[184:187], v[70:73]
	v_mfma_f32_16x16x32_f16 v[114:117], v[196:199], v[164:167], v[114:117]
	v_mfma_f32_16x16x32_f16 v[118:121], v[204:207], v[164:167], v[118:121]
	v_mfma_f32_16x16x32_f16 v[98:101], v[196:199], v[172:175], v[98:101]
	v_mfma_f32_16x16x32_f16 v[102:105], v[204:207], v[172:175], v[102:105]
	v_mfma_f32_16x16x32_f16 v[82:85], v[196:199], v[180:183], v[82:85]
	v_mfma_f32_16x16x32_f16 v[86:89], v[204:207], v[180:183], v[86:89]
	v_mfma_f32_16x16x32_f16 v[66:69], v[196:199], v[188:191], v[66:69]
	v_mfma_f32_16x16x32_f16 v[70:73], v[204:207], v[188:191], v[70:73]
	s_mov_b32 m0, s17
	v_lshl_add_u64 v[212:213], s[14:15], 0, v[136:137]
	s_barrier
	ds_read_b128 v[160:163], v1 offset:16384
	ds_read_b128 v[164:167], v1 offset:17408
	ds_read_b128 v[168:171], v1 offset:18432
	ds_read_b128 v[172:175], v1 offset:19456
	ds_read_b128 v[176:179], v1 offset:20480
	ds_read_b128 v[180:183], v1 offset:21504
	ds_read_b128 v[184:187], v1 offset:22528
	ds_read_b128 v[188:191], v1 offset:23552
	global_load_lds_dwordx4 v[212:213], off
	s_mov_b32 m0, s20
	v_lshl_add_u64 v[214:215], s[14:15], 0, v[132:133]
	global_load_lds_dwordx4 v[214:215], off
	s_barrier
	s_waitcnt lgkmcnt(0)
	s_waitcnt lgkmcnt(0)
	v_mfma_f32_16x16x32_f16 v[58:61], v[144:147], v[160:163], v[58:61]
	v_mfma_f32_16x16x32_f16 v[62:65], v[152:155], v[160:163], v[62:65]
	v_mfma_f32_16x16x32_f16 v[42:45], v[144:147], v[168:171], v[42:45]
	v_mfma_f32_16x16x32_f16 v[46:49], v[152:155], v[168:171], v[46:49]
	v_mfma_f32_16x16x32_f16 v[26:29], v[144:147], v[176:179], v[26:29]
	v_mfma_f32_16x16x32_f16 v[30:33], v[152:155], v[176:179], v[30:33]
	v_mfma_f32_16x16x32_f16 v[10:13], v[144:147], v[184:187], v[10:13]
	v_mfma_f32_16x16x32_f16 v[14:17], v[152:155], v[184:187], v[14:17]
	v_mfma_f32_16x16x32_f16 v[58:61], v[148:151], v[164:167], v[58:61]
	v_mfma_f32_16x16x32_f16 v[62:65], v[156:159], v[164:167], v[62:65]
	v_mfma_f32_16x16x32_f16 v[42:45], v[148:151], v[172:175], v[42:45]
	v_mfma_f32_16x16x32_f16 v[46:49], v[156:159], v[172:175], v[46:49]
	v_mfma_f32_16x16x32_f16 v[26:29], v[148:151], v[180:183], v[26:29]
	v_mfma_f32_16x16x32_f16 v[30:33], v[156:159], v[180:183], v[30:33]
	v_mfma_f32_16x16x32_f16 v[10:13], v[148:151], v[188:191], v[10:13]
	v_mfma_f32_16x16x32_f16 v[14:17], v[156:159], v[188:191], v[14:17]
	s_barrier
; #define G_STAGE(bufoff, gbase, v0, v1) do { \
;     __builtin_amdgcn_global_load_lds((const unsigned*)((const char*)(gbase) + (v0)), (LAS unsigned*)(lds + (bufoff) + ldsw), 16, 0, 0); \
;     __builtin_amdgcn_global_load_lds((const unsigned*)((const char*)(gbase) + (v1)), (LAS unsigned*)(lds + (bufoff) + ldsw + 8192), 16, 0, 0); } while (0)
; #define G_LDA(dst, b, h) do { _Pragma("unroll") for (int m = 0; m < 4; ++m) _Pragma("unroll") for (int k = 0; k < 2; ++k) dst[m][k] = *(const LAS h8*)(lds + G_SA(b, h) + aoff + m * 2048 + k * 1024); } while (0)
; #define G_LDB(dst, b, h) do { _Pragma("unroll") for (int n = 0; n < 2; ++n) _Pragma("unroll") for (int k = 0; k < 2; ++k) dst[n][k] = *(const LAS h8*)(lds + G_SB(b, h) + boff + n * 2048 + k * 1024); } while (0)
; #define G_MMA(ai, bj, At, Bt) do { __builtin_amdgcn_s_setprio(1); _Pragma("unroll") for (int m = 0; m < 4; ++m) _Pragma("unroll") for (int n = 0; n < 2; ++n) _Pragma("unroll") for (int k = 0; k < 2; ++k) \
;     acc[ai][bj][m][n] = __builtin_amdgcn_mfma_f32_16x16x32_f16(Bt[n][k], At[m][k], acc[ai][bj][m][n], 0, 0, 0); __builtin_amdgcn_s_setprio(0); } while (0)
; #define G_WAIT_V(n) asm volatile("s_waitcnt vmcnt(" #n ")" ::: "memory")
; #define G_WAIT_L(n) asm volatile("s_waitcnt lgkmcnt(" #n ")" ::: "memory")
; #define G_BAR __builtin_amdgcn_s_barrier()
; #define G_SCHED __builtin_amdgcn_sched_barrier(0)
; template <bool PERM, class Sched, class Epi>
; DI void gemm256(LAS unsigned char* lds, const Sched& S, const Epi& E, int wv_) {
;     ...
;       G_WAIT_V(6); G_BAR; G_MMA(1, 1, At, B1); G_BAR;
;       G_LDB(B0, 1, 0); G_SCHED; G_LDA(At, 1, 0); G_STAGE(G_SA(0, 1), a2 + chA, cvA0, cvA1);
;       G_WAIT_L(8); G_BAR; G_WAIT_L(0); G_MMA(0, 0, At, B0); G_BAR; G_SCHED;
;       G_LDB(B1, 1, 1); G_STAGE(G_SB(1, 0), b3, cvB0, cvB1);
	s_add_u32 s8, s12, 0x16000
	s_addc_u32 s9, s13, 0
	s_mov_b32 m0, s21
	v_lshl_add_u64 v[144:145], s[8:9], 0, v[134:135]
	global_load_lds_dwordx4 v[144:145], off
	s_mov_b32 m0, s22
	v_lshl_add_u64 v[144:145], s[8:9], 0, v[130:131]
	global_load_lds_dwordx4 v[144:145], off
	s_waitcnt vmcnt(6)
	s_barrier
	v_mfma_f32_16x16x32_f16 v[50:53], v[192:195], v[160:163], v[50:53]
	v_mfma_f32_16x16x32_f16 v[54:57], v[200:203], v[160:163], v[54:57]
	v_mfma_f32_16x16x32_f16 v[34:37], v[192:195], v[168:171], v[34:37]
	v_mfma_f32_16x16x32_f16 v[38:41], v[200:203], v[168:171], v[38:41]
	v_mfma_f32_16x16x32_f16 v[18:21], v[192:195], v[176:179], v[18:21]
	v_mfma_f32_16x16x32_f16 v[22:25], v[200:203], v[176:179], v[22:25]
	v_mfma_f32_16x16x32_f16 v[6:9], v[192:195], v[184:187], v[6:9]
	v_mfma_f32_16x16x32_f16 v[2:5], v[200:203], v[184:187], v[2:5]
	v_mfma_f32_16x16x32_f16 v[50:53], v[196:199], v[164:167], v[50:53]
	v_mfma_f32_16x16x32_f16 v[54:57], v[204:207], v[164:167], v[54:57]
	v_mfma_f32_16x16x32_f16 v[34:37], v[196:199], v[172:175], v[34:37]
	v_mfma_f32_16x16x32_f16 v[38:41], v[204:207], v[172:175], v[38:41]
	v_mfma_f32_16x16x32_f16 v[18:21], v[196:199], v[180:183], v[18:21]
	v_mfma_f32_16x16x32_f16 v[22:25], v[204:207], v[180:183], v[22:25]
	v_mfma_f32_16x16x32_f16 v[6:9], v[196:199], v[188:191], v[6:9]
	v_mfma_f32_16x16x32_f16 v[2:5], v[204:207], v[188:191], v[2:5]
	s_barrier
	ds_read_b128 v[144:147], v218
	ds_read_b128 v[148:151], v218 offset:1024
	ds_read_b128 v[152:155], v218 offset:2048
	ds_read_b128 v[156:159], v218 offset:3072
	ds_read_b128 v[160:163], v1 offset:32768
	ds_read_b128 v[164:167], v1 offset:33792
	ds_read_b128 v[168:171], v1 offset:34816
	ds_read_b128 v[172:175], v1 offset:35840
	ds_read_b128 v[176:179], v1 offset:36864
	ds_read_b128 v[180:183], v1 offset:37888
	ds_read_b128 v[184:187], v1 offset:38912
	ds_read_b128 v[188:191], v1 offset:39936
	s_add_u32 s8, s14, 0x10000
	s_addc_u32 s9, s15, 0
	s_mov_b32 m0, s23
	v_lshl_add_u64 v[192:193], s[8:9], 0, v[136:137]
	global_load_lds_dwordx4 v[192:193], off
	s_mov_b32 m0, s24
	v_lshl_add_u64 v[192:193], s[8:9], 0, v[132:133]
	global_load_lds_dwordx4 v[192:193], off
	s_waitcnt lgkmcnt(8)
	s_barrier
	s_waitcnt lgkmcnt(0)
	s_waitcnt lgkmcnt(0)
	v_mfma_f32_16x16x32_f16 v[122:125], v[144:147], v[160:163], v[122:125]
	v_mfma_f32_16x16x32_f16 v[126:129], v[152:155], v[160:163], v[126:129]
	v_mfma_f32_16x16x32_f16 v[106:109], v[144:147], v[168:171], v[106:109]
	v_mfma_f32_16x16x32_f16 v[110:113], v[152:155], v[168:171], v[110:113]
	v_mfma_f32_16x16x32_f16 v[90:93], v[144:147], v[176:179], v[90:93]
	v_mfma_f32_16x16x32_f16 v[94:97], v[152:155], v[176:179], v[94:97]
	v_mfma_f32_16x16x32_f16 v[74:77], v[144:147], v[184:187], v[74:77]
	v_mfma_f32_16x16x32_f16 v[78:81], v[152:155], v[184:187], v[78:81]
	v_mfma_f32_16x16x32_f16 v[122:125], v[148:151], v[164:167], v[122:125]
	v_mfma_f32_16x16x32_f16 v[126:129], v[156:159], v[164:167], v[126:129]
	v_mfma_f32_16x16x32_f16 v[106:109], v[148:151], v[172:175], v[106:109]
	v_mfma_f32_16x16x32_f16 v[110:113], v[156:159], v[172:175], v[110:113]
	v_mfma_f32_16x16x32_f16 v[90:93], v[148:151], v[180:183], v[90:93]
	v_mfma_f32_16x16x32_f16 v[94:97], v[156:159], v[180:183], v[94:97]
	v_mfma_f32_16x16x32_f16 v[74:77], v[148:151], v[188:191], v[74:77]
	v_mfma_f32_16x16x32_f16 v[78:81], v[156:159], v[188:191], v[78:81]
	s_barrier
	ds_read_b128 v[192:195], v219
	ds_read_b128 v[196:199], v219 offset:1024
	ds_read_b128 v[200:203], v219 offset:2048
	ds_read_b128 v[204:207], v219 offset:3072
	s_mov_b32 m0, s25
	v_lshl_add_u64 v[208:209], v[208:209], 0, s[86:87]
	global_load_lds_dwordx4 v[208:209], off
	s_mov_b32 m0, s26
	v_lshl_add_u64 v[208:209], v[210:211], 0, s[86:87]
	global_load_lds_dwordx4 v[208:209], off
	s_barrier
; #define G_STAGE(bufoff, gbase, v0, v1) do { \
;     __builtin_amdgcn_global_load_lds((const unsigned*)((const char*)(gbase) + (v0)), (LAS unsigned*)(lds + (bufoff) + ldsw), 16, 0, 0); \
;     __builtin_amdgcn_global_load_lds((const unsigned*)((const char*)(gbase) + (v1)), (LAS unsigned*)(lds + (bufoff) + ldsw + 8192), 16, 0, 0); } while (0)
; #define G_LDA(dst, b, h) do { _Pragma("unroll") for (int m = 0; m < 4; ++m) _Pragma("unroll") for (int k = 0; k < 2; ++k) dst[m][k] = *(const LAS h8*)(lds + G_SA(b, h) + aoff + m * 2048 + k * 1024); } while (0)
; #define G_MMA(ai, bj, At, Bt) do { __builtin_amdgcn_s_setprio(1); _Pragma("unroll") for (int m = 0; m < 4; ++m) _Pragma("unroll") for (int n = 0; n < 2; ++n) _Pragma("unroll") for (int k = 0; k < 2; ++k) \
;     acc[ai][bj][m][n] = __builtin_amdgcn_mfma_f32_16x16x32_f16(Bt[n][k], At[m][k], acc[ai][bj][m][n], 0, 0, 0); __builtin_amdgcn_s_setprio(0); } while (0)
; #define G_WAIT_V(n) asm volatile("s_waitcnt vmcnt(" #n ")" ::: "memory")
; #define G_WAIT_L(n) asm volatile("s_waitcnt lgkmcnt(" #n ")" ::: "memory")
; #define G_BAR __builtin_amdgcn_s_barrier()
; #define G_SCHED __builtin_amdgcn_sched_barrier(0)
; template <bool PERM, class Sched, class Epi>
; DI void gemm256(LAS unsigned char* lds, const Sched& S, const Epi& E, int wv_) {
;     ...
;       G_BAR; G_WAIT_L(0); G_MMA(0, 1, At, B1); G_BAR;
;       G_LDA(At, 1, 1); G_STAGE(G_SA(1, 0), a3, cvA0, cvA1);
;       G_BAR; G_WAIT_L(0); G_MMA(1, 0, At, B0); G_BAR; G_SCHED;
;       G_STAGE(G_SB(1, 1), b3 + chB, cvB0, cvB1);
;       G_WAIT_V(6); G_BAR; G_MMA(1, 1, At, B1); G_BAR;
;     }
;     bool keep = false;
;     if constexpr (Sched::CHAIN) keep = E(acc, cur, wr, wc, fr, fq); else E(acc, cur, wr, wc, fr, fq);
;     if (!has_next) break;
	s_waitcnt lgkmcnt(0)
	s_waitcnt lgkmcnt(0)
	v_mfma_f32_16x16x32_f16 v[114:117], v[192:195], v[160:163], v[114:117]
	v_mfma_f32_16x16x32_f16 v[118:121], v[200:203], v[160:163], v[118:121]
	v_mfma_f32_16x16x32_f16 v[98:101], v[192:195], v[168:171], v[98:101]
	v_mfma_f32_16x16x32_f16 v[102:105], v[200:203], v[168:171], v[102:105]
	v_mfma_f32_16x16x32_f16 v[82:85], v[192:195], v[176:179], v[82:85]
	v_mfma_f32_16x16x32_f16 v[86:89], v[200:203], v[176:179], v[86:89]
	v_mfma_f32_16x16x32_f16 v[66:69], v[192:195], v[184:187], v[66:69]
	v_mfma_f32_16x16x32_f16 v[70:73], v[200:203], v[184:187], v[70:73]
	v_mfma_f32_16x16x32_f16 v[114:117], v[196:199], v[164:167], v[114:117]
	v_mfma_f32_16x16x32_f16 v[118:121], v[204:207], v[164:167], v[118:121]
	v_mfma_f32_16x16x32_f16 v[98:101], v[196:199], v[172:175], v[98:101]
	v_mfma_f32_16x16x32_f16 v[102:105], v[204:207], v[172:175], v[102:105]
	v_mfma_f32_16x16x32_f16 v[82:85], v[196:199], v[180:183], v[82:85]
	v_mfma_f32_16x16x32_f16 v[86:89], v[204:207], v[180:183], v[86:89]
	v_mfma_f32_16x16x32_f16 v[66:69], v[196:199], v[188:191], v[66:69]
	v_mfma_f32_16x16x32_f16 v[70:73], v[204:207], v[188:191], v[70:73]
	s_mov_b32 m0, s27
	v_lshl_add_u64 v[208:209], v[212:213], 0, s[86:87]
	s_barrier
	ds_read_b128 v[160:163], v1 offset:49152
	ds_read_b128 v[164:167], v1 offset:50176
	ds_read_b128 v[168:171], v1 offset:51200
	ds_read_b128 v[172:175], v1 offset:52224
	ds_read_b128 v[176:179], v1 offset:53248
	ds_read_b128 v[180:183], v1 offset:54272
	ds_read_b128 v[184:187], v1 offset:55296
	ds_read_b128 v[188:191], v1 offset:56320
	global_load_lds_dwordx4 v[208:209], off
	s_mov_b32 m0, s28
	v_lshl_add_u64 v[208:209], v[214:215], 0, s[86:87]
	global_load_lds_dwordx4 v[208:209], off
	s_barrier
	s_waitcnt lgkmcnt(0)
	s_waitcnt lgkmcnt(0)
	v_mfma_f32_16x16x32_f16 v[58:61], v[144:147], v[160:163], v[58:61]
	v_mfma_f32_16x16x32_f16 v[62:65], v[152:155], v[160:163], v[62:65]
	v_mfma_f32_16x16x32_f16 v[42:45], v[144:147], v[168:171], v[42:45]
	v_mfma_f32_16x16x32_f16 v[46:49], v[152:155], v[168:171], v[46:49]
	v_mfma_f32_16x16x32_f16 v[26:29], v[144:147], v[176:179], v[26:29]
	v_mfma_f32_16x16x32_f16 v[30:33], v[152:155], v[176:179], v[30:33]
	v_mfma_f32_16x16x32_f16 v[10:13], v[144:147], v[184:187], v[10:13]
	v_mfma_f32_16x16x32_f16 v[14:17], v[152:155], v[184:187], v[14:17]
	v_mfma_f32_16x16x32_f16 v[58:61], v[148:151], v[164:167], v[58:61]
	v_mfma_f32_16x16x32_f16 v[62:65], v[156:159], v[164:167], v[62:65]
	v_mfma_f32_16x16x32_f16 v[42:45], v[148:151], v[172:175], v[42:45]
	v_mfma_f32_16x16x32_f16 v[46:49], v[156:159], v[172:175], v[46:49]
	v_mfma_f32_16x16x32_f16 v[26:29], v[148:151], v[180:183], v[26:29]
	v_mfma_f32_16x16x32_f16 v[30:33], v[156:159], v[180:183], v[30:33]
	v_mfma_f32_16x16x32_f16 v[10:13], v[148:151], v[188:191], v[10:13]
	v_mfma_f32_16x16x32_f16 v[14:17], v[156:159], v[188:191], v[14:17]
	s_barrier
	s_add_u32 s8, s12, 0x16080
	s_addc_u32 s9, s13, 0
	s_mov_b32 m0, s29
	v_lshl_add_u64 v[144:145], s[8:9], 0, v[134:135]
	global_load_lds_dwordx4 v[144:145], off
	s_mov_b32 m0, s30
	v_lshl_add_u64 v[144:145], s[8:9], 0, v[130:131]
	global_load_lds_dwordx4 v[144:145], off
	s_waitcnt vmcnt(6)
	s_barrier
	v_mfma_f32_16x16x32_f16 v[50:53], v[192:195], v[160:163], v[50:53]
	v_mfma_f32_16x16x32_f16 v[54:57], v[200:203], v[160:163], v[54:57]
	v_mfma_f32_16x16x32_f16 v[34:37], v[192:195], v[168:171], v[34:37]
	v_mfma_f32_16x16x32_f16 v[38:41], v[200:203], v[168:171], v[38:41]
	v_mfma_f32_16x16x32_f16 v[18:21], v[192:195], v[176:179], v[18:21]
	v_mfma_f32_16x16x32_f16 v[22:25], v[200:203], v[176:179], v[22:25]
	v_mfma_f32_16x16x32_f16 v[6:9], v[192:195], v[184:187], v[6:9]
	v_mfma_f32_16x16x32_f16 v[2:5], v[200:203], v[184:187], v[2:5]
	v_mfma_f32_16x16x32_f16 v[50:53], v[196:199], v[164:167], v[50:53]
	v_mfma_f32_16x16x32_f16 v[54:57], v[204:207], v[164:167], v[54:57]
	v_mfma_f32_16x16x32_f16 v[34:37], v[196:199], v[172:175], v[34:37]
	v_mfma_f32_16x16x32_f16 v[38:41], v[204:207], v[172:175], v[38:41]
	v_mfma_f32_16x16x32_f16 v[18:21], v[196:199], v[180:183], v[18:21]
	v_mfma_f32_16x16x32_f16 v[22:25], v[204:207], v[180:183], v[22:25]
	v_mfma_f32_16x16x32_f16 v[6:9], v[196:199], v[188:191], v[6:9]
	v_mfma_f32_16x16x32_f16 v[2:5], v[204:207], v[188:191], v[2:5]
	s_cmp_ge_i32 s60, s46
	s_mov_b64 s[8:9], s[10:11]
	s_mov_b32 s12, s60
	s_barrier
	s_cbranch_scc0 .LBB0_1748
	s_branch .LBB0_1743

; #define G_STAGE(bufoff, gbase, v0, v1) do { \
;     __builtin_amdgcn_global_load_lds((const unsigned*)((const char*)(gbase) + (v0)), (LAS unsigned*)(lds + (bufoff) + ldsw), 16, 0, 0); \
;     __builtin_amdgcn_global_load_lds((const unsigned*)((const char*)(gbase) + (v1)), (LAS unsigned*)(lds + (bufoff) + ldsw + 8192), 16, 0, 0); } while (0)
; #define G_LDA(dst, b, h) do { _Pragma("unroll") for (int m = 0; m < 4; ++m) _Pragma("unroll") for (int k = 0; k < 2; ++k) dst[m][k] = *(const LAS h8*)(lds + G_SA(b, h) + aoff + m * 2048 + k * 1024); } while (0)
; #define G_LDB(dst, b, h) do { _Pragma("unroll") for (int n = 0; n < 2; ++n) _Pragma("unroll") for (int k = 0; k < 2; ++k) dst[n][k] = *(const LAS h8*)(lds + G_SB(b, h) + boff + n * 2048 + k * 1024); } while (0)
; #define G_MMA(ai, bj, At, Bt) do { __builtin_amdgcn_s_setprio(1); _Pragma("unroll") for (int m = 0; m < 4; ++m) _Pragma("unroll") for (int n = 0; n < 2; ++n) _Pragma("unroll") for (int k = 0; k < 2; ++k) \
;     acc[ai][bj][m][n] = __builtin_amdgcn_mfma_f32_16x16x32_f16(Bt[n][k], At[m][k], acc[ai][bj][m][n], 0, 0, 0); __builtin_amdgcn_s_setprio(0); } while (0)
; #define G_WAIT_V(n) asm volatile("s_waitcnt vmcnt(" #n ")" ::: "memory")
; #define G_WAIT_L(n) asm volatile("s_waitcnt lgkmcnt(" #n ")" ::: "memory")
; #define G_BAR __builtin_amdgcn_s_barrier()
; #define G_SCHED __builtin_amdgcn_sched_barrier(0)
; template <bool PERM, class Sched, class Epi>
; DI void gemm256(LAS unsigned char* lds, const Sched& S, const Epi& E, int wv_) {
;     ...
;       const bool last = (t == nt - 2);
;       const char* a1 = cA + (size_t)(t + 1) * kstep;
;       const char* a2 = last ? nA : cA + (size_t)(t + 2) * kstep;
;       const char* b2 = last ? nB : cB + (size_t)(t + 2) * kstep;
;       const char* a3 = a2 + kstep;
;       const char* b3 = b2 + kstep;
;       G_LDB(B0, 0, 0); G_SCHED; G_LDA(At, 0, 0); G_STAGE(G_SA(1, 1), a1 + chA, cvA0, cvA1);
;       G_WAIT_L(8); G_BAR; G_WAIT_L(0); G_MMA(0, 0, At, B0); G_BAR; G_SCHED;
;       G_LDB(B1, 0, 1); G_STAGE(G_SB(0, 0), b2, cvB0, cvB1);
;       G_BAR; G_WAIT_L(0); G_MMA(0, 1, At, B1); G_BAR;
;       G_LDA(At, 0, 1); G_STAGE(G_SA(0, 0), a2, cvA0, cvA1);
;       G_BAR; G_WAIT_L(0); G_MMA(1, 0, At, B0); G_BAR; G_SCHED;
;       G_STAGE(G_SB(0, 1), b2 + chB, cvB0, cvB1);
;       G_WAIT_V(6); G_BAR; G_MMA(1, 1, At, B1); G_BAR;
.LBB0_2281:
	ds_read_b128 v[148:151], v239
	ds_read_b128 v[152:155], v239 offset:1024
	ds_read_b128 v[156:159], v239 offset:2048
	ds_read_b128 v[160:163], v239 offset:3072
	ds_read_b128 v[164:167], v1
	ds_read_b128 v[168:171], v1 offset:1024
	ds_read_b128 v[172:175], v1 offset:2048
	ds_read_b128 v[176:179], v1 offset:3072
	ds_read_b128 v[180:183], v1 offset:4096
	ds_read_b128 v[184:187], v1 offset:5120
	ds_read_b128 v[188:191], v1 offset:6144
	ds_read_b128 v[192:195], v1 offset:7168
	s_add_i32 s85, s14, 2
	s_add_u32 s15, s12, 0xfffc0080
	s_addc_u32 s16, s13, -1
	s_cmp_eq_u32 s75, s14
	s_cselect_b32 s14, s8, s46
	s_cselect_b32 s17, s7, s16
	s_cselect_b32 s16, s6, s15
	s_cselect_b32 s15, s9, s74
	s_add_i32 m0, s20, 0xc000
	v_lshl_add_u64 v[144:145], s[12:13], 0, v[140:141]
	global_load_lds_dwordx4 v[144:145], off
	s_add_i32 m0, s20, 0xe000
	v_lshl_add_u64 v[144:145], s[12:13], 0, v[142:143]
	global_load_lds_dwordx4 v[144:145], off
	s_waitcnt lgkmcnt(8)
	s_barrier
	s_waitcnt lgkmcnt(0)
	s_waitcnt lgkmcnt(0)
	v_mfma_f32_16x16x32_f16 v[114:117], v[148:151], v[164:167], v[114:117]
	v_mfma_f32_16x16x32_f16 v[126:129], v[156:159], v[164:167], v[126:129]
	v_mfma_f32_16x16x32_f16 v[98:101], v[148:151], v[172:175], v[98:101]
	v_mfma_f32_16x16x32_f16 v[110:113], v[156:159], v[172:175], v[110:113]
	v_mfma_f32_16x16x32_f16 v[82:85], v[148:151], v[180:183], v[82:85]
	v_mfma_f32_16x16x32_f16 v[94:97], v[156:159], v[180:183], v[94:97]
	v_mfma_f32_16x16x32_f16 v[66:69], v[148:151], v[188:191], v[66:69]
	v_mfma_f32_16x16x32_f16 v[78:81], v[156:159], v[188:191], v[78:81]
	v_mfma_f32_16x16x32_f16 v[114:117], v[152:155], v[168:171], v[114:117]
	v_mfma_f32_16x16x32_f16 v[126:129], v[160:163], v[168:171], v[126:129]
	v_mfma_f32_16x16x32_f16 v[98:101], v[152:155], v[176:179], v[98:101]
	v_mfma_f32_16x16x32_f16 v[110:113], v[160:163], v[176:179], v[110:113]
	v_mfma_f32_16x16x32_f16 v[82:85], v[152:155], v[184:187], v[82:85]
	v_mfma_f32_16x16x32_f16 v[94:97], v[160:163], v[184:187], v[94:97]
	v_mfma_f32_16x16x32_f16 v[66:69], v[152:155], v[192:195], v[66:69]
	v_mfma_f32_16x16x32_f16 v[78:81], v[160:163], v[192:195], v[78:81]
	s_barrier
	ds_read_b128 v[196:199], v243
	ds_read_b128 v[200:203], v243 offset:1024
	ds_read_b128 v[204:207], v243 offset:2048
	ds_read_b128 v[208:211], v243 offset:3072
	s_mov_b32 m0, s11
	v_lshl_add_u64 v[144:145], s[14:15], 0, v[132:133]
	global_load_lds_dwordx4 v[144:145], off
	s_mov_b32 m0, s21
	v_lshl_add_u64 v[212:213], s[14:15], 0, v[136:137]
	global_load_lds_dwordx4 v[212:213], off
	s_barrier
	s_waitcnt lgkmcnt(0)
	s_waitcnt lgkmcnt(0)
	v_mfma_f32_16x16x32_f16 v[122:125], v[196:199], v[164:167], v[122:125]
	v_mfma_f32_16x16x32_f16 v[118:121], v[204:207], v[164:167], v[118:121]
	v_mfma_f32_16x16x32_f16 v[106:109], v[196:199], v[172:175], v[106:109]
	v_mfma_f32_16x16x32_f16 v[102:105], v[204:207], v[172:175], v[102:105]
	v_mfma_f32_16x16x32_f16 v[90:93], v[196:199], v[180:183], v[90:93]
	v_mfma_f32_16x16x32_f16 v[86:89], v[204:207], v[180:183], v[86:89]
	v_mfma_f32_16x16x32_f16 v[74:77], v[196:199], v[188:191], v[74:77]
	v_mfma_f32_16x16x32_f16 v[70:73], v[204:207], v[188:191], v[70:73]
	v_mfma_f32_16x16x32_f16 v[122:125], v[200:203], v[168:171], v[122:125]
	v_mfma_f32_16x16x32_f16 v[118:121], v[208:211], v[168:171], v[118:121]
	v_mfma_f32_16x16x32_f16 v[106:109], v[200:203], v[176:179], v[106:109]
	v_mfma_f32_16x16x32_f16 v[102:105], v[208:211], v[176:179], v[102:105]
	v_mfma_f32_16x16x32_f16 v[90:93], v[200:203], v[184:187], v[90:93]
	v_mfma_f32_16x16x32_f16 v[86:89], v[208:211], v[184:187], v[86:89]
	v_mfma_f32_16x16x32_f16 v[74:77], v[200:203], v[192:195], v[74:77]
	v_mfma_f32_16x16x32_f16 v[70:73], v[208:211], v[192:195], v[70:73]
	s_mov_b32 m0, s20
	v_lshl_add_u64 v[214:215], s[16:17], 0, v[130:131]
	s_barrier
	ds_read_b128 v[164:167], v1 offset:16384
	ds_read_b128 v[168:171], v1 offset:17408
	ds_read_b128 v[172:175], v1 offset:18432
	ds_read_b128 v[176:179], v1 offset:19456
	ds_read_b128 v[180:183], v1 offset:20480
	ds_read_b128 v[184:187], v1 offset:21504
	ds_read_b128 v[188:191], v1 offset:22528
	ds_read_b128 v[192:195], v1 offset:23552
	global_load_lds_dwordx4 v[214:215], off
	s_mov_b32 m0, s22
	v_lshl_add_u64 v[216:217], s[16:17], 0, v[134:135]
	global_load_lds_dwordx4 v[216:217], off
	s_barrier
	s_waitcnt lgkmcnt(0)
	s_waitcnt lgkmcnt(0)
	v_mfma_f32_16x16x32_f16 v[50:53], v[148:151], v[164:167], v[50:53]
	v_mfma_f32_16x16x32_f16 v[62:65], v[156:159], v[164:167], v[62:65]
	v_mfma_f32_16x16x32_f16 v[34:37], v[148:151], v[172:175], v[34:37]
	v_mfma_f32_16x16x32_f16 v[46:49], v[156:159], v[172:175], v[46:49]
	v_mfma_f32_16x16x32_f16 v[18:21], v[148:151], v[180:183], v[18:21]
	v_mfma_f32_16x16x32_f16 v[30:33], v[156:159], v[180:183], v[30:33]
	v_mfma_f32_16x16x32_f16 v[2:5], v[148:151], v[188:191], v[2:5]
	v_mfma_f32_16x16x32_f16 v[14:17], v[156:159], v[188:191], v[14:17]
	v_mfma_f32_16x16x32_f16 v[50:53], v[152:155], v[168:171], v[50:53]
	v_mfma_f32_16x16x32_f16 v[62:65], v[160:163], v[168:171], v[62:65]
	v_mfma_f32_16x16x32_f16 v[34:37], v[152:155], v[176:179], v[34:37]
	v_mfma_f32_16x16x32_f16 v[46:49], v[160:163], v[176:179], v[46:49]
	v_mfma_f32_16x16x32_f16 v[18:21], v[152:155], v[184:187], v[18:21]
	v_mfma_f32_16x16x32_f16 v[30:33], v[160:163], v[184:187], v[30:33]
	v_mfma_f32_16x16x32_f16 v[2:5], v[152:155], v[192:195], v[2:5]
	v_mfma_f32_16x16x32_f16 v[14:17], v[160:163], v[192:195], v[14:17]
	s_barrier
	s_add_u32 s40, s14, 0x400000
	s_addc_u32 s41, s15, 0
	s_mov_b32 m0, s23
	v_lshl_add_u64 v[148:149], s[40:41], 0, v[132:133]
	global_load_lds_dwordx4 v[148:149], off
	s_mov_b32 m0, s24
	v_lshl_add_u64 v[148:149], s[40:41], 0, v[136:137]
	global_load_lds_dwordx4 v[148:149], off
	s_waitcnt vmcnt(6)
	s_barrier
; #define G_STAGE(bufoff, gbase, v0, v1) do { \
;     __builtin_amdgcn_global_load_lds((const unsigned*)((const char*)(gbase) + (v0)), (LAS unsigned*)(lds + (bufoff) + ldsw), 16, 0, 0); \
;     __builtin_amdgcn_global_load_lds((const unsigned*)((const char*)(gbase) + (v1)), (LAS unsigned*)(lds + (bufoff) + ldsw + 8192), 16, 0, 0); } while (0)
; #define G_LDA(dst, b, h) do { _Pragma("unroll") for (int m = 0; m < 4; ++m) _Pragma("unroll") for (int k = 0; k < 2; ++k) dst[m][k] = *(const LAS h8*)(lds + G_SA(b, h) + aoff + m * 2048 + k * 1024); } while (0)
; #define G_LDB(dst, b, h) do { _Pragma("unroll") for (int n = 0; n < 2; ++n) _Pragma("unroll") for (int k = 0; k < 2; ++k) dst[n][k] = *(const LAS h8*)(lds + G_SB(b, h) + boff + n * 2048 + k * 1024); } while (0)
; #define G_MMA(ai, bj, At, Bt) do { __builtin_amdgcn_s_setprio(1); _Pragma("unroll") for (int m = 0; m < 4; ++m) _Pragma("unroll") for (int n = 0; n < 2; ++n) _Pragma("unroll") for (int k = 0; k < 2; ++k) \
;     acc[ai][bj][m][n] = __builtin_amdgcn_mfma_f32_16x16x32_f16(Bt[n][k], At[m][k], acc[ai][bj][m][n], 0, 0, 0); __builtin_amdgcn_s_setprio(0); } while (0)
; #define G_WAIT_V(n) asm volatile("s_waitcnt vmcnt(" #n ")" ::: "memory")
; #define G_WAIT_L(n) asm volatile("s_waitcnt lgkmcnt(" #n ")" ::: "memory")
; #define G_BAR __builtin_amdgcn_s_barrier()
; #define G_SCHED __builtin_amdgcn_sched_barrier(0)
; template <bool PERM, class Sched, class Epi>
; DI void gemm256(LAS unsigned char* lds, const Sched& S, const Epi& E, int wv_) {
;     ...
;       G_WAIT_V(6); G_BAR; G_MMA(1, 1, At, B1); G_BAR;
;       G_LDB(B0, 1, 0); G_SCHED; G_LDA(At, 1, 0); G_STAGE(G_SA(0, 1), a2 + chA, cvA0, cvA1);
;       G_WAIT_L(8); G_BAR; G_WAIT_L(0); G_MMA(0, 0, At, B0); G_BAR; G_SCHED;
;       G_LDB(B1, 1, 1); G_STAGE(G_SB(1, 0), b3, cvB0, cvB1);
	v_mfma_f32_16x16x32_f16 v[58:61], v[196:199], v[164:167], v[58:61]
	v_mfma_f32_16x16x32_f16 v[54:57], v[204:207], v[164:167], v[54:57]
	v_mfma_f32_16x16x32_f16 v[42:45], v[196:199], v[172:175], v[42:45]
	v_mfma_f32_16x16x32_f16 v[38:41], v[204:207], v[172:175], v[38:41]
	v_mfma_f32_16x16x32_f16 v[26:29], v[196:199], v[180:183], v[26:29]
	v_mfma_f32_16x16x32_f16 v[22:25], v[204:207], v[180:183], v[22:25]
	v_mfma_f32_16x16x32_f16 v[10:13], v[196:199], v[188:191], v[10:13]
	v_mfma_f32_16x16x32_f16 v[6:9], v[204:207], v[188:191], v[6:9]
	v_mfma_f32_16x16x32_f16 v[58:61], v[200:203], v[168:171], v[58:61]
	v_mfma_f32_16x16x32_f16 v[54:57], v[208:211], v[168:171], v[54:57]
	v_mfma_f32_16x16x32_f16 v[42:45], v[200:203], v[176:179], v[42:45]
	v_mfma_f32_16x16x32_f16 v[38:41], v[208:211], v[176:179], v[38:41]
	v_mfma_f32_16x16x32_f16 v[26:29], v[200:203], v[184:187], v[26:29]
	v_mfma_f32_16x16x32_f16 v[22:25], v[208:211], v[184:187], v[22:25]
	v_mfma_f32_16x16x32_f16 v[10:13], v[200:203], v[192:195], v[10:13]
	v_mfma_f32_16x16x32_f16 v[6:9], v[208:211], v[192:195], v[6:9]
	s_barrier
	ds_read_b128 v[148:151], v244
	ds_read_b128 v[152:155], v244 offset:1024
	ds_read_b128 v[156:159], v244 offset:2048
	ds_read_b128 v[160:163], v244 offset:3072
	ds_read_b128 v[164:167], v1 offset:32768
	ds_read_b128 v[168:171], v1 offset:33792
	ds_read_b128 v[172:175], v1 offset:34816
	ds_read_b128 v[176:179], v1 offset:35840
	ds_read_b128 v[180:183], v1 offset:36864
	ds_read_b128 v[184:187], v1 offset:37888
	ds_read_b128 v[188:191], v1 offset:38912
	ds_read_b128 v[192:195], v1 offset:39936
	s_add_u32 s16, s16, 0x40000
	s_addc_u32 s17, s17, 0
	s_mov_b32 m0, s25
	v_lshl_add_u64 v[196:197], s[16:17], 0, v[130:131]
	global_load_lds_dwordx4 v[196:197], off
	s_mov_b32 m0, s26
	v_lshl_add_u64 v[196:197], s[16:17], 0, v[134:135]
	global_load_lds_dwordx4 v[196:197], off
	s_waitcnt lgkmcnt(8)
	s_barrier
	s_waitcnt lgkmcnt(0)
	s_waitcnt lgkmcnt(0)
	v_mfma_f32_16x16x32_f16 v[114:117], v[148:151], v[164:167], v[114:117]
	v_mfma_f32_16x16x32_f16 v[126:129], v[156:159], v[164:167], v[126:129]
	v_mfma_f32_16x16x32_f16 v[98:101], v[148:151], v[172:175], v[98:101]
	v_mfma_f32_16x16x32_f16 v[110:113], v[156:159], v[172:175], v[110:113]
	v_mfma_f32_16x16x32_f16 v[82:85], v[148:151], v[180:183], v[82:85]
	v_mfma_f32_16x16x32_f16 v[94:97], v[156:159], v[180:183], v[94:97]
	v_mfma_f32_16x16x32_f16 v[66:69], v[148:151], v[188:191], v[66:69]
	v_mfma_f32_16x16x32_f16 v[78:81], v[156:159], v[188:191], v[78:81]
	v_mfma_f32_16x16x32_f16 v[114:117], v[152:155], v[168:171], v[114:117]
	v_mfma_f32_16x16x32_f16 v[126:129], v[160:163], v[168:171], v[126:129]
	v_mfma_f32_16x16x32_f16 v[98:101], v[152:155], v[176:179], v[98:101]
	v_mfma_f32_16x16x32_f16 v[110:113], v[160:163], v[176:179], v[110:113]
	v_mfma_f32_16x16x32_f16 v[82:85], v[152:155], v[184:187], v[82:85]
	v_mfma_f32_16x16x32_f16 v[94:97], v[160:163], v[184:187], v[94:97]
	v_mfma_f32_16x16x32_f16 v[66:69], v[152:155], v[192:195], v[66:69]
	v_mfma_f32_16x16x32_f16 v[78:81], v[160:163], v[192:195], v[78:81]
	s_barrier
	ds_read_b128 v[196:199], v246
	ds_read_b128 v[200:203], v246 offset:1024
	ds_read_b128 v[204:207], v246 offset:2048
	ds_read_b128 v[208:211], v246 offset:3072
	s_mov_b32 m0, s28
	v_lshl_add_u64 v[144:145], v[144:145], 0, s[86:87]
	global_load_lds_dwordx4 v[144:145], off
	s_mov_b32 m0, s29
	v_lshl_add_u64 v[144:145], v[212:213], 0, s[86:87]
	global_load_lds_dwordx4 v[144:145], off
	s_barrier
; #define G_STAGE(bufoff, gbase, v0, v1) do { \
;     __builtin_amdgcn_global_load_lds((const unsigned*)((const char*)(gbase) + (v0)), (LAS unsigned*)(lds + (bufoff) + ldsw), 16, 0, 0); \
;     __builtin_amdgcn_global_load_lds((const unsigned*)((const char*)(gbase) + (v1)), (LAS unsigned*)(lds + (bufoff) + ldsw + 8192), 16, 0, 0); } while (0)
; #define G_LDA(dst, b, h) do { _Pragma("unroll") for (int m = 0; m < 4; ++m) _Pragma("unroll") for (int k = 0; k < 2; ++k) dst[m][k] = *(const LAS h8*)(lds + G_SA(b, h) + aoff + m * 2048 + k * 1024); } while (0)
; #define G_MMA(ai, bj, At, Bt) do { __builtin_amdgcn_s_setprio(1); _Pragma("unroll") for (int m = 0; m < 4; ++m) _Pragma("unroll") for (int n = 0; n < 2; ++n) _Pragma("unroll") for (int k = 0; k < 2; ++k) \
;     acc[ai][bj][m][n] = __builtin_amdgcn_mfma_f32_16x16x32_f16(Bt[n][k], At[m][k], acc[ai][bj][m][n], 0, 0, 0); __builtin_amdgcn_s_setprio(0); } while (0)
; #define G_WAIT_V(n) asm volatile("s_waitcnt vmcnt(" #n ")" ::: "memory")
; #define G_WAIT_L(n) asm volatile("s_waitcnt lgkmcnt(" #n ")" ::: "memory")
; #define G_BAR __builtin_amdgcn_s_barrier()
; #define G_SCHED __builtin_amdgcn_sched_barrier(0)
; template <bool PERM, class Sched, class Epi>
; DI void gemm256(LAS unsigned char* lds, const Sched& S, const Epi& E, int wv_) {
;     ...
;       G_BAR; G_WAIT_L(0); G_MMA(0, 1, At, B1); G_BAR;
;       G_LDA(At, 1, 1); G_STAGE(G_SA(1, 0), a3, cvA0, cvA1);
;       G_BAR; G_WAIT_L(0); G_MMA(1, 0, At, B0); G_BAR; G_SCHED;
;       G_STAGE(G_SB(1, 1), b3 + chB, cvB0, cvB1);
;       G_WAIT_V(6); G_BAR; G_MMA(1, 1, At, B1); G_BAR;
;     }
;     bool keep = false;
;     if constexpr (Sched::CHAIN) keep = E(acc, cur, wr, wc, fr, fq); else E(acc, cur, wr, wc, fr, fq);
;     if (!has_next) break;
	s_waitcnt lgkmcnt(0)
	s_waitcnt lgkmcnt(0)
	v_mfma_f32_16x16x32_f16 v[122:125], v[196:199], v[164:167], v[122:125]
	v_mfma_f32_16x16x32_f16 v[118:121], v[204:207], v[164:167], v[118:121]
	v_mfma_f32_16x16x32_f16 v[106:109], v[196:199], v[172:175], v[106:109]
	v_mfma_f32_16x16x32_f16 v[102:105], v[204:207], v[172:175], v[102:105]
	v_mfma_f32_16x16x32_f16 v[90:93], v[196:199], v[180:183], v[90:93]
	v_mfma_f32_16x16x32_f16 v[86:89], v[204:207], v[180:183], v[86:89]
	v_mfma_f32_16x16x32_f16 v[74:77], v[196:199], v[188:191], v[74:77]
	v_mfma_f32_16x16x32_f16 v[70:73], v[204:207], v[188:191], v[70:73]
	v_mfma_f32_16x16x32_f16 v[122:125], v[200:203], v[168:171], v[122:125]
	v_mfma_f32_16x16x32_f16 v[118:121], v[208:211], v[168:171], v[118:121]
	v_mfma_f32_16x16x32_f16 v[106:109], v[200:203], v[176:179], v[106:109]
	v_mfma_f32_16x16x32_f16 v[102:105], v[208:211], v[176:179], v[102:105]
	v_mfma_f32_16x16x32_f16 v[90:93], v[200:203], v[184:187], v[90:93]
	v_mfma_f32_16x16x32_f16 v[86:89], v[208:211], v[184:187], v[86:89]
	v_mfma_f32_16x16x32_f16 v[74:77], v[200:203], v[192:195], v[74:77]
	v_mfma_f32_16x16x32_f16 v[70:73], v[208:211], v[192:195], v[70:73]
	s_mov_b32 m0, s30
	v_lshl_add_u64 v[144:145], v[214:215], 0, s[86:87]
	s_barrier
	ds_read_b128 v[164:167], v1 offset:49152
	ds_read_b128 v[168:171], v1 offset:50176
	ds_read_b128 v[172:175], v1 offset:51200
	ds_read_b128 v[176:179], v1 offset:52224
	ds_read_b128 v[180:183], v1 offset:53248
	ds_read_b128 v[184:187], v1 offset:54272
	ds_read_b128 v[188:191], v1 offset:55296
	ds_read_b128 v[192:195], v1 offset:56320
	global_load_lds_dwordx4 v[144:145], off
	s_mov_b32 m0, s31
	v_lshl_add_u64 v[144:145], v[216:217], 0, s[86:87]
	global_load_lds_dwordx4 v[144:145], off
	s_barrier
	s_waitcnt lgkmcnt(0)
	s_waitcnt lgkmcnt(0)
	v_mfma_f32_16x16x32_f16 v[50:53], v[148:151], v[164:167], v[50:53]
	v_mfma_f32_16x16x32_f16 v[62:65], v[156:159], v[164:167], v[62:65]
	v_mfma_f32_16x16x32_f16 v[34:37], v[148:151], v[172:175], v[34:37]
	v_mfma_f32_16x16x32_f16 v[46:49], v[156:159], v[172:175], v[46:49]
	v_mfma_f32_16x16x32_f16 v[18:21], v[148:151], v[180:183], v[18:21]
	v_mfma_f32_16x16x32_f16 v[30:33], v[156:159], v[180:183], v[30:33]
	v_mfma_f32_16x16x32_f16 v[2:5], v[148:151], v[188:191], v[2:5]
	v_mfma_f32_16x16x32_f16 v[14:17], v[156:159], v[188:191], v[14:17]
	v_mfma_f32_16x16x32_f16 v[50:53], v[152:155], v[168:171], v[50:53]
	v_mfma_f32_16x16x32_f16 v[62:65], v[160:163], v[168:171], v[62:65]
	v_mfma_f32_16x16x32_f16 v[34:37], v[152:155], v[176:179], v[34:37]
	v_mfma_f32_16x16x32_f16 v[46:49], v[160:163], v[176:179], v[46:49]
	v_mfma_f32_16x16x32_f16 v[18:21], v[152:155], v[184:187], v[18:21]
	v_mfma_f32_16x16x32_f16 v[30:33], v[160:163], v[184:187], v[30:33]
	v_mfma_f32_16x16x32_f16 v[2:5], v[152:155], v[192:195], v[2:5]
	v_mfma_f32_16x16x32_f16 v[14:17], v[160:163], v[192:195], v[14:17]
	s_barrier
	s_add_u32 s14, s14, 0x400080
	s_addc_u32 s15, s15, 0
	s_mov_b32 m0, s34
	v_lshl_add_u64 v[144:145], s[14:15], 0, v[132:133]
	global_load_lds_dwordx4 v[144:145], off
	s_mov_b32 m0, s35
	v_lshl_add_u64 v[144:145], s[14:15], 0, v[136:137]
	global_load_lds_dwordx4 v[144:145], off
	s_waitcnt vmcnt(6)
	s_barrier
	v_mfma_f32_16x16x32_f16 v[58:61], v[196:199], v[164:167], v[58:61]
	v_mfma_f32_16x16x32_f16 v[54:57], v[204:207], v[164:167], v[54:57]
	v_mfma_f32_16x16x32_f16 v[42:45], v[196:199], v[172:175], v[42:45]
	v_mfma_f32_16x16x32_f16 v[38:41], v[204:207], v[172:175], v[38:41]
	v_mfma_f32_16x16x32_f16 v[26:29], v[196:199], v[180:183], v[26:29]
	v_mfma_f32_16x16x32_f16 v[22:25], v[204:207], v[180:183], v[22:25]
	v_mfma_f32_16x16x32_f16 v[10:13], v[196:199], v[188:191], v[10:13]
	v_mfma_f32_16x16x32_f16 v[6:9], v[204:207], v[188:191], v[6:9]
	v_mfma_f32_16x16x32_f16 v[58:61], v[200:203], v[168:171], v[58:61]
	v_mfma_f32_16x16x32_f16 v[54:57], v[208:211], v[168:171], v[54:57]
	v_mfma_f32_16x16x32_f16 v[42:45], v[200:203], v[176:179], v[42:45]
	v_mfma_f32_16x16x32_f16 v[38:41], v[208:211], v[176:179], v[38:41]
	v_mfma_f32_16x16x32_f16 v[26:29], v[200:203], v[184:187], v[26:29]
	v_mfma_f32_16x16x32_f16 v[22:25], v[208:211], v[184:187], v[22:25]
	v_mfma_f32_16x16x32_f16 v[10:13], v[200:203], v[192:195], v[10:13]
	v_mfma_f32_16x16x32_f16 v[6:9], v[208:211], v[192:195], v[6:9]
	s_add_u32 s12, s12, 0x100
	s_addc_u32 s13, s13, 0
	s_add_u32 s46, s46, 0x100
	s_addc_u32 s74, s74, 0
	s_cmp_ge_i32 s85, s5
	s_mov_b32 s14, s85
	s_barrier
	s_cbranch_scc0 .LBB0_2281
	s_branch .LBB0_2268

; #define G_STAGE(bufoff, gbase, v0, v1) do { \
;     __builtin_amdgcn_global_load_lds((const unsigned*)((const char*)(gbase) + (v0)), (LAS unsigned*)(lds + (bufoff) + ldsw), 16, 0, 0); \
;     __builtin_amdgcn_global_load_lds((const unsigned*)((const char*)(gbase) + (v1)), (LAS unsigned*)(lds + (bufoff) + ldsw + 8192), 16, 0, 0); } while (0)
; #define G_LDA(dst, b, h) do { _Pragma("unroll") for (int m = 0; m < 4; ++m) _Pragma("unroll") for (int k = 0; k < 2; ++k) dst[m][k] = *(const LAS h8*)(lds + G_SA(b, h) + aoff + m * 2048 + k * 1024); } while (0)
; #define G_LDB(dst, b, h) do { _Pragma("unroll") for (int n = 0; n < 2; ++n) _Pragma("unroll") for (int k = 0; k < 2; ++k) dst[n][k] = *(const LAS h8*)(lds + G_SB(b, h) + boff + n * 2048 + k * 1024); } while (0)
; #define G_MMA(ai, bj, At, Bt) do { __builtin_amdgcn_s_setprio(1); _Pragma("unroll") for (int m = 0; m < 4; ++m) _Pragma("unroll") for (int n = 0; n < 2; ++n) _Pragma("unroll") for (int k = 0; k < 2; ++k) \
;     acc[ai][bj][m][n] = __builtin_amdgcn_mfma_f32_16x16x32_f16(Bt[n][k], At[m][k], acc[ai][bj][m][n], 0, 0, 0); __builtin_amdgcn_s_setprio(0); } while (0)
; #define G_WAIT_V(n) asm volatile("s_waitcnt vmcnt(" #n ")" ::: "memory")
; #define G_WAIT_L(n) asm volatile("s_waitcnt lgkmcnt(" #n ")" ::: "memory")
; #define G_BAR __builtin_amdgcn_s_barrier()
; #define G_SCHED __builtin_amdgcn_sched_barrier(0)
; template <bool PERM, class Sched, class Epi>
; DI void gemm256(LAS unsigned char* lds, const Sched& S, const Epi& E, int wv_) {
;     ...
;       const bool last = (t == nt - 2);
;       const char* a1 = cA + (size_t)(t + 1) * kstep;
;       const char* a2 = last ? nA : cA + (size_t)(t + 2) * kstep;
;       const char* b2 = last ? nB : cB + (size_t)(t + 2) * kstep;
;       const char* a3 = a2 + kstep;
;       const char* b3 = b2 + kstep;
;       G_LDB(B0, 0, 0); G_SCHED; G_LDA(At, 0, 0); G_STAGE(G_SA(1, 1), a1 + chA, cvA0, cvA1);
;       G_WAIT_L(8); G_BAR; G_WAIT_L(0); G_MMA(0, 0, At, B0); G_BAR; G_SCHED;
;       G_LDB(B1, 0, 1); G_STAGE(G_SB(0, 0), b2, cvB0, cvB1);
;       G_BAR; G_WAIT_L(0); G_MMA(0, 1, At, B1); G_BAR;
;       G_LDA(At, 0, 1); G_STAGE(G_SA(0, 0), a2, cvA0, cvA1);
;       G_BAR; G_WAIT_L(0); G_MMA(1, 0, At, B0); G_BAR; G_SCHED;
;       G_STAGE(G_SB(0, 1), b2 + chB, cvB0, cvB1);
;       G_WAIT_V(6); G_BAR; G_MMA(1, 1, At, B1); G_BAR;
.LBB0_2355:
	ds_read_b128 v[132:135], v201
	ds_read_b128 v[136:139], v201 offset:1024
	ds_read_b128 v[140:143], v201 offset:2048
	ds_read_b128 v[144:147], v201 offset:3072
	ds_read_b128 v[148:151], v184
	ds_read_b128 v[152:155], v184 offset:1024
	ds_read_b128 v[156:159], v184 offset:2048
	ds_read_b128 v[160:163], v184 offset:3072
	ds_read_b128 v[164:167], v184 offset:4096
	ds_read_b128 v[168:171], v184 offset:5120
	ds_read_b128 v[172:175], v184 offset:6144
	ds_read_b128 v[176:179], v184 offset:7168
	s_add_i32 s85, s10, 2
	s_add_u32 s11, s8, 0xfffc0080
	s_addc_u32 s12, s9, -1
	s_cmp_eq_u32 s69, s10
	s_cselect_b32 s10, s4, s74
	s_cselect_b32 s13, s3, s12
	s_cselect_b32 s12, s2, s11
	s_cselect_b32 s11, s5, s75
	s_add_i32 m0, s16, 0xc000
	v_lshl_add_u64 v[2:3], s[8:9], 0, v[196:197]
	global_load_lds_dwordx4 v[2:3], off
	s_add_i32 m0, s16, 0xe000
	v_lshl_add_u64 v[2:3], s[8:9], 0, v[198:199]
	global_load_lds_dwordx4 v[2:3], off
	s_waitcnt lgkmcnt(8)
	s_barrier
	s_waitcnt lgkmcnt(0)
	s_waitcnt lgkmcnt(0)
	v_mfma_f32_16x16x32_f16 v[128:131], v[132:135], v[148:151], v[128:131]
	v_mfma_f32_16x16x32_f16 v[124:127], v[140:143], v[148:151], v[124:127]
	v_mfma_f32_16x16x32_f16 v[120:123], v[132:135], v[156:159], v[120:123]
	v_mfma_f32_16x16x32_f16 v[116:119], v[140:143], v[156:159], v[116:119]
	v_mfma_f32_16x16x32_f16 v[112:115], v[132:135], v[164:167], v[112:115]
	v_mfma_f32_16x16x32_f16 v[108:111], v[140:143], v[164:167], v[108:111]
	v_mfma_f32_16x16x32_f16 v[104:107], v[132:135], v[172:175], v[104:107]
	v_mfma_f32_16x16x32_f16 v[100:103], v[140:143], v[172:175], v[100:103]
	v_mfma_f32_16x16x32_f16 v[128:131], v[136:139], v[152:155], v[128:131]
	v_mfma_f32_16x16x32_f16 v[124:127], v[144:147], v[152:155], v[124:127]
	v_mfma_f32_16x16x32_f16 v[120:123], v[136:139], v[160:163], v[120:123]
	v_mfma_f32_16x16x32_f16 v[116:119], v[144:147], v[160:163], v[116:119]
	v_mfma_f32_16x16x32_f16 v[112:115], v[136:139], v[168:171], v[112:115]
	v_mfma_f32_16x16x32_f16 v[108:111], v[144:147], v[168:171], v[108:111]
	v_mfma_f32_16x16x32_f16 v[104:107], v[136:139], v[176:179], v[104:107]
	v_mfma_f32_16x16x32_f16 v[100:103], v[144:147], v[176:179], v[100:103]
	s_barrier
	ds_read_b128 v[180:183], v239
	ds_read_b128 v[202:205], v239 offset:1024
	ds_read_b128 v[206:209], v239 offset:2048
	ds_read_b128 v[210:213], v239 offset:3072
	s_mov_b32 m0, s17
	v_lshl_add_u64 v[214:215], s[10:11], 0, v[188:189]
	global_load_lds_dwordx4 v[214:215], off
	s_mov_b32 m0, s18
	v_lshl_add_u64 v[216:217], s[10:11], 0, v[192:193]
	global_load_lds_dwordx4 v[216:217], off
	s_barrier
	s_waitcnt lgkmcnt(0)
	s_waitcnt lgkmcnt(0)
	v_mfma_f32_16x16x32_f16 v[96:99], v[180:183], v[148:151], v[96:99]
	v_mfma_f32_16x16x32_f16 v[92:95], v[206:209], v[148:151], v[92:95]
	v_mfma_f32_16x16x32_f16 v[88:91], v[180:183], v[156:159], v[88:91]
	v_mfma_f32_16x16x32_f16 v[84:87], v[206:209], v[156:159], v[84:87]
	v_mfma_f32_16x16x32_f16 v[80:83], v[180:183], v[164:167], v[80:83]
	v_mfma_f32_16x16x32_f16 v[76:79], v[206:209], v[164:167], v[76:79]
	v_mfma_f32_16x16x32_f16 v[72:75], v[180:183], v[172:175], v[72:75]
	v_mfma_f32_16x16x32_f16 v[68:71], v[206:209], v[172:175], v[68:71]
	v_mfma_f32_16x16x32_f16 v[96:99], v[202:205], v[152:155], v[96:99]
	v_mfma_f32_16x16x32_f16 v[92:95], v[210:213], v[152:155], v[92:95]
	v_mfma_f32_16x16x32_f16 v[88:91], v[202:205], v[160:163], v[88:91]
	v_mfma_f32_16x16x32_f16 v[84:87], v[210:213], v[160:163], v[84:87]
	v_mfma_f32_16x16x32_f16 v[80:83], v[202:205], v[168:171], v[80:83]
	v_mfma_f32_16x16x32_f16 v[76:79], v[210:213], v[168:171], v[76:79]
	v_mfma_f32_16x16x32_f16 v[72:75], v[202:205], v[176:179], v[72:75]
	v_mfma_f32_16x16x32_f16 v[68:71], v[210:213], v[176:179], v[68:71]
	s_mov_b32 m0, s16
	v_lshl_add_u64 v[218:219], s[12:13], 0, v[186:187]
	s_barrier
	ds_read_b128 v[148:151], v184 offset:16384
	ds_read_b128 v[152:155], v184 offset:17408
	ds_read_b128 v[156:159], v184 offset:18432
	ds_read_b128 v[160:163], v184 offset:19456
	ds_read_b128 v[164:167], v184 offset:20480
	ds_read_b128 v[168:171], v184 offset:21504
	ds_read_b128 v[172:175], v184 offset:22528
	ds_read_b128 v[176:179], v184 offset:23552
	global_load_lds_dwordx4 v[218:219], off
	s_mov_b32 m0, s19
	v_lshl_add_u64 v[220:221], s[12:13], 0, v[190:191]
	global_load_lds_dwordx4 v[220:221], off
	s_barrier
	s_waitcnt lgkmcnt(0)
	s_waitcnt lgkmcnt(0)
	v_mfma_f32_16x16x32_f16 v[64:67], v[132:135], v[148:151], v[64:67]
	v_mfma_f32_16x16x32_f16 v[60:63], v[140:143], v[148:151], v[60:63]
	v_mfma_f32_16x16x32_f16 v[56:59], v[132:135], v[156:159], v[56:59]
	v_mfma_f32_16x16x32_f16 v[52:55], v[140:143], v[156:159], v[52:55]
	v_mfma_f32_16x16x32_f16 v[48:51], v[132:135], v[164:167], v[48:51]
	v_mfma_f32_16x16x32_f16 v[44:47], v[140:143], v[164:167], v[44:47]
	v_mfma_f32_16x16x32_f16 v[40:43], v[132:135], v[172:175], v[40:43]
	v_mfma_f32_16x16x32_f16 v[36:39], v[140:143], v[172:175], v[36:39]
	v_mfma_f32_16x16x32_f16 v[64:67], v[136:139], v[152:155], v[64:67]
	v_mfma_f32_16x16x32_f16 v[60:63], v[144:147], v[152:155], v[60:63]
	v_mfma_f32_16x16x32_f16 v[56:59], v[136:139], v[160:163], v[56:59]
	v_mfma_f32_16x16x32_f16 v[52:55], v[144:147], v[160:163], v[52:55]
	v_mfma_f32_16x16x32_f16 v[48:51], v[136:139], v[168:171], v[48:51]
	v_mfma_f32_16x16x32_f16 v[44:47], v[144:147], v[168:171], v[44:47]
	v_mfma_f32_16x16x32_f16 v[40:43], v[136:139], v[176:179], v[40:43]
	v_mfma_f32_16x16x32_f16 v[36:39], v[144:147], v[176:179], v[36:39]
	s_barrier
	s_add_u32 s40, s10, 0x10000
	s_addc_u32 s41, s11, 0
	s_mov_b32 m0, s20
	v_lshl_add_u64 v[2:3], s[40:41], 0, v[188:189]
	global_load_lds_dwordx4 v[2:3], off
	s_mov_b32 m0, s21
	v_lshl_add_u64 v[2:3], s[40:41], 0, v[192:193]
	global_load_lds_dwordx4 v[2:3], off
	s_waitcnt vmcnt(6)
	s_barrier
; #define G_STAGE(bufoff, gbase, v0, v1) do { \
;     __builtin_amdgcn_global_load_lds((const unsigned*)((const char*)(gbase) + (v0)), (LAS unsigned*)(lds + (bufoff) + ldsw), 16, 0, 0); \
;     __builtin_amdgcn_global_load_lds((const unsigned*)((const char*)(gbase) + (v1)), (LAS unsigned*)(lds + (bufoff) + ldsw + 8192), 16, 0, 0); } while (0)
; #define G_LDA(dst, b, h) do { _Pragma("unroll") for (int m = 0; m < 4; ++m) _Pragma("unroll") for (int k = 0; k < 2; ++k) dst[m][k] = *(const LAS h8*)(lds + G_SA(b, h) + aoff + m * 2048 + k * 1024); } while (0)
; #define G_LDB(dst, b, h) do { _Pragma("unroll") for (int n = 0; n < 2; ++n) _Pragma("unroll") for (int k = 0; k < 2; ++k) dst[n][k] = *(const LAS h8*)(lds + G_SB(b, h) + boff + n * 2048 + k * 1024); } while (0)
; #define G_MMA(ai, bj, At, Bt) do { __builtin_amdgcn_s_setprio(1); _Pragma("unroll") for (int m = 0; m < 4; ++m) _Pragma("unroll") for (int n = 0; n < 2; ++n) _Pragma("unroll") for (int k = 0; k < 2; ++k) \
;     acc[ai][bj][m][n] = __builtin_amdgcn_mfma_f32_16x16x32_f16(Bt[n][k], At[m][k], acc[ai][bj][m][n], 0, 0, 0); __builtin_amdgcn_s_setprio(0); } while (0)
; #define G_WAIT_V(n) asm volatile("s_waitcnt vmcnt(" #n ")" ::: "memory")
; #define G_WAIT_L(n) asm volatile("s_waitcnt lgkmcnt(" #n ")" ::: "memory")
; #define G_BAR __builtin_amdgcn_s_barrier()
; #define G_SCHED __builtin_amdgcn_sched_barrier(0)
; template <bool PERM, class Sched, class Epi>
; DI void gemm256(LAS unsigned char* lds, const Sched& S, const Epi& E, int wv_) {
;     ...
;       G_WAIT_V(6); G_BAR; G_MMA(1, 1, At, B1); G_BAR;
;       G_LDB(B0, 1, 0); G_SCHED; G_LDA(At, 1, 0); G_STAGE(G_SA(0, 1), a2 + chA, cvA0, cvA1);
;       G_WAIT_L(8); G_BAR; G_WAIT_L(0); G_MMA(0, 0, At, B0); G_BAR; G_SCHED;
;       G_LDB(B1, 1, 1); G_STAGE(G_SB(1, 0), b3, cvB0, cvB1);
	v_mfma_f32_16x16x32_f16 v[32:35], v[180:183], v[148:151], v[32:35]
	v_mfma_f32_16x16x32_f16 v[28:31], v[206:209], v[148:151], v[28:31]
	v_mfma_f32_16x16x32_f16 v[24:27], v[180:183], v[156:159], v[24:27]
	v_mfma_f32_16x16x32_f16 v[20:23], v[206:209], v[156:159], v[20:23]
	v_mfma_f32_16x16x32_f16 v[16:19], v[180:183], v[164:167], v[16:19]
	v_mfma_f32_16x16x32_f16 v[12:15], v[206:209], v[164:167], v[12:15]
	v_mfma_f32_16x16x32_f16 v[8:11], v[180:183], v[172:175], v[8:11]
	v_mfma_f32_16x16x32_f16 v[2:5], v[206:209], v[172:175], v[4:7]
	v_mfma_f32_16x16x32_f16 v[32:35], v[202:205], v[152:155], v[32:35]
	v_mfma_f32_16x16x32_f16 v[28:31], v[210:213], v[152:155], v[28:31]
	v_mfma_f32_16x16x32_f16 v[24:27], v[202:205], v[160:163], v[24:27]
	v_mfma_f32_16x16x32_f16 v[20:23], v[210:213], v[160:163], v[20:23]
	v_mfma_f32_16x16x32_f16 v[16:19], v[202:205], v[168:171], v[16:19]
	v_mfma_f32_16x16x32_f16 v[12:15], v[210:213], v[168:171], v[12:15]
	v_mfma_f32_16x16x32_f16 v[8:11], v[202:205], v[176:179], v[8:11]
	v_mfma_f32_16x16x32_f16 v[2:5], v[210:213], v[176:179], v[2:5]
	s_barrier
	ds_read_b128 v[132:135], v243
	ds_read_b128 v[136:139], v243 offset:1024
	ds_read_b128 v[140:143], v243 offset:2048
	ds_read_b128 v[144:147], v243 offset:3072
	ds_read_b128 v[148:151], v184 offset:32768
	ds_read_b128 v[152:155], v184 offset:33792
	ds_read_b128 v[156:159], v184 offset:34816
	ds_read_b128 v[160:163], v184 offset:35840
	ds_read_b128 v[164:167], v184 offset:36864
	ds_read_b128 v[168:171], v184 offset:37888
	ds_read_b128 v[172:175], v184 offset:38912
	ds_read_b128 v[176:179], v184 offset:39936
	s_add_u32 s12, s12, 0x40000
	s_addc_u32 s13, s13, 0
	s_mov_b32 m0, s22
	v_lshl_add_u64 v[6:7], s[12:13], 0, v[186:187]
	global_load_lds_dwordx4 v[6:7], off
	s_mov_b32 m0, s23
	v_lshl_add_u64 v[6:7], s[12:13], 0, v[190:191]
	global_load_lds_dwordx4 v[6:7], off
	s_waitcnt lgkmcnt(8)
	s_barrier
	s_waitcnt lgkmcnt(0)
	s_waitcnt lgkmcnt(0)
	v_mfma_f32_16x16x32_f16 v[128:131], v[132:135], v[148:151], v[128:131]
	v_mfma_f32_16x16x32_f16 v[124:127], v[140:143], v[148:151], v[124:127]
	v_mfma_f32_16x16x32_f16 v[120:123], v[132:135], v[156:159], v[120:123]
	v_mfma_f32_16x16x32_f16 v[116:119], v[140:143], v[156:159], v[116:119]
	v_mfma_f32_16x16x32_f16 v[112:115], v[132:135], v[164:167], v[112:115]
	v_mfma_f32_16x16x32_f16 v[108:111], v[140:143], v[164:167], v[108:111]
	v_mfma_f32_16x16x32_f16 v[104:107], v[132:135], v[172:175], v[104:107]
	v_mfma_f32_16x16x32_f16 v[100:103], v[140:143], v[172:175], v[100:103]
	v_mfma_f32_16x16x32_f16 v[128:131], v[136:139], v[152:155], v[128:131]
	v_mfma_f32_16x16x32_f16 v[124:127], v[144:147], v[152:155], v[124:127]
	v_mfma_f32_16x16x32_f16 v[120:123], v[136:139], v[160:163], v[120:123]
	v_mfma_f32_16x16x32_f16 v[116:119], v[144:147], v[160:163], v[116:119]
	v_mfma_f32_16x16x32_f16 v[112:115], v[136:139], v[168:171], v[112:115]
	v_mfma_f32_16x16x32_f16 v[108:111], v[144:147], v[168:171], v[108:111]
	v_mfma_f32_16x16x32_f16 v[104:107], v[136:139], v[176:179], v[104:107]
	v_mfma_f32_16x16x32_f16 v[100:103], v[144:147], v[176:179], v[100:103]
	s_barrier
	ds_read_b128 v[180:183], v244
	ds_read_b128 v[202:205], v244 offset:1024
	ds_read_b128 v[206:209], v244 offset:2048
	ds_read_b128 v[210:213], v244 offset:3072
	s_mov_b32 m0, s26
	v_lshl_add_u64 v[6:7], v[214:215], 0, s[86:87]
	global_load_lds_dwordx4 v[6:7], off
	s_mov_b32 m0, s27
	v_lshl_add_u64 v[6:7], v[216:217], 0, s[86:87]
	global_load_lds_dwordx4 v[6:7], off
	s_barrier
; #define G_STAGE(bufoff, gbase, v0, v1) do { \
;     __builtin_amdgcn_global_load_lds((const unsigned*)((const char*)(gbase) + (v0)), (LAS unsigned*)(lds + (bufoff) + ldsw), 16, 0, 0); \
;     __builtin_amdgcn_global_load_lds((const unsigned*)((const char*)(gbase) + (v1)), (LAS unsigned*)(lds + (bufoff) + ldsw + 8192), 16, 0, 0); } while (0)
; #define G_LDA(dst, b, h) do { _Pragma("unroll") for (int m = 0; m < 4; ++m) _Pragma("unroll") for (int k = 0; k < 2; ++k) dst[m][k] = *(const LAS h8*)(lds + G_SA(b, h) + aoff + m * 2048 + k * 1024); } while (0)
; #define G_MMA(ai, bj, At, Bt) do { __builtin_amdgcn_s_setprio(1); _Pragma("unroll") for (int m = 0; m < 4; ++m) _Pragma("unroll") for (int n = 0; n < 2; ++n) _Pragma("unroll") for (int k = 0; k < 2; ++k) \
;     acc[ai][bj][m][n] = __builtin_amdgcn_mfma_f32_16x16x32_f16(Bt[n][k], At[m][k], acc[ai][bj][m][n], 0, 0, 0); __builtin_amdgcn_s_setprio(0); } while (0)
; #define G_WAIT_V(n) asm volatile("s_waitcnt vmcnt(" #n ")" ::: "memory")
; #define G_WAIT_L(n) asm volatile("s_waitcnt lgkmcnt(" #n ")" ::: "memory")
; #define G_BAR __builtin_amdgcn_s_barrier()
; #define G_SCHED __builtin_amdgcn_sched_barrier(0)
; template <bool PERM, class Sched, class Epi>
; DI void gemm256(LAS unsigned char* lds, const Sched& S, const Epi& E, int wv_) {
;     ...
;       G_BAR; G_WAIT_L(0); G_MMA(0, 1, At, B1); G_BAR;
;       G_LDA(At, 1, 1); G_STAGE(G_SA(1, 0), a3, cvA0, cvA1);
;       G_BAR; G_WAIT_L(0); G_MMA(1, 0, At, B0); G_BAR; G_SCHED;
;       G_STAGE(G_SB(1, 1), b3 + chB, cvB0, cvB1);
;       G_WAIT_V(6); G_BAR; G_MMA(1, 1, At, B1); G_BAR;
;     }
;     bool keep = false;
;     if constexpr (Sched::CHAIN) keep = E(acc, cur, wr, wc, fr, fq); else E(acc, cur, wr, wc, fr, fq);
;     if (!has_next) break;
	s_waitcnt lgkmcnt(0)
	s_waitcnt lgkmcnt(0)
	v_mfma_f32_16x16x32_f16 v[96:99], v[180:183], v[148:151], v[96:99]
	v_mfma_f32_16x16x32_f16 v[92:95], v[206:209], v[148:151], v[92:95]
	v_mfma_f32_16x16x32_f16 v[88:91], v[180:183], v[156:159], v[88:91]
	v_mfma_f32_16x16x32_f16 v[84:87], v[206:209], v[156:159], v[84:87]
	v_mfma_f32_16x16x32_f16 v[80:83], v[180:183], v[164:167], v[80:83]
	v_mfma_f32_16x16x32_f16 v[76:79], v[206:209], v[164:167], v[76:79]
	v_mfma_f32_16x16x32_f16 v[72:75], v[180:183], v[172:175], v[72:75]
	v_mfma_f32_16x16x32_f16 v[68:71], v[206:209], v[172:175], v[68:71]
	v_mfma_f32_16x16x32_f16 v[96:99], v[202:205], v[152:155], v[96:99]
	v_mfma_f32_16x16x32_f16 v[92:95], v[210:213], v[152:155], v[92:95]
	v_mfma_f32_16x16x32_f16 v[88:91], v[202:205], v[160:163], v[88:91]
	v_mfma_f32_16x16x32_f16 v[84:87], v[210:213], v[160:163], v[84:87]
	v_mfma_f32_16x16x32_f16 v[80:83], v[202:205], v[168:171], v[80:83]
	v_mfma_f32_16x16x32_f16 v[76:79], v[210:213], v[168:171], v[76:79]
	v_mfma_f32_16x16x32_f16 v[72:75], v[202:205], v[176:179], v[72:75]
	v_mfma_f32_16x16x32_f16 v[68:71], v[210:213], v[176:179], v[68:71]
	s_mov_b32 m0, s28
	v_lshl_add_u64 v[6:7], v[218:219], 0, s[86:87]
	s_barrier
	ds_read_b128 v[148:151], v184 offset:49152
	ds_read_b128 v[152:155], v184 offset:50176
	ds_read_b128 v[156:159], v184 offset:51200
	ds_read_b128 v[160:163], v184 offset:52224
	ds_read_b128 v[164:167], v184 offset:53248
	ds_read_b128 v[168:171], v184 offset:54272
	ds_read_b128 v[172:175], v184 offset:55296
	ds_read_b128 v[176:179], v184 offset:56320
	global_load_lds_dwordx4 v[6:7], off
	s_mov_b32 m0, s29
	v_lshl_add_u64 v[6:7], v[220:221], 0, s[86:87]
	global_load_lds_dwordx4 v[6:7], off
	s_barrier
	s_waitcnt lgkmcnt(0)
	s_waitcnt lgkmcnt(0)
	v_mfma_f32_16x16x32_f16 v[64:67], v[132:135], v[148:151], v[64:67]
	v_mfma_f32_16x16x32_f16 v[60:63], v[140:143], v[148:151], v[60:63]
	v_mfma_f32_16x16x32_f16 v[56:59], v[132:135], v[156:159], v[56:59]
	v_mfma_f32_16x16x32_f16 v[52:55], v[140:143], v[156:159], v[52:55]
	v_mfma_f32_16x16x32_f16 v[48:51], v[132:135], v[164:167], v[48:51]
	v_mfma_f32_16x16x32_f16 v[44:47], v[140:143], v[164:167], v[44:47]
	v_mfma_f32_16x16x32_f16 v[40:43], v[132:135], v[172:175], v[40:43]
	v_mfma_f32_16x16x32_f16 v[36:39], v[140:143], v[172:175], v[36:39]
	v_mfma_f32_16x16x32_f16 v[64:67], v[136:139], v[152:155], v[64:67]
	v_mfma_f32_16x16x32_f16 v[60:63], v[144:147], v[152:155], v[60:63]
	v_mfma_f32_16x16x32_f16 v[56:59], v[136:139], v[160:163], v[56:59]
	v_mfma_f32_16x16x32_f16 v[52:55], v[144:147], v[160:163], v[52:55]
	v_mfma_f32_16x16x32_f16 v[48:51], v[136:139], v[168:171], v[48:51]
	v_mfma_f32_16x16x32_f16 v[44:47], v[144:147], v[168:171], v[44:47]
	v_mfma_f32_16x16x32_f16 v[40:43], v[136:139], v[176:179], v[40:43]
	v_mfma_f32_16x16x32_f16 v[36:39], v[144:147], v[176:179], v[36:39]
	s_barrier
	s_add_u32 s10, s10, 0x10080
	s_addc_u32 s11, s11, 0
	s_mov_b32 m0, s30
	v_lshl_add_u64 v[6:7], s[10:11], 0, v[188:189]
	global_load_lds_dwordx4 v[6:7], off
	s_mov_b32 m0, s31
	v_lshl_add_u64 v[6:7], s[10:11], 0, v[192:193]
	global_load_lds_dwordx4 v[6:7], off
	s_waitcnt vmcnt(6)
	s_barrier
	v_mfma_f32_16x16x32_f16 v[32:35], v[180:183], v[148:151], v[32:35]
	v_mfma_f32_16x16x32_f16 v[28:31], v[206:209], v[148:151], v[28:31]
	v_mfma_f32_16x16x32_f16 v[24:27], v[180:183], v[156:159], v[24:27]
	v_mfma_f32_16x16x32_f16 v[20:23], v[206:209], v[156:159], v[20:23]
	v_mfma_f32_16x16x32_f16 v[16:19], v[180:183], v[164:167], v[16:19]
	v_mfma_f32_16x16x32_f16 v[12:15], v[206:209], v[164:167], v[12:15]
	v_mfma_f32_16x16x32_f16 v[6:9], v[180:183], v[172:175], v[8:11]
	v_mfma_f32_16x16x32_f16 v[2:5], v[206:209], v[172:175], v[2:5]
	v_mfma_f32_16x16x32_f16 v[32:35], v[202:205], v[152:155], v[32:35]
	v_mfma_f32_16x16x32_f16 v[28:31], v[210:213], v[152:155], v[28:31]
	v_mfma_f32_16x16x32_f16 v[24:27], v[202:205], v[160:163], v[24:27]
	v_mfma_f32_16x16x32_f16 v[20:23], v[210:213], v[160:163], v[20:23]
	v_mfma_f32_16x16x32_f16 v[16:19], v[202:205], v[168:171], v[16:19]
	v_mfma_f32_16x16x32_f16 v[12:15], v[210:213], v[168:171], v[12:15]
	v_mfma_f32_16x16x32_f16 v[8:11], v[202:205], v[176:179], v[6:9]
	v_mfma_f32_16x16x32_f16 v[4:7], v[210:213], v[176:179], v[2:5]
	s_add_u32 s8, s8, 0x100
	s_addc_u32 s9, s9, 0
	s_add_u32 s74, s74, 0x100
	s_addc_u32 s75, s75, 0
	s_cmp_ge_i32 s85, s46
	s_mov_b32 s10, s85
	s_barrier
	s_cbranch_scc0 .LBB0_2355

; #define G_STAGE(bufoff, gbase, v0, v1) do { \
;     __builtin_amdgcn_global_load_lds((const unsigned*)((const char*)(gbase) + (v0)), (LAS unsigned*)(lds + (bufoff) + ldsw), 16, 0, 0); \
;     __builtin_amdgcn_global_load_lds((const unsigned*)((const char*)(gbase) + (v1)), (LAS unsigned*)(lds + (bufoff) + ldsw + 8192), 16, 0, 0); } while (0)
; #define G_LDA(dst, b, h) do { _Pragma("unroll") for (int m = 0; m < 4; ++m) _Pragma("unroll") for (int k = 0; k < 2; ++k) dst[m][k] = *(const LAS h8*)(lds + G_SA(b, h) + aoff + m * 2048 + k * 1024); } while (0)
; #define G_LDB(dst, b, h) do { _Pragma("unroll") for (int n = 0; n < 2; ++n) _Pragma("unroll") for (int k = 0; k < 2; ++k) dst[n][k] = *(const LAS h8*)(lds + G_SB(b, h) + boff + n * 2048 + k * 1024); } while (0)
; #define G_MMA(ai, bj, At, Bt) do { __builtin_amdgcn_s_setprio(1); _Pragma("unroll") for (int m = 0; m < 4; ++m) _Pragma("unroll") for (int n = 0; n < 2; ++n) _Pragma("unroll") for (int k = 0; k < 2; ++k) \
;     acc[ai][bj][m][n] = __builtin_amdgcn_mfma_f32_16x16x32_f16(Bt[n][k], At[m][k], acc[ai][bj][m][n], 0, 0, 0); __builtin_amdgcn_s_setprio(0); } while (0)
; #define G_WAIT_V(n) asm volatile("s_waitcnt vmcnt(" #n ")" ::: "memory")
; #define G_WAIT_L(n) asm volatile("s_waitcnt lgkmcnt(" #n ")" ::: "memory")
; #define G_BAR __builtin_amdgcn_s_barrier()
; #define G_SCHED __builtin_amdgcn_sched_barrier(0)
; template <bool PERM, class Sched, class Epi>
; DI void gemm256(LAS unsigned char* lds, const Sched& S, const Epi& E, int wv_) {
;     ...
;       const bool last = (t == nt - 2);
;       const char* a1 = cA + (size_t)(t + 1) * kstep;
;       const char* a2 = last ? nA : cA + (size_t)(t + 2) * kstep;
;       const char* b2 = last ? nB : cB + (size_t)(t + 2) * kstep;
;       const char* a3 = a2 + kstep;
;       const char* b3 = b2 + kstep;
;       G_LDB(B0, 0, 0); G_SCHED; G_LDA(At, 0, 0); G_STAGE(G_SA(1, 1), a1 + chA, cvA0, cvA1);
;       G_WAIT_L(8); G_BAR; G_WAIT_L(0); G_MMA(0, 0, At, B0); G_BAR; G_SCHED;
;       G_LDB(B1, 0, 1); G_STAGE(G_SB(0, 0), b2, cvB0, cvB1);
;       G_BAR; G_WAIT_L(0); G_MMA(0, 1, At, B1); G_BAR;
;       G_LDA(At, 0, 1); G_STAGE(G_SA(0, 0), a2, cvA0, cvA1);
;       G_BAR; G_WAIT_L(0); G_MMA(1, 0, At, B0); G_BAR; G_SCHED;
;       G_STAGE(G_SB(0, 1), b2 + chB, cvB0, cvB1);
;       G_WAIT_V(6); G_BAR; G_MMA(1, 1, At, B1); G_BAR;
.LBB0_2433:
	s_waitcnt vmcnt(0)
	ds_read_b128 v[130:133], v216
	ds_read_b128 v[134:137], v216 offset:1024
	ds_read_b128 v[138:141], v216 offset:2048
	ds_read_b128 v[142:145], v216 offset:3072
	ds_read_b128 v[146:149], v1
	ds_read_b128 v[164:167], v1 offset:1024
	ds_read_b128 v[168:171], v1 offset:2048
	ds_read_b128 v[172:175], v1 offset:3072
	ds_read_b128 v[176:179], v1 offset:4096
	ds_read_b128 v[180:183], v1 offset:5120
	ds_read_b128 v[184:187], v1 offset:6144
	ds_read_b128 v[188:191], v1 offset:7168
	s_add_i32 s74, s20, 2
	s_add_u32 s21, s18, 0xfffc0080
	s_addc_u32 s22, s19, -1
	s_cmp_eq_u32 vcc_lo, s20
	s_cselect_b32 s20, s85, s75
	s_cselect_b32 s23, s9, s22
	s_cselect_b32 s22, s27, s21
	s_cselect_b32 s21, s56, s46
	s_add_i32 m0, s31, 0xc000
	v_lshl_add_u64 v[192:193], s[18:19], 0, v[158:159]
	global_load_lds_dwordx4 v[192:193], off
	s_add_i32 m0, s31, 0xe000
	v_lshl_add_u64 v[192:193], s[18:19], 0, v[160:161]
	global_load_lds_dwordx4 v[192:193], off
	s_waitcnt lgkmcnt(8)
	s_barrier
	s_waitcnt lgkmcnt(0)
	s_waitcnt lgkmcnt(0)
	v_mfma_f32_16x16x32_f16 v[126:129], v[130:133], v[146:149], v[126:129]
	v_mfma_f32_16x16x32_f16 v[122:125], v[138:141], v[146:149], v[122:125]
	v_mfma_f32_16x16x32_f16 v[110:113], v[130:133], v[168:171], v[110:113]
	v_mfma_f32_16x16x32_f16 v[106:109], v[138:141], v[168:171], v[106:109]
	v_mfma_f32_16x16x32_f16 v[94:97], v[130:133], v[176:179], v[94:97]
	v_mfma_f32_16x16x32_f16 v[90:93], v[138:141], v[176:179], v[90:93]
	v_mfma_f32_16x16x32_f16 v[78:81], v[130:133], v[184:187], v[78:81]
	v_mfma_f32_16x16x32_f16 v[74:77], v[138:141], v[184:187], v[74:77]
	v_mfma_f32_16x16x32_f16 v[126:129], v[134:137], v[164:167], v[126:129]
	v_mfma_f32_16x16x32_f16 v[122:125], v[142:145], v[164:167], v[122:125]
	v_mfma_f32_16x16x32_f16 v[110:113], v[134:137], v[172:175], v[110:113]
	v_mfma_f32_16x16x32_f16 v[106:109], v[142:145], v[172:175], v[106:109]
	v_mfma_f32_16x16x32_f16 v[94:97], v[134:137], v[180:183], v[94:97]
	v_mfma_f32_16x16x32_f16 v[90:93], v[142:145], v[180:183], v[90:93]
	v_mfma_f32_16x16x32_f16 v[78:81], v[134:137], v[188:191], v[78:81]
	v_mfma_f32_16x16x32_f16 v[74:77], v[142:145], v[188:191], v[74:77]
	s_barrier
	ds_read_b128 v[192:195], v217
	ds_read_b128 v[196:199], v217 offset:1024
	ds_read_b128 v[200:203], v217 offset:2048
	ds_read_b128 v[204:207], v217 offset:3072
	s_mov_b32 m0, s34
	v_lshl_add_u64 v[208:209], s[20:21], 0, v[150:151]
	global_load_lds_dwordx4 v[208:209], off
	s_mov_b32 m0, s35
	v_lshl_add_u64 v[210:211], s[20:21], 0, v[152:153]
	global_load_lds_dwordx4 v[210:211], off
	s_barrier
	s_waitcnt lgkmcnt(0)
	s_waitcnt lgkmcnt(0)
	v_mfma_f32_16x16x32_f16 v[118:121], v[192:195], v[146:149], v[118:121]
	v_mfma_f32_16x16x32_f16 v[114:117], v[200:203], v[146:149], v[114:117]
	v_mfma_f32_16x16x32_f16 v[102:105], v[192:195], v[168:171], v[102:105]
	v_mfma_f32_16x16x32_f16 v[98:101], v[200:203], v[168:171], v[98:101]
	v_mfma_f32_16x16x32_f16 v[86:89], v[192:195], v[176:179], v[86:89]
	v_mfma_f32_16x16x32_f16 v[82:85], v[200:203], v[176:179], v[82:85]
	v_mfma_f32_16x16x32_f16 v[70:73], v[192:195], v[184:187], v[70:73]
	v_mfma_f32_16x16x32_f16 v[66:69], v[200:203], v[184:187], v[66:69]
	v_mfma_f32_16x16x32_f16 v[118:121], v[196:199], v[164:167], v[118:121]
	v_mfma_f32_16x16x32_f16 v[114:117], v[204:207], v[164:167], v[114:117]
	v_mfma_f32_16x16x32_f16 v[102:105], v[196:199], v[172:175], v[102:105]
	v_mfma_f32_16x16x32_f16 v[98:101], v[204:207], v[172:175], v[98:101]
	v_mfma_f32_16x16x32_f16 v[86:89], v[196:199], v[180:183], v[86:89]
	v_mfma_f32_16x16x32_f16 v[82:85], v[204:207], v[180:183], v[82:85]
	v_mfma_f32_16x16x32_f16 v[70:73], v[196:199], v[188:191], v[70:73]
	v_mfma_f32_16x16x32_f16 v[66:69], v[204:207], v[188:191], v[66:69]
	s_mov_b32 m0, s31
	v_lshl_add_u64 v[212:213], s[22:23], 0, v[150:151]
	s_barrier
	ds_read_b128 v[146:149], v1 offset:16384
	ds_read_b128 v[164:167], v1 offset:17408
	ds_read_b128 v[168:171], v1 offset:18432
	ds_read_b128 v[172:175], v1 offset:19456
	ds_read_b128 v[176:179], v1 offset:20480
	ds_read_b128 v[180:183], v1 offset:21504
	ds_read_b128 v[184:187], v1 offset:22528
	ds_read_b128 v[188:191], v1 offset:23552
	global_load_lds_dwordx4 v[212:213], off
	s_mov_b32 m0, s36
	v_lshl_add_u64 v[214:215], s[22:23], 0, v[152:153]
	global_load_lds_dwordx4 v[214:215], off
	s_barrier
	s_waitcnt lgkmcnt(0)
	s_waitcnt lgkmcnt(0)
	v_mfma_f32_16x16x32_f16 v[62:65], v[130:133], v[146:149], v[62:65]
	v_mfma_f32_16x16x32_f16 v[58:61], v[138:141], v[146:149], v[58:61]
	v_mfma_f32_16x16x32_f16 v[46:49], v[130:133], v[168:171], v[46:49]
	v_mfma_f32_16x16x32_f16 v[42:45], v[138:141], v[168:171], v[42:45]
	v_mfma_f32_16x16x32_f16 v[30:33], v[130:133], v[176:179], v[30:33]
	v_mfma_f32_16x16x32_f16 v[26:29], v[138:141], v[176:179], v[26:29]
	v_mfma_f32_16x16x32_f16 v[14:17], v[130:133], v[184:187], v[14:17]
	v_mfma_f32_16x16x32_f16 v[10:13], v[138:141], v[184:187], v[10:13]
	v_mfma_f32_16x16x32_f16 v[62:65], v[134:137], v[164:167], v[62:65]
	v_mfma_f32_16x16x32_f16 v[58:61], v[142:145], v[164:167], v[58:61]
	v_mfma_f32_16x16x32_f16 v[46:49], v[134:137], v[172:175], v[46:49]
	v_mfma_f32_16x16x32_f16 v[42:45], v[142:145], v[172:175], v[42:45]
	v_mfma_f32_16x16x32_f16 v[30:33], v[134:137], v[180:183], v[30:33]
	v_mfma_f32_16x16x32_f16 v[26:29], v[142:145], v[180:183], v[26:29]
	v_mfma_f32_16x16x32_f16 v[14:17], v[134:137], v[188:191], v[14:17]
	v_mfma_f32_16x16x32_f16 v[10:13], v[142:145], v[188:191], v[10:13]
	s_barrier
	s_add_u32 s40, s20, 0x40000
	s_addc_u32 s41, s21, 0
	s_mov_b32 m0, s37
	v_lshl_add_u64 v[130:131], s[40:41], 0, v[150:151]
	global_load_lds_dwordx4 v[130:131], off
	s_mov_b32 m0, s58
	v_lshl_add_u64 v[130:131], s[40:41], 0, v[152:153]
	global_load_lds_dwordx4 v[130:131], off
	s_waitcnt vmcnt(6)
	s_barrier
; #define G_STAGE(bufoff, gbase, v0, v1) do { \
;     __builtin_amdgcn_global_load_lds((const unsigned*)((const char*)(gbase) + (v0)), (LAS unsigned*)(lds + (bufoff) + ldsw), 16, 0, 0); \
;     __builtin_amdgcn_global_load_lds((const unsigned*)((const char*)(gbase) + (v1)), (LAS unsigned*)(lds + (bufoff) + ldsw + 8192), 16, 0, 0); } while (0)
; #define G_LDA(dst, b, h) do { _Pragma("unroll") for (int m = 0; m < 4; ++m) _Pragma("unroll") for (int k = 0; k < 2; ++k) dst[m][k] = *(const LAS h8*)(lds + G_SA(b, h) + aoff + m * 2048 + k * 1024); } while (0)
; #define G_LDB(dst, b, h) do { _Pragma("unroll") for (int n = 0; n < 2; ++n) _Pragma("unroll") for (int k = 0; k < 2; ++k) dst[n][k] = *(const LAS h8*)(lds + G_SB(b, h) + boff + n * 2048 + k * 1024); } while (0)
; #define G_MMA(ai, bj, At, Bt) do { __builtin_amdgcn_s_setprio(1); _Pragma("unroll") for (int m = 0; m < 4; ++m) _Pragma("unroll") for (int n = 0; n < 2; ++n) _Pragma("unroll") for (int k = 0; k < 2; ++k) \
;     acc[ai][bj][m][n] = __builtin_amdgcn_mfma_f32_16x16x32_f16(Bt[n][k], At[m][k], acc[ai][bj][m][n], 0, 0, 0); __builtin_amdgcn_s_setprio(0); } while (0)
; #define G_WAIT_V(n) asm volatile("s_waitcnt vmcnt(" #n ")" ::: "memory")
; #define G_WAIT_L(n) asm volatile("s_waitcnt lgkmcnt(" #n ")" ::: "memory")
; #define G_BAR __builtin_amdgcn_s_barrier()
; #define G_SCHED __builtin_amdgcn_sched_barrier(0)
; template <bool PERM, class Sched, class Epi>
; DI void gemm256(LAS unsigned char* lds, const Sched& S, const Epi& E, int wv_) {
;     ...
;       G_WAIT_V(6); G_BAR; G_MMA(1, 1, At, B1); G_BAR;
;       G_LDB(B0, 1, 0); G_SCHED; G_LDA(At, 1, 0); G_STAGE(G_SA(0, 1), a2 + chA, cvA0, cvA1);
;       G_WAIT_L(8); G_BAR; G_WAIT_L(0); G_MMA(0, 0, At, B0); G_BAR; G_SCHED;
;       G_LDB(B1, 1, 1); G_STAGE(G_SB(1, 0), b3, cvB0, cvB1);
	v_mfma_f32_16x16x32_f16 v[54:57], v[192:195], v[146:149], v[54:57]
	v_mfma_f32_16x16x32_f16 v[50:53], v[200:203], v[146:149], v[50:53]
	v_mfma_f32_16x16x32_f16 v[38:41], v[192:195], v[168:171], v[38:41]
	v_mfma_f32_16x16x32_f16 v[34:37], v[200:203], v[168:171], v[34:37]
	v_mfma_f32_16x16x32_f16 v[22:25], v[192:195], v[176:179], v[22:25]
	v_mfma_f32_16x16x32_f16 v[18:21], v[200:203], v[176:179], v[18:21]
	v_mfma_f32_16x16x32_f16 v[6:9], v[192:195], v[184:187], v[6:9]
	v_mfma_f32_16x16x32_f16 v[2:5], v[200:203], v[184:187], v[2:5]
	v_mfma_f32_16x16x32_f16 v[54:57], v[196:199], v[164:167], v[54:57]
	v_mfma_f32_16x16x32_f16 v[50:53], v[204:207], v[164:167], v[50:53]
	v_mfma_f32_16x16x32_f16 v[38:41], v[196:199], v[172:175], v[38:41]
	v_mfma_f32_16x16x32_f16 v[34:37], v[204:207], v[172:175], v[34:37]
	v_mfma_f32_16x16x32_f16 v[22:25], v[196:199], v[180:183], v[22:25]
	v_mfma_f32_16x16x32_f16 v[18:21], v[204:207], v[180:183], v[18:21]
	v_mfma_f32_16x16x32_f16 v[6:9], v[196:199], v[188:191], v[6:9]
	v_mfma_f32_16x16x32_f16 v[2:5], v[204:207], v[188:191], v[2:5]
	s_barrier
	ds_read_b128 v[130:133], v218
	ds_read_b128 v[134:137], v218 offset:1024
	ds_read_b128 v[138:141], v218 offset:2048
	ds_read_b128 v[142:145], v218 offset:3072
	ds_read_b128 v[146:149], v1 offset:32768
	ds_read_b128 v[164:167], v1 offset:33792
	ds_read_b128 v[168:171], v1 offset:34816
	ds_read_b128 v[172:175], v1 offset:35840
	ds_read_b128 v[176:179], v1 offset:36864
	ds_read_b128 v[180:183], v1 offset:37888
	ds_read_b128 v[184:187], v1 offset:38912
	ds_read_b128 v[188:191], v1 offset:39936
	s_add_u32 s22, s22, 0x40000
	s_addc_u32 s23, s23, 0
	s_mov_b32 m0, s59
	v_lshl_add_u64 v[192:193], s[22:23], 0, v[150:151]
	global_load_lds_dwordx4 v[192:193], off
	s_mov_b32 m0, s61
	v_lshl_add_u64 v[192:193], s[22:23], 0, v[152:153]
	global_load_lds_dwordx4 v[192:193], off
	s_waitcnt lgkmcnt(8)
	s_barrier
	s_waitcnt lgkmcnt(0)
	s_waitcnt lgkmcnt(0)
	v_mfma_f32_16x16x32_f16 v[126:129], v[130:133], v[146:149], v[126:129]
	v_mfma_f32_16x16x32_f16 v[122:125], v[138:141], v[146:149], v[122:125]
	v_mfma_f32_16x16x32_f16 v[110:113], v[130:133], v[168:171], v[110:113]
	v_mfma_f32_16x16x32_f16 v[106:109], v[138:141], v[168:171], v[106:109]
	v_mfma_f32_16x16x32_f16 v[94:97], v[130:133], v[176:179], v[94:97]
	v_mfma_f32_16x16x32_f16 v[90:93], v[138:141], v[176:179], v[90:93]
	v_mfma_f32_16x16x32_f16 v[78:81], v[130:133], v[184:187], v[78:81]
	v_mfma_f32_16x16x32_f16 v[74:77], v[138:141], v[184:187], v[74:77]
	v_mfma_f32_16x16x32_f16 v[126:129], v[134:137], v[164:167], v[126:129]
	v_mfma_f32_16x16x32_f16 v[122:125], v[142:145], v[164:167], v[122:125]
	v_mfma_f32_16x16x32_f16 v[110:113], v[134:137], v[172:175], v[110:113]
	v_mfma_f32_16x16x32_f16 v[106:109], v[142:145], v[172:175], v[106:109]
	v_mfma_f32_16x16x32_f16 v[94:97], v[134:137], v[180:183], v[94:97]
	v_mfma_f32_16x16x32_f16 v[90:93], v[142:145], v[180:183], v[90:93]
	v_mfma_f32_16x16x32_f16 v[78:81], v[134:137], v[188:191], v[78:81]
	v_mfma_f32_16x16x32_f16 v[74:77], v[142:145], v[188:191], v[74:77]
	s_barrier
	ds_read_b128 v[192:195], v219
	ds_read_b128 v[196:199], v219 offset:1024
	ds_read_b128 v[200:203], v219 offset:2048
	ds_read_b128 v[204:207], v219 offset:3072
	s_mov_b32 m0, s69
	v_lshl_add_u64 v[208:209], v[208:209], 0, s[86:87]
	global_load_lds_dwordx4 v[208:209], off
	s_mov_b32 m0, s78
	v_lshl_add_u64 v[208:209], v[210:211], 0, s[86:87]
	global_load_lds_dwordx4 v[208:209], off
	s_barrier
; #define G_STAGE(bufoff, gbase, v0, v1) do { \
;     __builtin_amdgcn_global_load_lds((const unsigned*)((const char*)(gbase) + (v0)), (LAS unsigned*)(lds + (bufoff) + ldsw), 16, 0, 0); \
;     __builtin_amdgcn_global_load_lds((const unsigned*)((const char*)(gbase) + (v1)), (LAS unsigned*)(lds + (bufoff) + ldsw + 8192), 16, 0, 0); } while (0)
; #define G_LDA(dst, b, h) do { _Pragma("unroll") for (int m = 0; m < 4; ++m) _Pragma("unroll") for (int k = 0; k < 2; ++k) dst[m][k] = *(const LAS h8*)(lds + G_SA(b, h) + aoff + m * 2048 + k * 1024); } while (0)
; #define G_MMA(ai, bj, At, Bt) do { __builtin_amdgcn_s_setprio(1); _Pragma("unroll") for (int m = 0; m < 4; ++m) _Pragma("unroll") for (int n = 0; n < 2; ++n) _Pragma("unroll") for (int k = 0; k < 2; ++k) \
;     acc[ai][bj][m][n] = __builtin_amdgcn_mfma_f32_16x16x32_f16(Bt[n][k], At[m][k], acc[ai][bj][m][n], 0, 0, 0); __builtin_amdgcn_s_setprio(0); } while (0)
; #define G_WAIT_V(n) asm volatile("s_waitcnt vmcnt(" #n ")" ::: "memory")
; #define G_WAIT_L(n) asm volatile("s_waitcnt lgkmcnt(" #n ")" ::: "memory")
; #define G_BAR __builtin_amdgcn_s_barrier()
; #define G_SCHED __builtin_amdgcn_sched_barrier(0)
; template <bool PERM, class Sched, class Epi>
; DI void gemm256(LAS unsigned char* lds, const Sched& S, const Epi& E, int wv_) {
;     ...
;       G_BAR; G_WAIT_L(0); G_MMA(0, 1, At, B1); G_BAR;
;       G_LDA(At, 1, 1); G_STAGE(G_SA(1, 0), a3, cvA0, cvA1);
;       G_BAR; G_WAIT_L(0); G_MMA(1, 0, At, B0); G_BAR; G_SCHED;
;       G_STAGE(G_SB(1, 1), b3 + chB, cvB0, cvB1);
;       G_WAIT_V(6); G_BAR; G_MMA(1, 1, At, B1); G_BAR;
;     }
;     bool keep = false;
;     if constexpr (Sched::CHAIN) keep = E(acc, cur, wr, wc, fr, fq); else E(acc, cur, wr, wc, fr, fq);
;     if (!has_next) break;
	s_waitcnt lgkmcnt(0)
	s_waitcnt lgkmcnt(0)
	v_mfma_f32_16x16x32_f16 v[118:121], v[192:195], v[146:149], v[118:121]
	v_mfma_f32_16x16x32_f16 v[114:117], v[200:203], v[146:149], v[114:117]
	v_mfma_f32_16x16x32_f16 v[102:105], v[192:195], v[168:171], v[102:105]
	v_mfma_f32_16x16x32_f16 v[98:101], v[200:203], v[168:171], v[98:101]
	v_mfma_f32_16x16x32_f16 v[86:89], v[192:195], v[176:179], v[86:89]
	v_mfma_f32_16x16x32_f16 v[82:85], v[200:203], v[176:179], v[82:85]
	v_mfma_f32_16x16x32_f16 v[70:73], v[192:195], v[184:187], v[70:73]
	v_mfma_f32_16x16x32_f16 v[66:69], v[200:203], v[184:187], v[66:69]
	v_mfma_f32_16x16x32_f16 v[118:121], v[196:199], v[164:167], v[118:121]
	v_mfma_f32_16x16x32_f16 v[114:117], v[204:207], v[164:167], v[114:117]
	v_mfma_f32_16x16x32_f16 v[102:105], v[196:199], v[172:175], v[102:105]
	v_mfma_f32_16x16x32_f16 v[98:101], v[204:207], v[172:175], v[98:101]
	v_mfma_f32_16x16x32_f16 v[86:89], v[196:199], v[180:183], v[86:89]
	v_mfma_f32_16x16x32_f16 v[82:85], v[204:207], v[180:183], v[82:85]
	v_mfma_f32_16x16x32_f16 v[70:73], v[196:199], v[188:191], v[70:73]
	v_mfma_f32_16x16x32_f16 v[66:69], v[204:207], v[188:191], v[66:69]
	s_mov_b32 m0, s79
	v_lshl_add_u64 v[208:209], v[212:213], 0, s[86:87]
	s_barrier
	ds_read_b128 v[146:149], v1 offset:49152
	ds_read_b128 v[164:167], v1 offset:50176
	ds_read_b128 v[168:171], v1 offset:51200
	ds_read_b128 v[172:175], v1 offset:52224
	ds_read_b128 v[176:179], v1 offset:53248
	ds_read_b128 v[180:183], v1 offset:54272
	ds_read_b128 v[184:187], v1 offset:55296
	ds_read_b128 v[188:191], v1 offset:56320
	global_load_lds_dwordx4 v[208:209], off
	s_mov_b32 m0, s83
	v_lshl_add_u64 v[208:209], v[214:215], 0, s[86:87]
	global_load_lds_dwordx4 v[208:209], off
	s_barrier
	s_waitcnt lgkmcnt(0)
	s_waitcnt lgkmcnt(0)
	v_mfma_f32_16x16x32_f16 v[62:65], v[130:133], v[146:149], v[62:65]
	v_mfma_f32_16x16x32_f16 v[58:61], v[138:141], v[146:149], v[58:61]
	v_mfma_f32_16x16x32_f16 v[46:49], v[130:133], v[168:171], v[46:49]
	v_mfma_f32_16x16x32_f16 v[42:45], v[138:141], v[168:171], v[42:45]
	v_mfma_f32_16x16x32_f16 v[30:33], v[130:133], v[176:179], v[30:33]
	v_mfma_f32_16x16x32_f16 v[26:29], v[138:141], v[176:179], v[26:29]
	v_mfma_f32_16x16x32_f16 v[14:17], v[130:133], v[184:187], v[14:17]
	v_mfma_f32_16x16x32_f16 v[10:13], v[138:141], v[184:187], v[10:13]
	v_mfma_f32_16x16x32_f16 v[62:65], v[134:137], v[164:167], v[62:65]
	v_mfma_f32_16x16x32_f16 v[58:61], v[142:145], v[164:167], v[58:61]
	v_mfma_f32_16x16x32_f16 v[46:49], v[134:137], v[172:175], v[46:49]
	v_mfma_f32_16x16x32_f16 v[42:45], v[142:145], v[172:175], v[42:45]
	v_mfma_f32_16x16x32_f16 v[30:33], v[134:137], v[180:183], v[30:33]
	v_mfma_f32_16x16x32_f16 v[26:29], v[142:145], v[180:183], v[26:29]
	v_mfma_f32_16x16x32_f16 v[14:17], v[134:137], v[188:191], v[14:17]
	v_mfma_f32_16x16x32_f16 v[10:13], v[142:145], v[188:191], v[10:13]
	s_barrier
	s_add_u32 s20, s20, 0x40080
	s_addc_u32 s21, s21, 0
	s_mov_b32 m0, s90
	v_lshl_add_u64 v[130:131], s[20:21], 0, v[150:151]
	global_load_lds_dwordx4 v[130:131], off
	s_mov_b32 m0, s93
	v_lshl_add_u64 v[130:131], s[20:21], 0, v[152:153]
	global_load_lds_dwordx4 v[130:131], off
	s_waitcnt vmcnt(6)
	s_barrier
	v_mfma_f32_16x16x32_f16 v[54:57], v[192:195], v[146:149], v[54:57]
	v_mfma_f32_16x16x32_f16 v[50:53], v[200:203], v[146:149], v[50:53]
	v_mfma_f32_16x16x32_f16 v[38:41], v[192:195], v[168:171], v[38:41]
	v_mfma_f32_16x16x32_f16 v[34:37], v[200:203], v[168:171], v[34:37]
	v_mfma_f32_16x16x32_f16 v[22:25], v[192:195], v[176:179], v[22:25]
	v_mfma_f32_16x16x32_f16 v[18:21], v[200:203], v[176:179], v[18:21]
	v_mfma_f32_16x16x32_f16 v[6:9], v[192:195], v[184:187], v[6:9]
	v_mfma_f32_16x16x32_f16 v[2:5], v[200:203], v[184:187], v[2:5]
	v_mfma_f32_16x16x32_f16 v[54:57], v[196:199], v[164:167], v[54:57]
	v_mfma_f32_16x16x32_f16 v[50:53], v[204:207], v[164:167], v[50:53]
	v_mfma_f32_16x16x32_f16 v[38:41], v[196:199], v[172:175], v[38:41]
	v_mfma_f32_16x16x32_f16 v[34:37], v[204:207], v[172:175], v[34:37]
	v_mfma_f32_16x16x32_f16 v[22:25], v[196:199], v[180:183], v[22:25]
	v_mfma_f32_16x16x32_f16 v[18:21], v[204:207], v[180:183], v[18:21]
	v_mfma_f32_16x16x32_f16 v[6:9], v[196:199], v[188:191], v[6:9]
	v_mfma_f32_16x16x32_f16 v[2:5], v[204:207], v[188:191], v[2:5]
	s_add_u32 s18, s18, 0x100
	s_addc_u32 s19, s19, 0
	s_add_u32 s75, s75, 0x100
	s_addc_u32 s46, s46, 0
	s_cmp_ge_i32 s74, s25
	s_mov_b32 s20, s74
	s_barrier
	s_cbranch_scc0 .LBB0_2433
	s_mov_b32 s56, 0x8fff
	s_branch .LBB0_2436

; #define G_STAGE(bufoff, gbase, v0, v1) do { \
;     __builtin_amdgcn_global_load_lds((const unsigned*)((const char*)(gbase) + (v0)), (LAS unsigned*)(lds + (bufoff) + ldsw), 16, 0, 0); \
;     __builtin_amdgcn_global_load_lds((const unsigned*)((const char*)(gbase) + (v1)), (LAS unsigned*)(lds + (bufoff) + ldsw + 8192), 16, 0, 0); } while (0)
; #define G_LDA(dst, b, h) do { _Pragma("unroll") for (int m = 0; m < 4; ++m) _Pragma("unroll") for (int k = 0; k < 2; ++k) dst[m][k] = *(const LAS h8*)(lds + G_SA(b, h) + aoff + m * 2048 + k * 1024); } while (0)
; #define G_LDB(dst, b, h) do { _Pragma("unroll") for (int n = 0; n < 2; ++n) _Pragma("unroll") for (int k = 0; k < 2; ++k) dst[n][k] = *(const LAS h8*)(lds + G_SB(b, h) + boff + n * 2048 + k * 1024); } while (0)
; #define G_MMA(ai, bj, At, Bt) do { __builtin_amdgcn_s_setprio(1); _Pragma("unroll") for (int m = 0; m < 4; ++m) _Pragma("unroll") for (int n = 0; n < 2; ++n) _Pragma("unroll") for (int k = 0; k < 2; ++k) \
;     acc[ai][bj][m][n] = __builtin_amdgcn_mfma_f32_16x16x32_f16(Bt[n][k], At[m][k], acc[ai][bj][m][n], 0, 0, 0); __builtin_amdgcn_s_setprio(0); } while (0)
; #define G_WAIT_V(n) asm volatile("s_waitcnt vmcnt(" #n ")" ::: "memory")
; #define G_WAIT_L(n) asm volatile("s_waitcnt lgkmcnt(" #n ")" ::: "memory")
; #define G_BAR __builtin_amdgcn_s_barrier()
; #define G_SCHED __builtin_amdgcn_sched_barrier(0)
; template <bool PERM, class Sched, class Epi>
; DI void gemm256(LAS unsigned char* lds, const Sched& S, const Epi& E, int wv_) {
;     ...
;       const bool last = (t == nt - 2);
;       const char* a1 = cA + (size_t)(t + 1) * kstep;
;       const char* a2 = last ? nA : cA + (size_t)(t + 2) * kstep;
;       const char* b2 = last ? nB : cB + (size_t)(t + 2) * kstep;
;       const char* a3 = a2 + kstep;
;       const char* b3 = b2 + kstep;
;       G_LDB(B0, 0, 0); G_SCHED; G_LDA(At, 0, 0); G_STAGE(G_SA(1, 1), a1 + chA, cvA0, cvA1);
;       G_WAIT_L(8); G_BAR; G_WAIT_L(0); G_MMA(0, 0, At, B0); G_BAR; G_SCHED;
;       G_LDB(B1, 0, 1); G_STAGE(G_SB(0, 0), b2, cvB0, cvB1);
;       G_BAR; G_WAIT_L(0); G_MMA(0, 1, At, B1); G_BAR;
;       G_LDA(At, 0, 1); G_STAGE(G_SA(0, 0), a2, cvA0, cvA1);
;       G_BAR; G_WAIT_L(0); G_MMA(1, 0, At, B0); G_BAR; G_SCHED;
;       G_STAGE(G_SB(0, 1), b2 + chB, cvB0, cvB1);
;       G_WAIT_V(6); G_BAR; G_MMA(1, 1, At, B1); G_BAR;
.LBB0_2581:
	ds_read_b128 v[144:147], v216
	ds_read_b128 v[148:151], v216 offset:1024
	ds_read_b128 v[152:155], v216 offset:2048
	ds_read_b128 v[156:159], v216 offset:3072
	ds_read_b128 v[160:163], v1
	ds_read_b128 v[164:167], v1 offset:1024
	ds_read_b128 v[168:171], v1 offset:2048
	ds_read_b128 v[172:175], v1 offset:3072
	ds_read_b128 v[176:179], v1 offset:4096
	ds_read_b128 v[180:183], v1 offset:5120
	ds_read_b128 v[184:187], v1 offset:6144
	ds_read_b128 v[188:191], v1 offset:7168
	s_add_i32 s68, s14, 2
	s_add_u32 s15, s12, 0xfffc0080
	s_addc_u32 s16, s13, -1
	s_cmp_eq_u32 s11, s14
	s_cselect_b32 s14, s8, s66
	s_cselect_b32 s17, s7, s16
	s_cselect_b32 s16, s6, s15
	s_cselect_b32 s15, s9, s46
	s_add_i32 m0, s24, 0xc000
	v_lshl_add_u64 v[192:193], s[12:13], 0, v[138:139]
	global_load_lds_dwordx4 v[192:193], off
	s_add_i32 m0, s24, 0xe000
	v_lshl_add_u64 v[192:193], s[12:13], 0, v[140:141]
	global_load_lds_dwordx4 v[192:193], off
	s_waitcnt lgkmcnt(8)
	s_barrier
	s_waitcnt lgkmcnt(0)
	s_waitcnt lgkmcnt(0)
	v_mfma_f32_16x16x32_f16 v[126:129], v[144:147], v[160:163], v[126:129]
	v_mfma_f32_16x16x32_f16 v[122:125], v[152:155], v[160:163], v[122:125]
	v_mfma_f32_16x16x32_f16 v[110:113], v[144:147], v[168:171], v[110:113]
	v_mfma_f32_16x16x32_f16 v[106:109], v[152:155], v[168:171], v[106:109]
	v_mfma_f32_16x16x32_f16 v[94:97], v[144:147], v[176:179], v[94:97]
	v_mfma_f32_16x16x32_f16 v[90:93], v[152:155], v[176:179], v[90:93]
	v_mfma_f32_16x16x32_f16 v[78:81], v[144:147], v[184:187], v[78:81]
	v_mfma_f32_16x16x32_f16 v[74:77], v[152:155], v[184:187], v[74:77]
	v_mfma_f32_16x16x32_f16 v[126:129], v[148:151], v[164:167], v[126:129]
	v_mfma_f32_16x16x32_f16 v[122:125], v[156:159], v[164:167], v[122:125]
	v_mfma_f32_16x16x32_f16 v[110:113], v[148:151], v[172:175], v[110:113]
	v_mfma_f32_16x16x32_f16 v[106:109], v[156:159], v[172:175], v[106:109]
	v_mfma_f32_16x16x32_f16 v[94:97], v[148:151], v[180:183], v[94:97]
	v_mfma_f32_16x16x32_f16 v[90:93], v[156:159], v[180:183], v[90:93]
	v_mfma_f32_16x16x32_f16 v[78:81], v[148:151], v[188:191], v[78:81]
	v_mfma_f32_16x16x32_f16 v[74:77], v[156:159], v[188:191], v[74:77]
	s_barrier
	ds_read_b128 v[192:195], v217
	ds_read_b128 v[196:199], v217 offset:1024
	ds_read_b128 v[200:203], v217 offset:2048
	ds_read_b128 v[204:207], v217 offset:3072
	s_mov_b32 m0, s25
	v_lshl_add_u64 v[208:209], s[14:15], 0, v[132:133]
	global_load_lds_dwordx4 v[208:209], off
	s_mov_b32 m0, s26
	v_lshl_add_u64 v[210:211], s[14:15], 0, v[136:137]
	global_load_lds_dwordx4 v[210:211], off
	s_barrier
	s_waitcnt lgkmcnt(0)
	s_waitcnt lgkmcnt(0)
	v_mfma_f32_16x16x32_f16 v[118:121], v[192:195], v[160:163], v[118:121]
	v_mfma_f32_16x16x32_f16 v[114:117], v[200:203], v[160:163], v[114:117]
	v_mfma_f32_16x16x32_f16 v[102:105], v[192:195], v[168:171], v[102:105]
	v_mfma_f32_16x16x32_f16 v[98:101], v[200:203], v[168:171], v[98:101]
	v_mfma_f32_16x16x32_f16 v[86:89], v[192:195], v[176:179], v[86:89]
	v_mfma_f32_16x16x32_f16 v[82:85], v[200:203], v[176:179], v[82:85]
	v_mfma_f32_16x16x32_f16 v[70:73], v[192:195], v[184:187], v[70:73]
	v_mfma_f32_16x16x32_f16 v[66:69], v[200:203], v[184:187], v[66:69]
	v_mfma_f32_16x16x32_f16 v[118:121], v[196:199], v[164:167], v[118:121]
	v_mfma_f32_16x16x32_f16 v[114:117], v[204:207], v[164:167], v[114:117]
	v_mfma_f32_16x16x32_f16 v[102:105], v[196:199], v[172:175], v[102:105]
	v_mfma_f32_16x16x32_f16 v[98:101], v[204:207], v[172:175], v[98:101]
	v_mfma_f32_16x16x32_f16 v[86:89], v[196:199], v[180:183], v[86:89]
	v_mfma_f32_16x16x32_f16 v[82:85], v[204:207], v[180:183], v[82:85]
	v_mfma_f32_16x16x32_f16 v[70:73], v[196:199], v[188:191], v[70:73]
	v_mfma_f32_16x16x32_f16 v[66:69], v[204:207], v[188:191], v[66:69]
	s_mov_b32 m0, s24
	v_lshl_add_u64 v[212:213], s[16:17], 0, v[130:131]
	s_barrier
	ds_read_b128 v[160:163], v1 offset:16384
	ds_read_b128 v[164:167], v1 offset:17408
	ds_read_b128 v[168:171], v1 offset:18432
	ds_read_b128 v[172:175], v1 offset:19456
	ds_read_b128 v[176:179], v1 offset:20480
	ds_read_b128 v[180:183], v1 offset:21504
	ds_read_b128 v[184:187], v1 offset:22528
	ds_read_b128 v[188:191], v1 offset:23552
	global_load_lds_dwordx4 v[212:213], off
	s_mov_b32 m0, s27
	v_lshl_add_u64 v[214:215], s[16:17], 0, v[134:135]
	global_load_lds_dwordx4 v[214:215], off
	s_barrier
	s_waitcnt lgkmcnt(0)
	s_waitcnt lgkmcnt(0)
	v_mfma_f32_16x16x32_f16 v[62:65], v[144:147], v[160:163], v[62:65]
	v_mfma_f32_16x16x32_f16 v[58:61], v[152:155], v[160:163], v[58:61]
	v_mfma_f32_16x16x32_f16 v[46:49], v[144:147], v[168:171], v[46:49]
	v_mfma_f32_16x16x32_f16 v[42:45], v[152:155], v[168:171], v[42:45]
	v_mfma_f32_16x16x32_f16 v[30:33], v[144:147], v[176:179], v[30:33]
	v_mfma_f32_16x16x32_f16 v[26:29], v[152:155], v[176:179], v[26:29]
	v_mfma_f32_16x16x32_f16 v[14:17], v[144:147], v[184:187], v[14:17]
	v_mfma_f32_16x16x32_f16 v[10:13], v[152:155], v[184:187], v[10:13]
	v_mfma_f32_16x16x32_f16 v[62:65], v[148:151], v[164:167], v[62:65]
	v_mfma_f32_16x16x32_f16 v[58:61], v[156:159], v[164:167], v[58:61]
	v_mfma_f32_16x16x32_f16 v[46:49], v[148:151], v[172:175], v[46:49]
	v_mfma_f32_16x16x32_f16 v[42:45], v[156:159], v[172:175], v[42:45]
	v_mfma_f32_16x16x32_f16 v[30:33], v[148:151], v[180:183], v[30:33]
	v_mfma_f32_16x16x32_f16 v[26:29], v[156:159], v[180:183], v[26:29]
	v_mfma_f32_16x16x32_f16 v[14:17], v[148:151], v[188:191], v[14:17]
	v_mfma_f32_16x16x32_f16 v[10:13], v[156:159], v[188:191], v[10:13]
	s_barrier
	s_add_u32 s40, s14, 0x40000
	s_addc_u32 s41, s15, 0
	s_mov_b32 m0, s28
	v_lshl_add_u64 v[144:145], s[40:41], 0, v[132:133]
	global_load_lds_dwordx4 v[144:145], off
	s_mov_b32 m0, s29
	v_lshl_add_u64 v[144:145], s[40:41], 0, v[136:137]
	global_load_lds_dwordx4 v[144:145], off
	s_waitcnt vmcnt(6)
	s_barrier
; #define G_STAGE(bufoff, gbase, v0, v1) do { \
;     __builtin_amdgcn_global_load_lds((const unsigned*)((const char*)(gbase) + (v0)), (LAS unsigned*)(lds + (bufoff) + ldsw), 16, 0, 0); \
;     __builtin_amdgcn_global_load_lds((const unsigned*)((const char*)(gbase) + (v1)), (LAS unsigned*)(lds + (bufoff) + ldsw + 8192), 16, 0, 0); } while (0)
; #define G_LDA(dst, b, h) do { _Pragma("unroll") for (int m = 0; m < 4; ++m) _Pragma("unroll") for (int k = 0; k < 2; ++k) dst[m][k] = *(const LAS h8*)(lds + G_SA(b, h) + aoff + m * 2048 + k * 1024); } while (0)
; #define G_LDB(dst, b, h) do { _Pragma("unroll") for (int n = 0; n < 2; ++n) _Pragma("unroll") for (int k = 0; k < 2; ++k) dst[n][k] = *(const LAS h8*)(lds + G_SB(b, h) + boff + n * 2048 + k * 1024); } while (0)
; #define G_MMA(ai, bj, At, Bt) do { __builtin_amdgcn_s_setprio(1); _Pragma("unroll") for (int m = 0; m < 4; ++m) _Pragma("unroll") for (int n = 0; n < 2; ++n) _Pragma("unroll") for (int k = 0; k < 2; ++k) \
;     acc[ai][bj][m][n] = __builtin_amdgcn_mfma_f32_16x16x32_f16(Bt[n][k], At[m][k], acc[ai][bj][m][n], 0, 0, 0); __builtin_amdgcn_s_setprio(0); } while (0)
; #define G_WAIT_V(n) asm volatile("s_waitcnt vmcnt(" #n ")" ::: "memory")
; #define G_WAIT_L(n) asm volatile("s_waitcnt lgkmcnt(" #n ")" ::: "memory")
; #define G_BAR __builtin_amdgcn_s_barrier()
; #define G_SCHED __builtin_amdgcn_sched_barrier(0)
; template <bool PERM, class Sched, class Epi>
; DI void gemm256(LAS unsigned char* lds, const Sched& S, const Epi& E, int wv_) {
;     ...
;       G_WAIT_V(6); G_BAR; G_MMA(1, 1, At, B1); G_BAR;
;       G_LDB(B0, 1, 0); G_SCHED; G_LDA(At, 1, 0); G_STAGE(G_SA(0, 1), a2 + chA, cvA0, cvA1);
;       G_WAIT_L(8); G_BAR; G_WAIT_L(0); G_MMA(0, 0, At, B0); G_BAR; G_SCHED;
;       G_LDB(B1, 1, 1); G_STAGE(G_SB(1, 0), b3, cvB0, cvB1);
	v_mfma_f32_16x16x32_f16 v[54:57], v[192:195], v[160:163], v[54:57]
	v_mfma_f32_16x16x32_f16 v[50:53], v[200:203], v[160:163], v[50:53]
	v_mfma_f32_16x16x32_f16 v[38:41], v[192:195], v[168:171], v[38:41]
	v_mfma_f32_16x16x32_f16 v[34:37], v[200:203], v[168:171], v[34:37]
	v_mfma_f32_16x16x32_f16 v[22:25], v[192:195], v[176:179], v[22:25]
	v_mfma_f32_16x16x32_f16 v[18:21], v[200:203], v[176:179], v[18:21]
	v_mfma_f32_16x16x32_f16 v[6:9], v[192:195], v[184:187], v[6:9]
	v_mfma_f32_16x16x32_f16 v[2:5], v[200:203], v[184:187], v[2:5]
	v_mfma_f32_16x16x32_f16 v[54:57], v[196:199], v[164:167], v[54:57]
	v_mfma_f32_16x16x32_f16 v[50:53], v[204:207], v[164:167], v[50:53]
	v_mfma_f32_16x16x32_f16 v[38:41], v[196:199], v[172:175], v[38:41]
	v_mfma_f32_16x16x32_f16 v[34:37], v[204:207], v[172:175], v[34:37]
	v_mfma_f32_16x16x32_f16 v[22:25], v[196:199], v[180:183], v[22:25]
	v_mfma_f32_16x16x32_f16 v[18:21], v[204:207], v[180:183], v[18:21]
	v_mfma_f32_16x16x32_f16 v[6:9], v[196:199], v[188:191], v[6:9]
	v_mfma_f32_16x16x32_f16 v[2:5], v[204:207], v[188:191], v[2:5]
	s_barrier
	ds_read_b128 v[144:147], v218
	ds_read_b128 v[148:151], v218 offset:1024
	ds_read_b128 v[152:155], v218 offset:2048
	ds_read_b128 v[156:159], v218 offset:3072
	ds_read_b128 v[160:163], v1 offset:32768
	ds_read_b128 v[164:167], v1 offset:33792
	ds_read_b128 v[168:171], v1 offset:34816
	ds_read_b128 v[172:175], v1 offset:35840
	ds_read_b128 v[176:179], v1 offset:36864
	ds_read_b128 v[180:183], v1 offset:37888
	ds_read_b128 v[184:187], v1 offset:38912
	ds_read_b128 v[188:191], v1 offset:39936
	s_add_u32 s16, s16, 0x40000
	s_addc_u32 s17, s17, 0
	s_mov_b32 m0, s30
	v_lshl_add_u64 v[192:193], s[16:17], 0, v[130:131]
	global_load_lds_dwordx4 v[192:193], off
	s_mov_b32 m0, s31
	v_lshl_add_u64 v[192:193], s[16:17], 0, v[134:135]
	global_load_lds_dwordx4 v[192:193], off
	s_waitcnt lgkmcnt(8)
	s_barrier
	s_waitcnt lgkmcnt(0)
	s_waitcnt lgkmcnt(0)
	v_mfma_f32_16x16x32_f16 v[126:129], v[144:147], v[160:163], v[126:129]
	v_mfma_f32_16x16x32_f16 v[122:125], v[152:155], v[160:163], v[122:125]
	v_mfma_f32_16x16x32_f16 v[110:113], v[144:147], v[168:171], v[110:113]
	v_mfma_f32_16x16x32_f16 v[106:109], v[152:155], v[168:171], v[106:109]
	v_mfma_f32_16x16x32_f16 v[94:97], v[144:147], v[176:179], v[94:97]
	v_mfma_f32_16x16x32_f16 v[90:93], v[152:155], v[176:179], v[90:93]
	v_mfma_f32_16x16x32_f16 v[78:81], v[144:147], v[184:187], v[78:81]
	v_mfma_f32_16x16x32_f16 v[74:77], v[152:155], v[184:187], v[74:77]
	v_mfma_f32_16x16x32_f16 v[126:129], v[148:151], v[164:167], v[126:129]
	v_mfma_f32_16x16x32_f16 v[122:125], v[156:159], v[164:167], v[122:125]
	v_mfma_f32_16x16x32_f16 v[110:113], v[148:151], v[172:175], v[110:113]
	v_mfma_f32_16x16x32_f16 v[106:109], v[156:159], v[172:175], v[106:109]
	v_mfma_f32_16x16x32_f16 v[94:97], v[148:151], v[180:183], v[94:97]
	v_mfma_f32_16x16x32_f16 v[90:93], v[156:159], v[180:183], v[90:93]
	v_mfma_f32_16x16x32_f16 v[78:81], v[148:151], v[188:191], v[78:81]
	v_mfma_f32_16x16x32_f16 v[74:77], v[156:159], v[188:191], v[74:77]
	s_barrier
	ds_read_b128 v[192:195], v219
	ds_read_b128 v[196:199], v219 offset:1024
	ds_read_b128 v[200:203], v219 offset:2048
	ds_read_b128 v[204:207], v219 offset:3072
	s_mov_b32 m0, s35
	v_lshl_add_u64 v[208:209], v[208:209], 0, s[86:87]
	global_load_lds_dwordx4 v[208:209], off
	s_mov_b32 m0, s36
	v_lshl_add_u64 v[208:209], v[210:211], 0, s[86:87]
	global_load_lds_dwordx4 v[208:209], off
	s_barrier
; #define G_STAGE(bufoff, gbase, v0, v1) do { \
;     __builtin_amdgcn_global_load_lds((const unsigned*)((const char*)(gbase) + (v0)), (LAS unsigned*)(lds + (bufoff) + ldsw), 16, 0, 0); \
;     __builtin_amdgcn_global_load_lds((const unsigned*)((const char*)(gbase) + (v1)), (LAS unsigned*)(lds + (bufoff) + ldsw + 8192), 16, 0, 0); } while (0)
; #define G_LDA(dst, b, h) do { _Pragma("unroll") for (int m = 0; m < 4; ++m) _Pragma("unroll") for (int k = 0; k < 2; ++k) dst[m][k] = *(const LAS h8*)(lds + G_SA(b, h) + aoff + m * 2048 + k * 1024); } while (0)
; #define G_MMA(ai, bj, At, Bt) do { __builtin_amdgcn_s_setprio(1); _Pragma("unroll") for (int m = 0; m < 4; ++m) _Pragma("unroll") for (int n = 0; n < 2; ++n) _Pragma("unroll") for (int k = 0; k < 2; ++k) \
;     acc[ai][bj][m][n] = __builtin_amdgcn_mfma_f32_16x16x32_f16(Bt[n][k], At[m][k], acc[ai][bj][m][n], 0, 0, 0); __builtin_amdgcn_s_setprio(0); } while (0)
; #define G_WAIT_V(n) asm volatile("s_waitcnt vmcnt(" #n ")" ::: "memory")
; #define G_WAIT_L(n) asm volatile("s_waitcnt lgkmcnt(" #n ")" ::: "memory")
; #define G_BAR __builtin_amdgcn_s_barrier()
; #define G_SCHED __builtin_amdgcn_sched_barrier(0)
; template <bool PERM, class Sched, class Epi>
; DI void gemm256(LAS unsigned char* lds, const Sched& S, const Epi& E, int wv_) {
;     ...
;       G_BAR; G_WAIT_L(0); G_MMA(0, 1, At, B1); G_BAR;
;       G_LDA(At, 1, 1); G_STAGE(G_SA(1, 0), a3, cvA0, cvA1);
;       G_BAR; G_WAIT_L(0); G_MMA(1, 0, At, B0); G_BAR; G_SCHED;
;       G_STAGE(G_SB(1, 1), b3 + chB, cvB0, cvB1);
;       G_WAIT_V(6); G_BAR; G_MMA(1, 1, At, B1); G_BAR;
;     }
;     bool keep = false;
;     if constexpr (Sched::CHAIN) keep = E(acc, cur, wr, wc, fr, fq); else E(acc, cur, wr, wc, fr, fq);
;     if (!has_next) break;
	s_waitcnt lgkmcnt(0)
	s_waitcnt lgkmcnt(0)
	v_mfma_f32_16x16x32_f16 v[118:121], v[192:195], v[160:163], v[118:121]
	v_mfma_f32_16x16x32_f16 v[114:117], v[200:203], v[160:163], v[114:117]
	v_mfma_f32_16x16x32_f16 v[102:105], v[192:195], v[168:171], v[102:105]
	v_mfma_f32_16x16x32_f16 v[98:101], v[200:203], v[168:171], v[98:101]
	v_mfma_f32_16x16x32_f16 v[86:89], v[192:195], v[176:179], v[86:89]
	v_mfma_f32_16x16x32_f16 v[82:85], v[200:203], v[176:179], v[82:85]
	v_mfma_f32_16x16x32_f16 v[70:73], v[192:195], v[184:187], v[70:73]
	v_mfma_f32_16x16x32_f16 v[66:69], v[200:203], v[184:187], v[66:69]
	v_mfma_f32_16x16x32_f16 v[118:121], v[196:199], v[164:167], v[118:121]
	v_mfma_f32_16x16x32_f16 v[114:117], v[204:207], v[164:167], v[114:117]
	v_mfma_f32_16x16x32_f16 v[102:105], v[196:199], v[172:175], v[102:105]
	v_mfma_f32_16x16x32_f16 v[98:101], v[204:207], v[172:175], v[98:101]
	v_mfma_f32_16x16x32_f16 v[86:89], v[196:199], v[180:183], v[86:89]
	v_mfma_f32_16x16x32_f16 v[82:85], v[204:207], v[180:183], v[82:85]
	v_mfma_f32_16x16x32_f16 v[70:73], v[196:199], v[188:191], v[70:73]
	v_mfma_f32_16x16x32_f16 v[66:69], v[204:207], v[188:191], v[66:69]
	s_mov_b32 m0, s37
	v_lshl_add_u64 v[208:209], v[212:213], 0, s[86:87]
	s_barrier
	ds_read_b128 v[160:163], v1 offset:49152
	ds_read_b128 v[164:167], v1 offset:50176
	ds_read_b128 v[168:171], v1 offset:51200
	ds_read_b128 v[172:175], v1 offset:52224
	ds_read_b128 v[176:179], v1 offset:53248
	ds_read_b128 v[180:183], v1 offset:54272
	ds_read_b128 v[184:187], v1 offset:55296
	ds_read_b128 v[188:191], v1 offset:56320
	global_load_lds_dwordx4 v[208:209], off
	s_mov_b32 m0, s52
	v_lshl_add_u64 v[208:209], v[214:215], 0, s[86:87]
	global_load_lds_dwordx4 v[208:209], off
	s_barrier
	s_waitcnt lgkmcnt(0)
	s_waitcnt lgkmcnt(0)
	v_mfma_f32_16x16x32_f16 v[62:65], v[144:147], v[160:163], v[62:65]
	v_mfma_f32_16x16x32_f16 v[58:61], v[152:155], v[160:163], v[58:61]
	v_mfma_f32_16x16x32_f16 v[46:49], v[144:147], v[168:171], v[46:49]
	v_mfma_f32_16x16x32_f16 v[42:45], v[152:155], v[168:171], v[42:45]
	v_mfma_f32_16x16x32_f16 v[30:33], v[144:147], v[176:179], v[30:33]
	v_mfma_f32_16x16x32_f16 v[26:29], v[152:155], v[176:179], v[26:29]
	v_mfma_f32_16x16x32_f16 v[14:17], v[144:147], v[184:187], v[14:17]
	v_mfma_f32_16x16x32_f16 v[10:13], v[152:155], v[184:187], v[10:13]
	v_mfma_f32_16x16x32_f16 v[62:65], v[148:151], v[164:167], v[62:65]
	v_mfma_f32_16x16x32_f16 v[58:61], v[156:159], v[164:167], v[58:61]
	v_mfma_f32_16x16x32_f16 v[46:49], v[148:151], v[172:175], v[46:49]
	v_mfma_f32_16x16x32_f16 v[42:45], v[156:159], v[172:175], v[42:45]
	v_mfma_f32_16x16x32_f16 v[30:33], v[148:151], v[180:183], v[30:33]
	v_mfma_f32_16x16x32_f16 v[26:29], v[156:159], v[180:183], v[26:29]
	v_mfma_f32_16x16x32_f16 v[14:17], v[148:151], v[188:191], v[14:17]
	v_mfma_f32_16x16x32_f16 v[10:13], v[156:159], v[188:191], v[10:13]
	s_barrier
	s_add_u32 s14, s14, 0x40080
	s_addc_u32 s15, s15, 0
	s_mov_b32 m0, s53
	v_lshl_add_u64 v[144:145], s[14:15], 0, v[132:133]
	global_load_lds_dwordx4 v[144:145], off
	s_mov_b32 m0, s56
	v_lshl_add_u64 v[144:145], s[14:15], 0, v[136:137]
	global_load_lds_dwordx4 v[144:145], off
	s_waitcnt vmcnt(6)
	s_barrier
	v_mfma_f32_16x16x32_f16 v[54:57], v[192:195], v[160:163], v[54:57]
	v_mfma_f32_16x16x32_f16 v[50:53], v[200:203], v[160:163], v[50:53]
	v_mfma_f32_16x16x32_f16 v[38:41], v[192:195], v[168:171], v[38:41]
	v_mfma_f32_16x16x32_f16 v[34:37], v[200:203], v[168:171], v[34:37]
	v_mfma_f32_16x16x32_f16 v[22:25], v[192:195], v[176:179], v[22:25]
	v_mfma_f32_16x16x32_f16 v[18:21], v[200:203], v[176:179], v[18:21]
	v_mfma_f32_16x16x32_f16 v[6:9], v[192:195], v[184:187], v[6:9]
	v_mfma_f32_16x16x32_f16 v[2:5], v[200:203], v[184:187], v[2:5]
	v_mfma_f32_16x16x32_f16 v[54:57], v[196:199], v[164:167], v[54:57]
	v_mfma_f32_16x16x32_f16 v[50:53], v[204:207], v[164:167], v[50:53]
	v_mfma_f32_16x16x32_f16 v[38:41], v[196:199], v[172:175], v[38:41]
	v_mfma_f32_16x16x32_f16 v[34:37], v[204:207], v[172:175], v[34:37]
	v_mfma_f32_16x16x32_f16 v[22:25], v[196:199], v[180:183], v[22:25]
	v_mfma_f32_16x16x32_f16 v[18:21], v[204:207], v[180:183], v[18:21]
	v_mfma_f32_16x16x32_f16 v[6:9], v[196:199], v[188:191], v[6:9]
	v_mfma_f32_16x16x32_f16 v[2:5], v[204:207], v[188:191], v[2:5]
	s_add_u32 s12, s12, 0x100
	s_addc_u32 s13, s13, 0
	s_add_u32 s66, s66, 0x100
	s_addc_u32 s46, s46, 0
	s_cmp_ge_i32 s68, s5
	s_mov_b32 s14, s68
	s_barrier
	s_cbranch_scc0 .LBB0_2581
	s_branch .LBB0_2583

; #define G_STAGE(bufoff, gbase, v0, v1) do { \
;     __builtin_amdgcn_global_load_lds((const unsigned*)((const char*)(gbase) + (v0)), (LAS unsigned*)(lds + (bufoff) + ldsw), 16, 0, 0); \
;     __builtin_amdgcn_global_load_lds((const unsigned*)((const char*)(gbase) + (v1)), (LAS unsigned*)(lds + (bufoff) + ldsw + 8192), 16, 0, 0); } while (0)
; #define G_LDA(dst, b, h) do { _Pragma("unroll") for (int m = 0; m < 4; ++m) _Pragma("unroll") for (int k = 0; k < 2; ++k) dst[m][k] = *(const LAS h8*)(lds + G_SA(b, h) + aoff + m * 2048 + k * 1024); } while (0)
; #define G_LDB(dst, b, h) do { _Pragma("unroll") for (int n = 0; n < 2; ++n) _Pragma("unroll") for (int k = 0; k < 2; ++k) dst[n][k] = *(const LAS h8*)(lds + G_SB(b, h) + boff + n * 2048 + k * 1024); } while (0)
; #define G_MMA(ai, bj, At, Bt) do { __builtin_amdgcn_s_setprio(1); _Pragma("unroll") for (int m = 0; m < 4; ++m) _Pragma("unroll") for (int n = 0; n < 2; ++n) _Pragma("unroll") for (int k = 0; k < 2; ++k) \
;     acc[ai][bj][m][n] = __builtin_amdgcn_mfma_f32_16x16x32_f16(Bt[n][k], At[m][k], acc[ai][bj][m][n], 0, 0, 0); __builtin_amdgcn_s_setprio(0); } while (0)
; #define G_WAIT_V(n) asm volatile("s_waitcnt vmcnt(" #n ")" ::: "memory")
; #define G_WAIT_L(n) asm volatile("s_waitcnt lgkmcnt(" #n ")" ::: "memory")
; #define G_BAR __builtin_amdgcn_s_barrier()
; #define G_SCHED __builtin_amdgcn_sched_barrier(0)
; template <bool PERM, class Sched, class Epi>
; DI void gemm256(LAS unsigned char* lds, const Sched& S, const Epi& E, int wv_) {
;     ...
;       const bool last = (t == nt - 2);
;       const char* a1 = cA + (size_t)(t + 1) * kstep;
;       const char* a2 = last ? nA : cA + (size_t)(t + 2) * kstep;
;       const char* b2 = last ? nB : cB + (size_t)(t + 2) * kstep;
;       const char* a3 = a2 + kstep;
;       const char* b3 = b2 + kstep;
;       G_LDB(B0, 0, 0); G_SCHED; G_LDA(At, 0, 0); G_STAGE(G_SA(1, 1), a1 + chA, cvA0, cvA1);
;       G_WAIT_L(8); G_BAR; G_WAIT_L(0); G_MMA(0, 0, At, B0); G_BAR; G_SCHED;
;       G_LDB(B1, 0, 1); G_STAGE(G_SB(0, 0), b2, cvB0, cvB1);
;       G_BAR; G_WAIT_L(0); G_MMA(0, 1, At, B1); G_BAR;
;       G_LDA(At, 0, 1); G_STAGE(G_SA(0, 0), a2, cvA0, cvA1);
;       G_BAR; G_WAIT_L(0); G_MMA(1, 0, At, B0); G_BAR; G_SCHED;
;       G_STAGE(G_SB(0, 1), b2 + chB, cvB0, cvB1);
;       G_WAIT_V(6); G_BAR; G_MMA(1, 1, At, B1); G_BAR;
.LBB0_2656:
	s_waitcnt vmcnt(0)
	ds_read_b128 v[130:133], v216
	ds_read_b128 v[134:137], v216 offset:1024
	ds_read_b128 v[138:141], v216 offset:2048
	ds_read_b128 v[142:145], v216 offset:3072
	ds_read_b128 v[146:149], v1
	ds_read_b128 v[164:167], v1 offset:1024
	ds_read_b128 v[168:171], v1 offset:2048
	ds_read_b128 v[172:175], v1 offset:3072
	ds_read_b128 v[176:179], v1 offset:4096
	ds_read_b128 v[180:183], v1 offset:5120
	ds_read_b128 v[184:187], v1 offset:6144
	ds_read_b128 v[188:191], v1 offset:7168
	s_add_i32 s91, s22, 2
	s_add_u32 s23, s20, 0xfff00080
	s_addc_u32 s24, s21, -1
	s_cmp_eq_u32 s27, s22
	s_cselect_b32 s22, vcc_hi, s46
	s_cselect_b32 s25, s29, s24
	s_cselect_b32 s24, s56, s23
	s_cselect_b32 s23, vcc_lo, s74
	s_add_i32 m0, s35, 0xc000
	v_lshl_add_u64 v[192:193], s[20:21], 0, v[158:159]
	global_load_lds_dwordx4 v[192:193], off
	s_add_i32 m0, s35, 0xe000
	v_lshl_add_u64 v[192:193], s[20:21], 0, v[160:161]
	global_load_lds_dwordx4 v[192:193], off
	s_waitcnt lgkmcnt(8)
	s_barrier
	s_waitcnt lgkmcnt(0)
	s_waitcnt lgkmcnt(0)
	v_mfma_f32_16x16x32_f16 v[126:129], v[130:133], v[146:149], v[126:129]
	v_mfma_f32_16x16x32_f16 v[122:125], v[138:141], v[146:149], v[122:125]
	v_mfma_f32_16x16x32_f16 v[110:113], v[130:133], v[168:171], v[110:113]
	v_mfma_f32_16x16x32_f16 v[106:109], v[138:141], v[168:171], v[106:109]
	v_mfma_f32_16x16x32_f16 v[94:97], v[130:133], v[176:179], v[94:97]
	v_mfma_f32_16x16x32_f16 v[90:93], v[138:141], v[176:179], v[90:93]
	v_mfma_f32_16x16x32_f16 v[78:81], v[130:133], v[184:187], v[78:81]
	v_mfma_f32_16x16x32_f16 v[74:77], v[138:141], v[184:187], v[74:77]
	v_mfma_f32_16x16x32_f16 v[126:129], v[134:137], v[164:167], v[126:129]
	v_mfma_f32_16x16x32_f16 v[122:125], v[142:145], v[164:167], v[122:125]
	v_mfma_f32_16x16x32_f16 v[110:113], v[134:137], v[172:175], v[110:113]
	v_mfma_f32_16x16x32_f16 v[106:109], v[142:145], v[172:175], v[106:109]
	v_mfma_f32_16x16x32_f16 v[94:97], v[134:137], v[180:183], v[94:97]
	v_mfma_f32_16x16x32_f16 v[90:93], v[142:145], v[180:183], v[90:93]
	v_mfma_f32_16x16x32_f16 v[78:81], v[134:137], v[188:191], v[78:81]
	v_mfma_f32_16x16x32_f16 v[74:77], v[142:145], v[188:191], v[74:77]
	s_barrier
	ds_read_b128 v[192:195], v217
	ds_read_b128 v[196:199], v217 offset:1024
	ds_read_b128 v[200:203], v217 offset:2048
	ds_read_b128 v[204:207], v217 offset:3072
	s_mov_b32 m0, s36
	v_lshl_add_u64 v[208:209], s[22:23], 0, v[150:151]
	global_load_lds_dwordx4 v[208:209], off
	s_mov_b32 m0, s37
	v_lshl_add_u64 v[210:211], s[22:23], 0, v[152:153]
	global_load_lds_dwordx4 v[210:211], off
	s_barrier
	s_waitcnt lgkmcnt(0)
	s_waitcnt lgkmcnt(0)
	v_mfma_f32_16x16x32_f16 v[118:121], v[192:195], v[146:149], v[118:121]
	v_mfma_f32_16x16x32_f16 v[114:117], v[200:203], v[146:149], v[114:117]
	v_mfma_f32_16x16x32_f16 v[102:105], v[192:195], v[168:171], v[102:105]
	v_mfma_f32_16x16x32_f16 v[98:101], v[200:203], v[168:171], v[98:101]
	v_mfma_f32_16x16x32_f16 v[86:89], v[192:195], v[176:179], v[86:89]
	v_mfma_f32_16x16x32_f16 v[82:85], v[200:203], v[176:179], v[82:85]
	v_mfma_f32_16x16x32_f16 v[70:73], v[192:195], v[184:187], v[70:73]
	v_mfma_f32_16x16x32_f16 v[66:69], v[200:203], v[184:187], v[66:69]
	v_mfma_f32_16x16x32_f16 v[118:121], v[196:199], v[164:167], v[118:121]
	v_mfma_f32_16x16x32_f16 v[114:117], v[204:207], v[164:167], v[114:117]
	v_mfma_f32_16x16x32_f16 v[102:105], v[196:199], v[172:175], v[102:105]
	v_mfma_f32_16x16x32_f16 v[98:101], v[204:207], v[172:175], v[98:101]
	v_mfma_f32_16x16x32_f16 v[86:89], v[196:199], v[180:183], v[86:89]
	v_mfma_f32_16x16x32_f16 v[82:85], v[204:207], v[180:183], v[82:85]
	v_mfma_f32_16x16x32_f16 v[70:73], v[196:199], v[188:191], v[70:73]
	v_mfma_f32_16x16x32_f16 v[66:69], v[204:207], v[188:191], v[66:69]
	s_mov_b32 m0, s35
	v_lshl_add_u64 v[212:213], s[24:25], 0, v[150:151]
	s_barrier
	ds_read_b128 v[146:149], v1 offset:16384
	ds_read_b128 v[164:167], v1 offset:17408
	ds_read_b128 v[168:171], v1 offset:18432
	ds_read_b128 v[172:175], v1 offset:19456
	ds_read_b128 v[176:179], v1 offset:20480
	ds_read_b128 v[180:183], v1 offset:21504
	ds_read_b128 v[184:187], v1 offset:22528
	ds_read_b128 v[188:191], v1 offset:23552
	global_load_lds_dwordx4 v[212:213], off
	s_mov_b32 m0, s52
	v_lshl_add_u64 v[214:215], s[24:25], 0, v[152:153]
	global_load_lds_dwordx4 v[214:215], off
	s_barrier
	s_waitcnt lgkmcnt(0)
	s_waitcnt lgkmcnt(0)
	v_mfma_f32_16x16x32_f16 v[62:65], v[130:133], v[146:149], v[62:65]
	v_mfma_f32_16x16x32_f16 v[58:61], v[138:141], v[146:149], v[58:61]
	v_mfma_f32_16x16x32_f16 v[46:49], v[130:133], v[168:171], v[46:49]
	v_mfma_f32_16x16x32_f16 v[42:45], v[138:141], v[168:171], v[42:45]
	v_mfma_f32_16x16x32_f16 v[30:33], v[130:133], v[176:179], v[30:33]
	v_mfma_f32_16x16x32_f16 v[26:29], v[138:141], v[176:179], v[26:29]
	v_mfma_f32_16x16x32_f16 v[14:17], v[130:133], v[184:187], v[14:17]
	v_mfma_f32_16x16x32_f16 v[10:13], v[138:141], v[184:187], v[10:13]
	v_mfma_f32_16x16x32_f16 v[62:65], v[134:137], v[164:167], v[62:65]
	v_mfma_f32_16x16x32_f16 v[58:61], v[142:145], v[164:167], v[58:61]
	v_mfma_f32_16x16x32_f16 v[46:49], v[134:137], v[172:175], v[46:49]
	v_mfma_f32_16x16x32_f16 v[42:45], v[142:145], v[172:175], v[42:45]
	v_mfma_f32_16x16x32_f16 v[30:33], v[134:137], v[180:183], v[30:33]
	v_mfma_f32_16x16x32_f16 v[26:29], v[142:145], v[180:183], v[26:29]
	v_mfma_f32_16x16x32_f16 v[14:17], v[134:137], v[188:191], v[14:17]
	v_mfma_f32_16x16x32_f16 v[10:13], v[142:145], v[188:191], v[10:13]
	s_barrier
	s_add_u32 s40, s22, 0x100000
	s_addc_u32 s41, s23, 0
	s_mov_b32 m0, s53
	v_lshl_add_u64 v[130:131], s[40:41], 0, v[150:151]
	global_load_lds_dwordx4 v[130:131], off
	s_mov_b32 m0, s58
	v_lshl_add_u64 v[130:131], s[40:41], 0, v[152:153]
	global_load_lds_dwordx4 v[130:131], off
	s_waitcnt vmcnt(6)
	s_barrier
; #define G_STAGE(bufoff, gbase, v0, v1) do { \
;     __builtin_amdgcn_global_load_lds((const unsigned*)((const char*)(gbase) + (v0)), (LAS unsigned*)(lds + (bufoff) + ldsw), 16, 0, 0); \
;     __builtin_amdgcn_global_load_lds((const unsigned*)((const char*)(gbase) + (v1)), (LAS unsigned*)(lds + (bufoff) + ldsw + 8192), 16, 0, 0); } while (0)
; #define G_LDA(dst, b, h) do { _Pragma("unroll") for (int m = 0; m < 4; ++m) _Pragma("unroll") for (int k = 0; k < 2; ++k) dst[m][k] = *(const LAS h8*)(lds + G_SA(b, h) + aoff + m * 2048 + k * 1024); } while (0)
; #define G_LDB(dst, b, h) do { _Pragma("unroll") for (int n = 0; n < 2; ++n) _Pragma("unroll") for (int k = 0; k < 2; ++k) dst[n][k] = *(const LAS h8*)(lds + G_SB(b, h) + boff + n * 2048 + k * 1024); } while (0)
; #define G_MMA(ai, bj, At, Bt) do { __builtin_amdgcn_s_setprio(1); _Pragma("unroll") for (int m = 0; m < 4; ++m) _Pragma("unroll") for (int n = 0; n < 2; ++n) _Pragma("unroll") for (int k = 0; k < 2; ++k) \
;     acc[ai][bj][m][n] = __builtin_amdgcn_mfma_f32_16x16x32_f16(Bt[n][k], At[m][k], acc[ai][bj][m][n], 0, 0, 0); __builtin_amdgcn_s_setprio(0); } while (0)
; #define G_WAIT_V(n) asm volatile("s_waitcnt vmcnt(" #n ")" ::: "memory")
; #define G_WAIT_L(n) asm volatile("s_waitcnt lgkmcnt(" #n ")" ::: "memory")
; #define G_BAR __builtin_amdgcn_s_barrier()
; #define G_SCHED __builtin_amdgcn_sched_barrier(0)
; template <bool PERM, class Sched, class Epi>
; DI void gemm256(LAS unsigned char* lds, const Sched& S, const Epi& E, int wv_) {
;     ...
;       G_WAIT_V(6); G_BAR; G_MMA(1, 1, At, B1); G_BAR;
;       G_LDB(B0, 1, 0); G_SCHED; G_LDA(At, 1, 0); G_STAGE(G_SA(0, 1), a2 + chA, cvA0, cvA1);
;       G_WAIT_L(8); G_BAR; G_WAIT_L(0); G_MMA(0, 0, At, B0); G_BAR; G_SCHED;
;       G_LDB(B1, 1, 1); G_STAGE(G_SB(1, 0), b3, cvB0, cvB1);
	v_mfma_f32_16x16x32_f16 v[54:57], v[192:195], v[146:149], v[54:57]
	v_mfma_f32_16x16x32_f16 v[50:53], v[200:203], v[146:149], v[50:53]
	v_mfma_f32_16x16x32_f16 v[38:41], v[192:195], v[168:171], v[38:41]
	v_mfma_f32_16x16x32_f16 v[34:37], v[200:203], v[168:171], v[34:37]
	v_mfma_f32_16x16x32_f16 v[22:25], v[192:195], v[176:179], v[22:25]
	v_mfma_f32_16x16x32_f16 v[18:21], v[200:203], v[176:179], v[18:21]
	v_mfma_f32_16x16x32_f16 v[6:9], v[192:195], v[184:187], v[6:9]
	v_mfma_f32_16x16x32_f16 v[2:5], v[200:203], v[184:187], v[2:5]
	v_mfma_f32_16x16x32_f16 v[54:57], v[196:199], v[164:167], v[54:57]
	v_mfma_f32_16x16x32_f16 v[50:53], v[204:207], v[164:167], v[50:53]
	v_mfma_f32_16x16x32_f16 v[38:41], v[196:199], v[172:175], v[38:41]
	v_mfma_f32_16x16x32_f16 v[34:37], v[204:207], v[172:175], v[34:37]
	v_mfma_f32_16x16x32_f16 v[22:25], v[196:199], v[180:183], v[22:25]
	v_mfma_f32_16x16x32_f16 v[18:21], v[204:207], v[180:183], v[18:21]
	v_mfma_f32_16x16x32_f16 v[6:9], v[196:199], v[188:191], v[6:9]
	v_mfma_f32_16x16x32_f16 v[2:5], v[204:207], v[188:191], v[2:5]
	s_barrier
	ds_read_b128 v[130:133], v218
	ds_read_b128 v[134:137], v218 offset:1024
	ds_read_b128 v[138:141], v218 offset:2048
	ds_read_b128 v[142:145], v218 offset:3072
	ds_read_b128 v[146:149], v1 offset:32768
	ds_read_b128 v[164:167], v1 offset:33792
	ds_read_b128 v[168:171], v1 offset:34816
	ds_read_b128 v[172:175], v1 offset:35840
	ds_read_b128 v[176:179], v1 offset:36864
	ds_read_b128 v[180:183], v1 offset:37888
	ds_read_b128 v[184:187], v1 offset:38912
	ds_read_b128 v[188:191], v1 offset:39936
	s_add_u32 s24, s24, 0x100000
	s_addc_u32 s25, s25, 0
	s_mov_b32 m0, s59
	v_lshl_add_u64 v[192:193], s[24:25], 0, v[150:151]
	global_load_lds_dwordx4 v[192:193], off
	s_mov_b32 m0, s61
	v_lshl_add_u64 v[192:193], s[24:25], 0, v[152:153]
	global_load_lds_dwordx4 v[192:193], off
	s_waitcnt lgkmcnt(8)
	s_barrier
	s_waitcnt lgkmcnt(0)
	s_waitcnt lgkmcnt(0)
	v_mfma_f32_16x16x32_f16 v[126:129], v[130:133], v[146:149], v[126:129]
	v_mfma_f32_16x16x32_f16 v[122:125], v[138:141], v[146:149], v[122:125]
	v_mfma_f32_16x16x32_f16 v[110:113], v[130:133], v[168:171], v[110:113]
	v_mfma_f32_16x16x32_f16 v[106:109], v[138:141], v[168:171], v[106:109]
	v_mfma_f32_16x16x32_f16 v[94:97], v[130:133], v[176:179], v[94:97]
	v_mfma_f32_16x16x32_f16 v[90:93], v[138:141], v[176:179], v[90:93]
	v_mfma_f32_16x16x32_f16 v[78:81], v[130:133], v[184:187], v[78:81]
	v_mfma_f32_16x16x32_f16 v[74:77], v[138:141], v[184:187], v[74:77]
	v_mfma_f32_16x16x32_f16 v[126:129], v[134:137], v[164:167], v[126:129]
	v_mfma_f32_16x16x32_f16 v[122:125], v[142:145], v[164:167], v[122:125]
	v_mfma_f32_16x16x32_f16 v[110:113], v[134:137], v[172:175], v[110:113]
	v_mfma_f32_16x16x32_f16 v[106:109], v[142:145], v[172:175], v[106:109]
	v_mfma_f32_16x16x32_f16 v[94:97], v[134:137], v[180:183], v[94:97]
	v_mfma_f32_16x16x32_f16 v[90:93], v[142:145], v[180:183], v[90:93]
	v_mfma_f32_16x16x32_f16 v[78:81], v[134:137], v[188:191], v[78:81]
	v_mfma_f32_16x16x32_f16 v[74:77], v[142:145], v[188:191], v[74:77]
	s_barrier
	ds_read_b128 v[192:195], v219
	ds_read_b128 v[196:199], v219 offset:1024
	ds_read_b128 v[200:203], v219 offset:2048
	ds_read_b128 v[204:207], v219 offset:3072
	s_mov_b32 m0, s69
	v_lshl_add_u64 v[208:209], v[208:209], 0, s[86:87]
	global_load_lds_dwordx4 v[208:209], off
	s_mov_b32 m0, s78
	v_lshl_add_u64 v[208:209], v[210:211], 0, s[86:87]
	global_load_lds_dwordx4 v[208:209], off
	s_barrier
; #define G_STAGE(bufoff, gbase, v0, v1) do { \
;     __builtin_amdgcn_global_load_lds((const unsigned*)((const char*)(gbase) + (v0)), (LAS unsigned*)(lds + (bufoff) + ldsw), 16, 0, 0); \
;     __builtin_amdgcn_global_load_lds((const unsigned*)((const char*)(gbase) + (v1)), (LAS unsigned*)(lds + (bufoff) + ldsw + 8192), 16, 0, 0); } while (0)
; #define G_LDA(dst, b, h) do { _Pragma("unroll") for (int m = 0; m < 4; ++m) _Pragma("unroll") for (int k = 0; k < 2; ++k) dst[m][k] = *(const LAS h8*)(lds + G_SA(b, h) + aoff + m * 2048 + k * 1024); } while (0)
; #define G_MMA(ai, bj, At, Bt) do { __builtin_amdgcn_s_setprio(1); _Pragma("unroll") for (int m = 0; m < 4; ++m) _Pragma("unroll") for (int n = 0; n < 2; ++n) _Pragma("unroll") for (int k = 0; k < 2; ++k) \
;     acc[ai][bj][m][n] = __builtin_amdgcn_mfma_f32_16x16x32_f16(Bt[n][k], At[m][k], acc[ai][bj][m][n], 0, 0, 0); __builtin_amdgcn_s_setprio(0); } while (0)
; #define G_WAIT_V(n) asm volatile("s_waitcnt vmcnt(" #n ")" ::: "memory")
; #define G_WAIT_L(n) asm volatile("s_waitcnt lgkmcnt(" #n ")" ::: "memory")
; #define G_BAR __builtin_amdgcn_s_barrier()
; #define G_SCHED __builtin_amdgcn_sched_barrier(0)
; template <bool PERM, class Sched, class Epi>
; DI void gemm256(LAS unsigned char* lds, const Sched& S, const Epi& E, int wv_) {
;     ...
;       G_BAR; G_WAIT_L(0); G_MMA(0, 1, At, B1); G_BAR;
;       G_LDA(At, 1, 1); G_STAGE(G_SA(1, 0), a3, cvA0, cvA1);
;       G_BAR; G_WAIT_L(0); G_MMA(1, 0, At, B0); G_BAR; G_SCHED;
;       G_STAGE(G_SB(1, 1), b3 + chB, cvB0, cvB1);
;       G_WAIT_V(6); G_BAR; G_MMA(1, 1, At, B1); G_BAR;
;     }
;     bool keep = false;
;     if constexpr (Sched::CHAIN) keep = E(acc, cur, wr, wc, fr, fq); else E(acc, cur, wr, wc, fr, fq);
;     if (!has_next) break;
	s_waitcnt lgkmcnt(0)
	s_waitcnt lgkmcnt(0)
	v_mfma_f32_16x16x32_f16 v[118:121], v[192:195], v[146:149], v[118:121]
	v_mfma_f32_16x16x32_f16 v[114:117], v[200:203], v[146:149], v[114:117]
	v_mfma_f32_16x16x32_f16 v[102:105], v[192:195], v[168:171], v[102:105]
	v_mfma_f32_16x16x32_f16 v[98:101], v[200:203], v[168:171], v[98:101]
	v_mfma_f32_16x16x32_f16 v[86:89], v[192:195], v[176:179], v[86:89]
	v_mfma_f32_16x16x32_f16 v[82:85], v[200:203], v[176:179], v[82:85]
	v_mfma_f32_16x16x32_f16 v[70:73], v[192:195], v[184:187], v[70:73]
	v_mfma_f32_16x16x32_f16 v[66:69], v[200:203], v[184:187], v[66:69]
	v_mfma_f32_16x16x32_f16 v[118:121], v[196:199], v[164:167], v[118:121]
	v_mfma_f32_16x16x32_f16 v[114:117], v[204:207], v[164:167], v[114:117]
	v_mfma_f32_16x16x32_f16 v[102:105], v[196:199], v[172:175], v[102:105]
	v_mfma_f32_16x16x32_f16 v[98:101], v[204:207], v[172:175], v[98:101]
	v_mfma_f32_16x16x32_f16 v[86:89], v[196:199], v[180:183], v[86:89]
	v_mfma_f32_16x16x32_f16 v[82:85], v[204:207], v[180:183], v[82:85]
	v_mfma_f32_16x16x32_f16 v[70:73], v[196:199], v[188:191], v[70:73]
	v_mfma_f32_16x16x32_f16 v[66:69], v[204:207], v[188:191], v[66:69]
	s_mov_b32 m0, s79
	v_lshl_add_u64 v[208:209], v[212:213], 0, s[86:87]
	s_barrier
	ds_read_b128 v[146:149], v1 offset:49152
	ds_read_b128 v[164:167], v1 offset:50176
	ds_read_b128 v[168:171], v1 offset:51200
	ds_read_b128 v[172:175], v1 offset:52224
	ds_read_b128 v[176:179], v1 offset:53248
	ds_read_b128 v[180:183], v1 offset:54272
	ds_read_b128 v[184:187], v1 offset:55296
	ds_read_b128 v[188:191], v1 offset:56320
	global_load_lds_dwordx4 v[208:209], off
	s_mov_b32 m0, s83
	v_lshl_add_u64 v[208:209], v[214:215], 0, s[86:87]
	global_load_lds_dwordx4 v[208:209], off
	s_barrier
	s_waitcnt lgkmcnt(0)
	s_waitcnt lgkmcnt(0)
	v_mfma_f32_16x16x32_f16 v[62:65], v[130:133], v[146:149], v[62:65]
	v_mfma_f32_16x16x32_f16 v[58:61], v[138:141], v[146:149], v[58:61]
	v_mfma_f32_16x16x32_f16 v[46:49], v[130:133], v[168:171], v[46:49]
	v_mfma_f32_16x16x32_f16 v[42:45], v[138:141], v[168:171], v[42:45]
	v_mfma_f32_16x16x32_f16 v[30:33], v[130:133], v[176:179], v[30:33]
	v_mfma_f32_16x16x32_f16 v[26:29], v[138:141], v[176:179], v[26:29]
	v_mfma_f32_16x16x32_f16 v[14:17], v[130:133], v[184:187], v[14:17]
	v_mfma_f32_16x16x32_f16 v[10:13], v[138:141], v[184:187], v[10:13]
	v_mfma_f32_16x16x32_f16 v[62:65], v[134:137], v[164:167], v[62:65]
	v_mfma_f32_16x16x32_f16 v[58:61], v[142:145], v[164:167], v[58:61]
	v_mfma_f32_16x16x32_f16 v[46:49], v[134:137], v[172:175], v[46:49]
	v_mfma_f32_16x16x32_f16 v[42:45], v[142:145], v[172:175], v[42:45]
	v_mfma_f32_16x16x32_f16 v[30:33], v[134:137], v[180:183], v[30:33]
	v_mfma_f32_16x16x32_f16 v[26:29], v[142:145], v[180:183], v[26:29]
	v_mfma_f32_16x16x32_f16 v[14:17], v[134:137], v[188:191], v[14:17]
	v_mfma_f32_16x16x32_f16 v[10:13], v[142:145], v[188:191], v[10:13]
	s_barrier
	s_add_u32 s22, s22, 0x100080
	s_addc_u32 s23, s23, 0
	s_mov_b32 m0, s84
	v_lshl_add_u64 v[130:131], s[22:23], 0, v[150:151]
	global_load_lds_dwordx4 v[130:131], off
	s_mov_b32 m0, s85
	v_lshl_add_u64 v[130:131], s[22:23], 0, v[152:153]
	global_load_lds_dwordx4 v[130:131], off
	s_waitcnt vmcnt(6)
	s_barrier
	v_mfma_f32_16x16x32_f16 v[54:57], v[192:195], v[146:149], v[54:57]
	v_mfma_f32_16x16x32_f16 v[50:53], v[200:203], v[146:149], v[50:53]
	v_mfma_f32_16x16x32_f16 v[38:41], v[192:195], v[168:171], v[38:41]
	v_mfma_f32_16x16x32_f16 v[34:37], v[200:203], v[168:171], v[34:37]
	v_mfma_f32_16x16x32_f16 v[22:25], v[192:195], v[176:179], v[22:25]
	v_mfma_f32_16x16x32_f16 v[18:21], v[200:203], v[176:179], v[18:21]
	v_mfma_f32_16x16x32_f16 v[6:9], v[192:195], v[184:187], v[6:9]
	v_mfma_f32_16x16x32_f16 v[2:5], v[200:203], v[184:187], v[2:5]
	v_mfma_f32_16x16x32_f16 v[54:57], v[196:199], v[164:167], v[54:57]
	v_mfma_f32_16x16x32_f16 v[50:53], v[204:207], v[164:167], v[50:53]
	v_mfma_f32_16x16x32_f16 v[38:41], v[196:199], v[172:175], v[38:41]
	v_mfma_f32_16x16x32_f16 v[34:37], v[204:207], v[172:175], v[34:37]
	v_mfma_f32_16x16x32_f16 v[22:25], v[196:199], v[180:183], v[22:25]
	v_mfma_f32_16x16x32_f16 v[18:21], v[204:207], v[180:183], v[18:21]
	v_mfma_f32_16x16x32_f16 v[6:9], v[196:199], v[188:191], v[6:9]
	v_mfma_f32_16x16x32_f16 v[2:5], v[204:207], v[188:191], v[2:5]
	s_add_u32 s20, s20, 0x100
	s_addc_u32 s21, s21, 0
	s_add_u32 s46, s46, 0x100
	s_addc_u32 s74, s74, 0
	s_cmp_ge_i32 s91, s75
	s_mov_b32 s22, s91
	s_barrier
	s_cbranch_scc0 .LBB0_2656
	v_readlane_b32 s91, v254, 47
	s_mov_b32 s56, 0x8fff
	s_branch .LBB0_2659
